# v70 + first K-loop iteration of every GEMM unit peeled with C=0 on each accumulator's first MFMA (the 128 zeroing v_mov per unit removed)
# speedup vs baseline: 1.0073x; 1.0050x over previous
; #define PG8_STAGE(bufoff, gbase, voff) do { _Pragma("unroll") for (int _i = 0; _i < 2; ++_i) \
;         __builtin_amdgcn_global_load_lds((const unsigned*)((const char*)(gbase) + (voff)[_i]), (LAS unsigned*)(lds + (bufoff) + ldsw + _i * 8192), 16, 0, 0); } while (0)
; #define PG8_LDA(dst, b, h) do { _Pragma("unroll") for (int m = 0; m < 4; ++m) _Pragma("unroll") for (int k = 0; k < 2; ++k) dst[m][k] = *(const LAS bf16x8*)(lds + PG8_SA(b, h) + aoff + m * 2048 + k * 1024); } while (0)
; #define PG8_LDB(dst, b, h) do { _Pragma("unroll") for (int n = 0; n < 2; ++n) _Pragma("unroll") for (int k = 0; k < 2; ++k) dst[n][k] = *(const LAS bf16x8*)(lds + PG8_SB(b, h) + boff + n * 2048 + k * 1024); } while (0)
; #define PG8_MMA(ai, bj, At, Bt) do { __builtin_amdgcn_s_setprio(1); _Pragma("unroll") for (int m = 0; m < 4; ++m) _Pragma("unroll") for (int n = 0; n < 2; ++n) _Pragma("unroll") for (int k = 0; k < 2; ++k) \
;         acc[ai][bj][m][n] = __builtin_amdgcn_mfma_f32_16x16x32_bf16(Bt[n][k], At[m][k], acc[ai][bj][m][n], 0, 0, 0); __builtin_amdgcn_s_setprio(0); } while (0)
; #define PG8_WAIT_V(n) asm volatile("s_waitcnt vmcnt(" #n ")" ::: "memory")
; #define PG8_WAIT_L(n) asm volatile("s_waitcnt lgkmcnt(" #n ")" ::: "memory")
; #define PG8_BAR __builtin_amdgcn_s_barrier()
; #define PG8_SCHED __builtin_amdgcn_sched_barrier(0)
; template <class Epi>
; DI void gemm_phase(LAS unsigned char* lds, int wid, int K, int lda, int ldb, bool bperm, const Sched3& S, const Epi& E) {
;     ...
;             PG8_LDB(B0, 0, 0); PG8_SCHED; PG8_LDA(At, 0, 0); PG8_STAGE(PG8_SA(1, 1), a1 + hA, voffA);
;             PG8_WAIT_L(8); PG8_BAR; PG8_WAIT_L(0); PG8_MMA(0, 0, At, B0); PG8_BAR; PG8_SCHED;
;             PG8_LDB(B1, 0, 1); PG8_STAGE(PG8_SB(0, 0), b2, voffB);
;             PG8_BAR; PG8_WAIT_L(0); PG8_MMA(0, 1, At, B1); PG8_BAR;
;             PG8_LDA(At, 0, 1); PG8_STAGE(PG8_SA(0, 0), a2, voffA);
;             PG8_BAR; PG8_WAIT_L(0); if (full) PG8_MMA(1, 0, At, B0); PG8_BAR; PG8_SCHED;
;             PG8_STAGE(PG8_SB(0, 1), b2 + hstepB, voffB);
;             PG8_WAIT_V(6); PG8_BAR; if (full) PG8_MMA(1, 1, At, B1); PG8_BAR;
.LBB0_326:
	s_xor_b64 s[44:45], s[52:53], -1
	s_and_b64 s[50:51], s[52:53], exec
	s_cselect_b32 s5, s41, s47
	s_cselect_b32 s37, s40, s46
	s_cselect_b32 s39, s43, s49
	s_cselect_b32 s52, s42, s48
	s_add_u32 s46, s46, 0x80080
	s_addc_u32 s47, s47, 0
	s_add_u32 s53, s48, 0x100
	s_nop 0
	s_addc_u32 s54, s49, 0
	s_mov_b32 s55, -2
	s_waitcnt lgkmcnt(0)
	ds_read_b128 v[128:131], v230
	ds_read_b128 v[132:135], v230 offset:1024
	ds_read_b128 v[136:139], v230 offset:2048
	ds_read_b128 v[156:159], v230 offset:3072
	s_add_u32 s48, s46, 0xfff80080
	s_addc_u32 s49, s47, -1
	s_cmp_eq_u32 s55, 28
	s_cselect_b32 s51, s5, s49
	s_cselect_b32 s50, s37, s48
	s_cselect_b32 s49, s39, s54
	s_cselect_b32 s48, s52, s53
	v_lshl_add_u64 v[192:193], s[46:47], 0, v[148:149]
	s_add_i32 m0, s58, 0xc000
	ds_read_b128 v[160:163], v231
	ds_read_b128 v[164:167], v231 offset:1024
	ds_read_b128 v[168:171], v231 offset:2048
	ds_read_b128 v[172:175], v231 offset:3072
	ds_read_b128 v[176:179], v231 offset:4096
	ds_read_b128 v[180:183], v231 offset:5120
	ds_read_b128 v[184:187], v231 offset:6144
	ds_read_b128 v[188:191], v231 offset:7168
	global_load_lds_dwordx4 v[192:193], off
	v_lshl_add_u64 v[192:193], s[46:47], 0, v[150:151]
	s_add_i32 m0, s58, 0xe000
	s_nop 0
	global_load_lds_dwordx4 v[192:193], off
	s_waitcnt lgkmcnt(8)
	s_barrier
	s_waitcnt lgkmcnt(0)
	s_setprio 1
	s_waitcnt lgkmcnt(0)
	v_mfma_f32_16x16x32_bf16 v[124:127], v[128:131], v[160:163], 0
	v_mfma_f32_16x16x32_bf16 v[120:123], v[136:139], v[160:163], 0
	v_mfma_f32_16x16x32_bf16 v[108:111], v[128:131], v[168:171], 0
	v_mfma_f32_16x16x32_bf16 v[104:107], v[136:139], v[168:171], 0
	v_mfma_f32_16x16x32_bf16 v[92:95], v[128:131], v[176:179], 0
	v_mfma_f32_16x16x32_bf16 v[88:91], v[136:139], v[176:179], 0
	v_mfma_f32_16x16x32_bf16 v[76:79], v[128:131], v[184:187], 0
	v_mfma_f32_16x16x32_bf16 v[72:75], v[136:139], v[184:187], 0
	v_mfma_f32_16x16x32_bf16 v[124:127], v[132:135], v[164:167], v[124:127]
	v_mfma_f32_16x16x32_bf16 v[120:123], v[156:159], v[164:167], v[120:123]
	v_mfma_f32_16x16x32_bf16 v[108:111], v[132:135], v[172:175], v[108:111]
	v_mfma_f32_16x16x32_bf16 v[104:107], v[156:159], v[172:175], v[104:107]
	v_mfma_f32_16x16x32_bf16 v[92:95], v[132:135], v[180:183], v[92:95]
	v_mfma_f32_16x16x32_bf16 v[88:91], v[156:159], v[180:183], v[88:91]
	v_mfma_f32_16x16x32_bf16 v[76:79], v[132:135], v[188:191], v[76:79]
	v_mfma_f32_16x16x32_bf16 v[72:75], v[156:159], v[188:191], v[72:75]
	s_setprio 0
	s_barrier
	s_add_i32 s75, s67, s57
	v_lshl_add_u64 v[208:209], s[48:49], 0, v[142:143]
	s_mov_b32 m0, s75
	ds_read_b128 v[192:195], v232
	ds_read_b128 v[196:199], v232 offset:1024
	ds_read_b128 v[200:203], v232 offset:2048
	ds_read_b128 v[204:207], v232 offset:3072
	global_load_lds_dwordx4 v[208:209], off
	v_lshl_add_u64 v[210:211], s[48:49], 0, v[146:147]
	s_add_i32 m0, s75, 0x2000
	s_nop 0
	global_load_lds_dwordx4 v[210:211], off
	s_barrier
	s_waitcnt lgkmcnt(0)
	s_setprio 1
	s_waitcnt lgkmcnt(0)
	v_mfma_f32_16x16x32_bf16 v[116:119], v[192:195], v[160:163], 0
	v_mfma_f32_16x16x32_bf16 v[112:115], v[200:203], v[160:163], 0
	v_mfma_f32_16x16x32_bf16 v[100:103], v[192:195], v[168:171], 0
	v_mfma_f32_16x16x32_bf16 v[96:99], v[200:203], v[168:171], 0
	v_mfma_f32_16x16x32_bf16 v[84:87], v[192:195], v[176:179], 0
	v_mfma_f32_16x16x32_bf16 v[80:83], v[200:203], v[176:179], 0
	v_mfma_f32_16x16x32_bf16 v[68:71], v[192:195], v[184:187], 0
	v_mfma_f32_16x16x32_bf16 v[64:67], v[200:203], v[184:187], 0
	v_mfma_f32_16x16x32_bf16 v[116:119], v[196:199], v[164:167], v[116:119]
	v_mfma_f32_16x16x32_bf16 v[112:115], v[204:207], v[164:167], v[112:115]
	v_mfma_f32_16x16x32_bf16 v[100:103], v[196:199], v[172:175], v[100:103]
	v_mfma_f32_16x16x32_bf16 v[96:99], v[204:207], v[172:175], v[96:99]
	v_mfma_f32_16x16x32_bf16 v[84:87], v[196:199], v[180:183], v[84:87]
	v_mfma_f32_16x16x32_bf16 v[80:83], v[204:207], v[180:183], v[80:83]
	v_mfma_f32_16x16x32_bf16 v[68:71], v[196:199], v[188:191], v[68:71]
	v_mfma_f32_16x16x32_bf16 v[64:67], v[204:207], v[188:191], v[64:67]
	s_setprio 0
	s_mov_b32 m0, s58
	v_lshl_add_u64 v[212:213], s[50:51], 0, v[140:141]
	s_barrier
	ds_read_b128 v[160:163], v231 offset:16384
	ds_read_b128 v[164:167], v231 offset:17408
	ds_read_b128 v[168:171], v231 offset:18432
	ds_read_b128 v[172:175], v231 offset:19456
	ds_read_b128 v[176:179], v231 offset:20480
	ds_read_b128 v[180:183], v231 offset:21504
	ds_read_b128 v[184:187], v231 offset:22528
	ds_read_b128 v[188:191], v231 offset:23552
	global_load_lds_dwordx4 v[212:213], off
	v_lshl_add_u64 v[214:215], s[50:51], 0, v[144:145]
	s_mov_b32 m0, s59
	s_nop 0
	global_load_lds_dwordx4 v[214:215], off
	s_barrier
	s_waitcnt lgkmcnt(0)
	s_setprio 1
	s_waitcnt lgkmcnt(0)
	v_mfma_f32_16x16x32_bf16 v[60:63], v[128:131], v[160:163], 0
	v_mfma_f32_16x16x32_bf16 v[56:59], v[136:139], v[160:163], 0
	v_mfma_f32_16x16x32_bf16 v[44:47], v[128:131], v[168:171], 0
	v_mfma_f32_16x16x32_bf16 v[40:43], v[136:139], v[168:171], 0
	v_mfma_f32_16x16x32_bf16 v[28:31], v[128:131], v[176:179], 0
	v_mfma_f32_16x16x32_bf16 v[24:27], v[136:139], v[176:179], 0
	v_mfma_f32_16x16x32_bf16 v[12:15], v[128:131], v[184:187], 0
	v_mfma_f32_16x16x32_bf16 v[8:11], v[136:139], v[184:187], 0
	v_mfma_f32_16x16x32_bf16 v[60:63], v[132:135], v[164:167], v[60:63]
	v_mfma_f32_16x16x32_bf16 v[56:59], v[156:159], v[164:167], v[56:59]
	v_mfma_f32_16x16x32_bf16 v[44:47], v[132:135], v[172:175], v[44:47]
	v_mfma_f32_16x16x32_bf16 v[40:43], v[156:159], v[172:175], v[40:43]
	v_mfma_f32_16x16x32_bf16 v[28:31], v[132:135], v[180:183], v[28:31]
	v_mfma_f32_16x16x32_bf16 v[24:27], v[156:159], v[180:183], v[24:27]
	v_mfma_f32_16x16x32_bf16 v[12:15], v[132:135], v[188:191], v[12:15]
	v_mfma_f32_16x16x32_bf16 v[8:11], v[156:159], v[188:191], v[8:11]
	s_setprio 0
	s_barrier
; #define PG8_STAGE(bufoff, gbase, voff) do { _Pragma("unroll") for (int _i = 0; _i < 2; ++_i) \
;         __builtin_amdgcn_global_load_lds((const unsigned*)((const char*)(gbase) + (voff)[_i]), (LAS unsigned*)(lds + (bufoff) + ldsw + _i * 8192), 16, 0, 0); } while (0)
; #define PG8_LDA(dst, b, h) do { _Pragma("unroll") for (int m = 0; m < 4; ++m) _Pragma("unroll") for (int k = 0; k < 2; ++k) dst[m][k] = *(const LAS bf16x8*)(lds + PG8_SA(b, h) + aoff + m * 2048 + k * 1024); } while (0)
; #define PG8_LDB(dst, b, h) do { _Pragma("unroll") for (int n = 0; n < 2; ++n) _Pragma("unroll") for (int k = 0; k < 2; ++k) dst[n][k] = *(const LAS bf16x8*)(lds + PG8_SB(b, h) + boff + n * 2048 + k * 1024); } while (0)
; #define PG8_MMA(ai, bj, At, Bt) do { __builtin_amdgcn_s_setprio(1); _Pragma("unroll") for (int m = 0; m < 4; ++m) _Pragma("unroll") for (int n = 0; n < 2; ++n) _Pragma("unroll") for (int k = 0; k < 2; ++k) \
;         acc[ai][bj][m][n] = __builtin_amdgcn_mfma_f32_16x16x32_bf16(Bt[n][k], At[m][k], acc[ai][bj][m][n], 0, 0, 0); __builtin_amdgcn_s_setprio(0); } while (0)
; #define PG8_WAIT_V(n) asm volatile("s_waitcnt vmcnt(" #n ")" ::: "memory")
; #define PG8_WAIT_L(n) asm volatile("s_waitcnt lgkmcnt(" #n ")" ::: "memory")
; #define PG8_BAR __builtin_amdgcn_s_barrier()
; #define PG8_SCHED __builtin_amdgcn_sched_barrier(0)
; template <class Epi>
; DI void gemm_phase(LAS unsigned char* lds, int wid, int K, int lda, int ldb, bool bperm, const Sched3& S, const Epi& E) {
;     ...
;             PG8_STAGE(PG8_SB(0, 1), b2 + hstepB, voffB);
;             PG8_WAIT_V(6); PG8_BAR; if (full) PG8_MMA(1, 1, At, B1); PG8_BAR;
;             PG8_LDB(B0, 1, 0); PG8_SCHED; PG8_LDA(At, 1, 0); PG8_STAGE(PG8_SA(0, 1), a2 + h2, voffA);
;             PG8_WAIT_L(8); PG8_BAR; PG8_WAIT_L(0); PG8_MMA(0, 0, At, B0); PG8_BAR; PG8_SCHED;
;             PG8_LDB(B1, 1, 1); PG8_STAGE(PG8_SB(1, 0), b3, voffB);
;             PG8_BAR; PG8_WAIT_L(0); PG8_MMA(0, 1, At, B1); PG8_BAR;
;             PG8_LDA(At, 1, 1); PG8_STAGE(PG8_SA(1, 0), a3, voffA);
;             PG8_BAR; PG8_WAIT_L(0); if (full) PG8_MMA(1, 0, At, B0); PG8_BAR; PG8_SCHED;
	s_add_u32 s76, s48, 0x80000
	s_addc_u32 s77, s49, 0
	s_add_i32 s75, s68, s57
	v_lshl_add_u64 v[128:129], s[76:77], 0, v[142:143]
	s_mov_b32 m0, s75
	s_nop 0
	global_load_lds_dwordx4 v[128:129], off
	v_lshl_add_u64 v[128:129], s[76:77], 0, v[146:147]
	s_add_i32 m0, s75, 0x2000
	s_nop 0
	global_load_lds_dwordx4 v[128:129], off
	s_waitcnt vmcnt(6)
	s_barrier
	s_setprio 1
	v_mfma_f32_16x16x32_bf16 v[52:55], v[192:195], v[160:163], 0
	v_mfma_f32_16x16x32_bf16 v[48:51], v[200:203], v[160:163], 0
	v_mfma_f32_16x16x32_bf16 v[36:39], v[192:195], v[168:171], 0
	v_mfma_f32_16x16x32_bf16 v[32:35], v[200:203], v[168:171], 0
	v_mfma_f32_16x16x32_bf16 v[20:23], v[192:195], v[176:179], 0
	v_mfma_f32_16x16x32_bf16 v[16:19], v[200:203], v[176:179], 0
	v_mfma_f32_16x16x32_bf16 v[4:7], v[192:195], v[184:187], 0
	v_mfma_f32_16x16x32_bf16 v[0:3], v[200:203], v[184:187], 0
	v_mfma_f32_16x16x32_bf16 v[52:55], v[196:199], v[164:167], v[52:55]
	v_mfma_f32_16x16x32_bf16 v[48:51], v[204:207], v[164:167], v[48:51]
	v_mfma_f32_16x16x32_bf16 v[36:39], v[196:199], v[172:175], v[36:39]
	v_mfma_f32_16x16x32_bf16 v[32:35], v[204:207], v[172:175], v[32:35]
	v_mfma_f32_16x16x32_bf16 v[20:23], v[196:199], v[180:183], v[20:23]
	v_mfma_f32_16x16x32_bf16 v[16:19], v[204:207], v[180:183], v[16:19]
	v_mfma_f32_16x16x32_bf16 v[4:7], v[196:199], v[188:191], v[4:7]
	v_mfma_f32_16x16x32_bf16 v[0:3], v[204:207], v[188:191], v[0:3]
	s_setprio 0
	s_add_i32 s75, 0, 0x18000
	v_add_u32_e32 v156, s75, v224
	s_barrier
	ds_read_b128 v[128:131], v156
	ds_read_b128 v[132:135], v156 offset:1024
	ds_read_b128 v[136:139], v156 offset:2048
	ds_read_b128 v[156:159], v156 offset:3072
	s_add_u32 s50, s50, 0x80000
	s_addc_u32 s51, s51, 0
	s_mov_b32 m0, s60
	v_lshl_add_u64 v[192:193], s[50:51], 0, v[140:141]
	ds_read_b128 v[160:163], v231 offset:32768
	ds_read_b128 v[164:167], v231 offset:33792
	ds_read_b128 v[168:171], v231 offset:34816
	ds_read_b128 v[172:175], v231 offset:35840
	ds_read_b128 v[176:179], v231 offset:36864
	ds_read_b128 v[180:183], v231 offset:37888
	ds_read_b128 v[184:187], v231 offset:38912
	ds_read_b128 v[188:191], v231 offset:39936
	global_load_lds_dwordx4 v[192:193], off
	v_lshl_add_u64 v[192:193], s[50:51], 0, v[144:145]
	s_mov_b32 m0, s61
	s_nop 0
	global_load_lds_dwordx4 v[192:193], off
	s_waitcnt lgkmcnt(8)
	s_barrier
	s_waitcnt lgkmcnt(0)
	s_setprio 1
	s_waitcnt lgkmcnt(0)
	v_mfma_f32_16x16x32_bf16 v[124:127], v[128:131], v[160:163], v[124:127]
	v_mfma_f32_16x16x32_bf16 v[120:123], v[136:139], v[160:163], v[120:123]
	v_mfma_f32_16x16x32_bf16 v[108:111], v[128:131], v[168:171], v[108:111]
	v_mfma_f32_16x16x32_bf16 v[104:107], v[136:139], v[168:171], v[104:107]
	v_mfma_f32_16x16x32_bf16 v[92:95], v[128:131], v[176:179], v[92:95]
	v_mfma_f32_16x16x32_bf16 v[88:91], v[136:139], v[176:179], v[88:91]
	v_mfma_f32_16x16x32_bf16 v[76:79], v[128:131], v[184:187], v[76:79]
	v_mfma_f32_16x16x32_bf16 v[72:75], v[136:139], v[184:187], v[72:75]
	v_mfma_f32_16x16x32_bf16 v[124:127], v[132:135], v[164:167], v[124:127]
	v_mfma_f32_16x16x32_bf16 v[120:123], v[156:159], v[164:167], v[120:123]
	v_mfma_f32_16x16x32_bf16 v[108:111], v[132:135], v[172:175], v[108:111]
	v_mfma_f32_16x16x32_bf16 v[104:107], v[156:159], v[172:175], v[104:107]
	v_mfma_f32_16x16x32_bf16 v[92:95], v[132:135], v[180:183], v[92:95]
	v_mfma_f32_16x16x32_bf16 v[88:91], v[156:159], v[180:183], v[88:91]
	v_mfma_f32_16x16x32_bf16 v[76:79], v[132:135], v[188:191], v[76:79]
	v_mfma_f32_16x16x32_bf16 v[72:75], v[156:159], v[188:191], v[72:75]
	s_setprio 0
	s_barrier
	s_add_i32 s50, 0, 0x1c000
	s_add_i32 s51, s75, s57
	v_add_u32_e32 v204, s50, v224
	v_lshl_add_u64 v[208:209], v[208:209], 0, s[14:15]
	s_mov_b32 m0, s51
	ds_read_b128 v[192:195], v204
	ds_read_b128 v[196:199], v204 offset:1024
	ds_read_b128 v[200:203], v204 offset:2048
	ds_read_b128 v[204:207], v204 offset:3072
	global_load_lds_dwordx4 v[208:209], off
	v_lshl_add_u64 v[208:209], v[210:211], 0, s[14:15]
	s_add_i32 m0, s51, 0x2000
	s_nop 0
	global_load_lds_dwordx4 v[208:209], off
	s_barrier
; #define PG8_STAGE(bufoff, gbase, voff) do { _Pragma("unroll") for (int _i = 0; _i < 2; ++_i) \
;         __builtin_amdgcn_global_load_lds((const unsigned*)((const char*)(gbase) + (voff)[_i]), (LAS unsigned*)(lds + (bufoff) + ldsw + _i * 8192), 16, 0, 0); } while (0)
; #define PG8_LDA(dst, b, h) do { _Pragma("unroll") for (int m = 0; m < 4; ++m) _Pragma("unroll") for (int k = 0; k < 2; ++k) dst[m][k] = *(const LAS bf16x8*)(lds + PG8_SA(b, h) + aoff + m * 2048 + k * 1024); } while (0)
; #define PG8_MMA(ai, bj, At, Bt) do { __builtin_amdgcn_s_setprio(1); _Pragma("unroll") for (int m = 0; m < 4; ++m) _Pragma("unroll") for (int n = 0; n < 2; ++n) _Pragma("unroll") for (int k = 0; k < 2; ++k) \
;         acc[ai][bj][m][n] = __builtin_amdgcn_mfma_f32_16x16x32_bf16(Bt[n][k], At[m][k], acc[ai][bj][m][n], 0, 0, 0); __builtin_amdgcn_s_setprio(0); } while (0)
; #define PG8_WAIT_V(n) asm volatile("s_waitcnt vmcnt(" #n ")" ::: "memory")
; #define PG8_WAIT_L(n) asm volatile("s_waitcnt lgkmcnt(" #n ")" ::: "memory")
; #define PG8_BAR __builtin_amdgcn_s_barrier()
; #define PG8_SCHED __builtin_amdgcn_sched_barrier(0)
; template <class Epi>
; DI void gemm_phase(LAS unsigned char* lds, int wid, int K, int lda, int ldb, bool bperm, const Sched3& S, const Epi& E) {
;     ...
;             PG8_LDA(At, 1, 1); PG8_STAGE(PG8_SA(1, 0), a3, voffA);
;             PG8_BAR; PG8_WAIT_L(0); if (full) PG8_MMA(1, 0, At, B0); PG8_BAR; PG8_SCHED;
;             PG8_STAGE(PG8_SB(1, 1), b3 + hstepB, voffB);
;             PG8_WAIT_V(6); PG8_BAR; if (full) PG8_MMA(1, 1, At, B1); PG8_BAR;
;         }
	s_waitcnt lgkmcnt(0)
	s_setprio 1
	s_waitcnt lgkmcnt(0)
	v_mfma_f32_16x16x32_bf16 v[116:119], v[192:195], v[160:163], v[116:119]
	v_mfma_f32_16x16x32_bf16 v[112:115], v[200:203], v[160:163], v[112:115]
	v_mfma_f32_16x16x32_bf16 v[100:103], v[192:195], v[168:171], v[100:103]
	v_mfma_f32_16x16x32_bf16 v[96:99], v[200:203], v[168:171], v[96:99]
	v_mfma_f32_16x16x32_bf16 v[84:87], v[192:195], v[176:179], v[84:87]
	v_mfma_f32_16x16x32_bf16 v[80:83], v[200:203], v[176:179], v[80:83]
	v_mfma_f32_16x16x32_bf16 v[68:71], v[192:195], v[184:187], v[68:71]
	v_mfma_f32_16x16x32_bf16 v[64:67], v[200:203], v[184:187], v[64:67]
	v_mfma_f32_16x16x32_bf16 v[116:119], v[196:199], v[164:167], v[116:119]
	v_mfma_f32_16x16x32_bf16 v[112:115], v[204:207], v[164:167], v[112:115]
	v_mfma_f32_16x16x32_bf16 v[100:103], v[196:199], v[172:175], v[100:103]
	v_mfma_f32_16x16x32_bf16 v[96:99], v[204:207], v[172:175], v[96:99]
	v_mfma_f32_16x16x32_bf16 v[84:87], v[196:199], v[180:183], v[84:87]
	v_mfma_f32_16x16x32_bf16 v[80:83], v[204:207], v[180:183], v[80:83]
	v_mfma_f32_16x16x32_bf16 v[68:71], v[196:199], v[188:191], v[68:71]
	v_mfma_f32_16x16x32_bf16 v[64:67], v[204:207], v[188:191], v[64:67]
	s_setprio 0
	s_mov_b32 m0, s63
	v_lshl_add_u64 v[208:209], v[212:213], 0, s[14:15]
	s_barrier
	ds_read_b128 v[160:163], v231 offset:49152
	ds_read_b128 v[164:167], v231 offset:50176
	ds_read_b128 v[168:171], v231 offset:51200
	ds_read_b128 v[172:175], v231 offset:52224
	ds_read_b128 v[176:179], v231 offset:53248
	ds_read_b128 v[180:183], v231 offset:54272
	ds_read_b128 v[184:187], v231 offset:55296
	ds_read_b128 v[188:191], v231 offset:56320
	global_load_lds_dwordx4 v[208:209], off
	v_lshl_add_u64 v[208:209], v[214:215], 0, s[14:15]
	s_mov_b32 m0, s64
	s_nop 0
	global_load_lds_dwordx4 v[208:209], off
	s_barrier
	s_waitcnt lgkmcnt(0)
	s_setprio 1
	s_waitcnt lgkmcnt(0)
	v_mfma_f32_16x16x32_bf16 v[60:63], v[128:131], v[160:163], v[60:63]
	v_mfma_f32_16x16x32_bf16 v[56:59], v[136:139], v[160:163], v[56:59]
	v_mfma_f32_16x16x32_bf16 v[44:47], v[128:131], v[168:171], v[44:47]
	v_mfma_f32_16x16x32_bf16 v[40:43], v[136:139], v[168:171], v[40:43]
	v_mfma_f32_16x16x32_bf16 v[28:31], v[128:131], v[176:179], v[28:31]
	v_mfma_f32_16x16x32_bf16 v[24:27], v[136:139], v[176:179], v[24:27]
	v_mfma_f32_16x16x32_bf16 v[12:15], v[128:131], v[184:187], v[12:15]
	v_mfma_f32_16x16x32_bf16 v[8:11], v[136:139], v[184:187], v[8:11]
	v_mfma_f32_16x16x32_bf16 v[60:63], v[132:135], v[164:167], v[60:63]
	v_mfma_f32_16x16x32_bf16 v[56:59], v[156:159], v[164:167], v[56:59]
	v_mfma_f32_16x16x32_bf16 v[44:47], v[132:135], v[172:175], v[44:47]
	v_mfma_f32_16x16x32_bf16 v[40:43], v[156:159], v[172:175], v[40:43]
	v_mfma_f32_16x16x32_bf16 v[28:31], v[132:135], v[180:183], v[28:31]
	v_mfma_f32_16x16x32_bf16 v[24:27], v[156:159], v[180:183], v[24:27]
	v_mfma_f32_16x16x32_bf16 v[12:15], v[132:135], v[188:191], v[12:15]
	v_mfma_f32_16x16x32_bf16 v[8:11], v[156:159], v[188:191], v[8:11]
	s_setprio 0
	s_barrier
	s_add_u32 s48, s48, 0x80080
	s_addc_u32 s49, s49, 0
	s_add_i32 s50, s50, s57
	v_lshl_add_u64 v[128:129], s[48:49], 0, v[142:143]
	s_mov_b32 m0, s50
	s_nop 0
	global_load_lds_dwordx4 v[128:129], off
	v_lshl_add_u64 v[128:129], s[48:49], 0, v[146:147]
	s_add_i32 m0, s50, 0x2000
	s_nop 0
	global_load_lds_dwordx4 v[128:129], off
	s_waitcnt vmcnt(6)
	s_barrier
	s_setprio 1
	v_mfma_f32_16x16x32_bf16 v[52:55], v[192:195], v[160:163], v[52:55]
	v_mfma_f32_16x16x32_bf16 v[48:51], v[200:203], v[160:163], v[48:51]
	v_mfma_f32_16x16x32_bf16 v[36:39], v[192:195], v[168:171], v[36:39]
	v_mfma_f32_16x16x32_bf16 v[32:35], v[200:203], v[168:171], v[32:35]
	v_mfma_f32_16x16x32_bf16 v[20:23], v[192:195], v[176:179], v[20:23]
	v_mfma_f32_16x16x32_bf16 v[16:19], v[200:203], v[176:179], v[16:19]
	v_mfma_f32_16x16x32_bf16 v[4:7], v[192:195], v[184:187], v[4:7]
	v_mfma_f32_16x16x32_bf16 v[0:3], v[200:203], v[184:187], v[0:3]
	v_mfma_f32_16x16x32_bf16 v[52:55], v[196:199], v[164:167], v[52:55]
	v_mfma_f32_16x16x32_bf16 v[48:51], v[204:207], v[164:167], v[48:51]
	v_mfma_f32_16x16x32_bf16 v[36:39], v[196:199], v[172:175], v[36:39]
	v_mfma_f32_16x16x32_bf16 v[32:35], v[204:207], v[172:175], v[32:35]
	v_mfma_f32_16x16x32_bf16 v[20:23], v[196:199], v[180:183], v[20:23]
	v_mfma_f32_16x16x32_bf16 v[16:19], v[204:207], v[180:183], v[16:19]
	v_mfma_f32_16x16x32_bf16 v[4:7], v[196:199], v[188:191], v[4:7]
	v_mfma_f32_16x16x32_bf16 v[0:3], v[204:207], v[188:191], v[0:3]
	s_setprio 0
	s_add_i32 s55, s55, 2
	s_add_u32 s46, s46, 0x100
	s_addc_u32 s47, s47, 0
	s_add_u32 s53, s53, 0x100
	s_addc_u32 s54, s54, 0
	s_cmp_gt_u32 s55, 29
	s_barrier
	s_cbranch_scc0 .LBB0_327
	s_branch .Lpeel_0_exit

; DI float gelu_tanh(float x) { const float t = x * (1.5957691216f + 0.0713548163f * x * x); return x * __builtin_amdgcn_rcpf(1.f + __builtin_amdgcn_exp2f(-1.4426950409f * t)); }
; #define ROWS8 _Pragma("unroll") for (int ai = 0; ai < 2; ++ai) _Pragma("unroll") for (int m = 0; m < 4; ++m) if (ai == 0 || !hf)
; #define PK8(v0, v1) ({ const u32x2 h0_ = pk4(v0), h1_ = pk4(v1); (u32x4){h0_.x, h0_.y, h1_.x, h1_.y}; })
; #define LOAD_COLP_RS(rsc, ssqp, invn) f32x4 rsc[2][2]; COLS4 rsc[bj][n] = *(const f32x4*)((ssqp) + colp + bj * HALF + n * 4); \
;         COLS4 rsc[bj][n] = (f32x4){rstd_of(rsc[bj][n][0], invn), rstd_of(rsc[bj][n][1], invn), rstd_of(rsc[bj][n][2], invn), rstd_of(rsc[bj][n][3], invn)}
;     DI void operator()(const Acc& acc, const Unit& u, int wr, int wc, int fr, int fq) const {
;     ...
;             } else {
;                 float* ssqv = SSQ(1 + sqo);
;                 LOAD_COLP_RS(rsc, SSQ(0), 1.f / 2048.f);
; #pragma unroll
;                 for (int bj = 0; bj < 2; ++bj) { const int cc = colp + bj * HALF;
;                     f32x4 sq0 = {0.f, 0.f, 0.f, 0.f}, sq1 = {0.f, 0.f, 0.f, 0.f};
;                     ROWS8 { const int r = row0 + ai * HALF + m * 16; f32x4 v0 = acc[ai][bj][m][0] * rsc[bj][0], v1 = acc[ai][bj][m][1] * rsc[bj][1];
;                         v0[0] = gelu_tanh(v0[0]); v0[1] = gelu_tanh(v0[1]); v0[2] = gelu_tanh(v0[2]); v0[3] = gelu_tanh(v0[3]);
;                         v1[0] = gelu_tanh(v1[0]); v1[1] = gelu_tanh(v1[1]); v1[2] = gelu_tanh(v1[2]); v1[3] = gelu_tanh(v1[3]);
;                         sq0 += v0 * v0; sq1 += v1 * v1; *(u32x4*)(WSB(OFF_VT) + (size_t)r * 8192 + cc) = PK8(v0, v1); }
.Lpeel_0_exit:
	v_lshl_add_u32 v158, s4, 8, v223
	v_lshl_add_u32 v156, s73, 8, v225
	v_or_b32_e32 v164, 16, v158
	v_or_b32_e32 v162, 32, v158
	v_or_b32_e32 v160, 48, v158
	s_cmp_lg_u32 s74, 0
	v_ashrrev_i32_e32 v157, 31, v156
	v_ashrrev_i32_e32 v159, 31, v158
	v_ashrrev_i32_e32 v165, 31, v164
	v_ashrrev_i32_e32 v163, 31, v162
	v_ashrrev_i32_e32 v161, 31, v160
	s_cbranch_scc0 .LBB0_362
	v_lshlrev_b64 v[136:137], 2, v[156:157]
	v_lshl_add_u64 v[132:133], s[16:17], 0, v[136:137]
	global_load_dwordx4 v[166:169], v[132:133], off
	global_load_dwordx4 v[172:175], v[132:133], off offset:16
	v_lshlrev_b64 v[128:129], 14, v[158:159]
	v_lshlrev_b64 v[170:171], 1, v[156:157]
	v_lshl_add_u64 v[138:139], s[20:21], 0, v[128:129]
	v_lshl_add_u64 v[138:139], v[138:139], 0, v[170:171]
	global_load_dwordx4 v[128:131], v[132:133], off offset:528
	s_nop 0
	global_load_dwordx4 v[132:135], v[132:133], off offset:512
	v_lshl_add_u64 v[136:137], s[18:19], 0, v[136:137]
	s_waitcnt vmcnt(0)
	v_fmamk_f32 v166, v166, 0x3a000000, v233
	v_fmamk_f32 v167, v167, 0x3a000000, v233
	v_fmamk_f32 v168, v168, 0x3a000000, v233
	v_fmamk_f32 v169, v169, 0x3a000000, v233
	v_rsq_f32_e32 v190, v166
	v_rsq_f32_e32 v191, v167
	v_rsq_f32_e32 v186, v168
	v_rsq_f32_e32 v187, v169
	v_fmamk_f32 v172, v172, 0x3a000000, v233
	v_fmamk_f32 v173, v173, 0x3a000000, v233
	v_fmamk_f32 v174, v174, 0x3a000000, v233
	v_fmamk_f32 v175, v175, 0x3a000000, v233
	v_rsq_f32_e32 v182, v172
	v_rsq_f32_e32 v184, v174
	v_rsq_f32_e32 v185, v175
	v_rsq_f32_e32 v183, v173
	v_pk_mul_f32 v[168:169], v[124:125], v[190:191]
	v_pk_mul_f32 v[166:167], v[126:127], v[186:187]
	v_mul_f32_e32 v178, 0x3d922279, v168
	v_mul_f32_e32 v179, 0x3d922279, v169
	v_mul_f32_e32 v192, 0x3d922279, v166
	v_mul_f32_e32 v193, 0x3d922279, v167
	v_fmaak_f32 v178, v168, v178, 0x3fcc422a
	v_fmaak_f32 v179, v169, v179, 0x3fcc422a
	v_pk_mul_f32 v[172:173], v[122:123], v[184:185]
	v_pk_mul_f32 v[174:175], v[120:121], v[182:183]
	v_fmaak_f32 v192, v166, v192, 0x3fcc422a
	v_fmaak_f32 v193, v167, v193, 0x3fcc422a
	v_mul_f32_e32 v178, v168, v178
	v_mul_f32_e32 v179, v169, v179
	v_mul_f32_e32 v196, 0x3d922279, v174
	v_mul_f32_e32 v197, 0x3d922279, v175
	v_mul_f32_e32 v198, 0x3d922279, v172
	v_mul_f32_e32 v199, 0x3d922279, v173
	v_mul_f32_e32 v192, v166, v192
	v_mul_f32_e32 v193, v167, v193
	v_mul_f32_e32 v178, 0xbfb8aa3b, v178
	v_mul_f32_e32 v179, 0xbfb8aa3b, v179
	v_fmaak_f32 v196, v174, v196, 0x3fcc422a
	v_fmaak_f32 v197, v175, v197, 0x3fcc422a
	v_fmaak_f32 v198, v172, v198, 0x3fcc422a
	v_fmaak_f32 v199, v173, v199, 0x3fcc422a
	v_mul_f32_e32 v192, 0xbfb8aa3b, v192
	v_mul_f32_e32 v193, 0xbfb8aa3b, v193
	v_exp_f32_e32 v178, v178
	v_exp_f32_e32 v179, v179
	v_mul_f32_e32 v196, v174, v196
	v_mul_f32_e32 v197, v175, v197
	v_mul_f32_e32 v198, v172, v198
	v_mul_f32_e32 v199, v173, v199
	v_exp_f32_e32 v192, v192
	v_exp_f32_e32 v193, v193
	v_mul_f32_e32 v196, 0xbfb8aa3b, v196
	v_mul_f32_e32 v197, 0xbfb8aa3b, v197
	v_mul_f32_e32 v198, 0xbfb8aa3b, v198
	v_mul_f32_e32 v199, 0xbfb8aa3b, v199
	v_exp_f32_e32 v196, v196
	v_exp_f32_e32 v197, v197
	v_exp_f32_e32 v198, v198
	v_exp_f32_e32 v199, v199
	v_add_f32_e32 v178, 1.0, v178
	v_add_f32_e32 v179, 1.0, v179
	v_add_f32_e32 v201, 1.0, v192
	v_add_f32_e32 v202, 1.0, v193
	v_rcp_f32_e32 v192, v178
	v_rcp_f32_e32 v193, v179
	v_add_f32_e32 v196, 1.0, v196
	v_add_f32_e32 v197, 1.0, v197
	v_add_f32_e32 v198, 1.0, v198
	v_add_f32_e32 v199, 1.0, v199
	v_pk_mul_f32 v[194:195], v[104:105], v[182:183]
	v_rcp_f32_e32 v178, v201
	v_rcp_f32_e32 v179, v202
	v_rcp_f32_e32 v196, v196
	v_rcp_f32_e32 v198, v198
	v_rcp_f32_e32 v199, v199
	v_rcp_f32_e32 v197, v197
	v_pk_mul_f32 v[202:203], v[168:169], v[192:193]
	v_mul_f32_e32 v192, 0x3d922279, v194
	v_fmaak_f32 v192, v194, v192, 0x3fcc422a
	v_mul_f32_e32 v192, v194, v192
	v_pk_mul_f32 v[178:179], v[166:167], v[178:179]
	v_pk_mul_f32 v[172:173], v[172:173], v[198:199]
	v_pk_mul_f32 v[174:175], v[174:175], v[196:197]
	v_mul_f32_e32 v192, 0xbfb8aa3b, v192
	v_pk_mul_f32 v[176:177], v[110:111], v[186:187]
	v_pk_mul_f32 v[188:189], v[106:107], v[184:185]
	v_cvt_pk_bf16_f32 v166, v202, v203
	v_cvt_pk_bf16_f32 v167, v178, v179
	v_cvt_pk_bf16_f32 v168, v174, v175
	v_cvt_pk_bf16_f32 v169, v172, v173
	v_exp_f32_e32 v192, v192
	global_store_dwordx4 v[138:139], v[166:169], off
	v_mul_f32_e32 v193, 0x3d922279, v188
	v_fmaak_f32 v193, v188, v193, 0x3fcc422a
	v_mul_f32_e32 v168, 0x3d922279, v176
	v_mul_f32_e32 v169, 0x3d922279, v177
	v_fmaak_f32 v168, v176, v168, 0x3fcc422a
	v_fmaak_f32 v169, v177, v169, 0x3fcc422a
	v_mul_f32_e32 v197, 0x3d922279, v189
	v_mul_f32_e32 v168, v176, v168
	v_mul_f32_e32 v169, v177, v169
	v_mul_f32_e32 v193, v188, v193
	v_fmaak_f32 v197, v189, v197, 0x3fcc422a
	v_mul_f32_e32 v168, 0xbfb8aa3b, v168
	v_mul_f32_e32 v169, 0xbfb8aa3b, v169
	v_add_f32_e32 v192, 1.0, v192
	v_mul_f32_e32 v193, 0xbfb8aa3b, v193
	v_mul_f32_e32 v197, v189, v197
	v_exp_f32_e32 v168, v168
	v_exp_f32_e32 v169, v169
	v_rcp_f32_e32 v196, v192
	v_mul_f32_e32 v192, 0x3d922279, v195
	v_exp_f32_e32 v193, v193
	v_mul_f32_e32 v197, 0xbfb8aa3b, v197
	v_fmaak_f32 v192, v195, v192, 0x3fcc422a
	v_exp_f32_e32 v197, v197
	v_mul_f32_e32 v192, v195, v192
	v_mul_f32_e32 v192, 0xbfb8aa3b, v192
	v_add_f32_e32 v168, 1.0, v168
	v_add_f32_e32 v169, 1.0, v169
	v_exp_f32_e32 v192, v192
	v_add_f32_e32 v193, 1.0, v193
	v_pk_mul_f32 v[180:181], v[108:109], v[190:191]
	v_rcp_f32_e32 v168, v168
	v_rcp_f32_e32 v169, v169
	v_rcp_f32_e32 v198, v193
	v_add_f32_e32 v193, 1.0, v197
	v_mul_f32_e32 v200, 0x3d922279, v180
	v_mul_f32_e32 v167, 0x3d922279, v181
	v_rcp_f32_e32 v199, v193
	v_fmaak_f32 v200, v180, v200, 0x3fcc422a
; DI float gelu_tanh(float x) { const float t = x * (1.5957691216f + 0.0713548163f * x * x); return x * __builtin_amdgcn_rcpf(1.f + __builtin_amdgcn_exp2f(-1.4426950409f * t)); }
; #define ROWS8 _Pragma("unroll") for (int ai = 0; ai < 2; ++ai) _Pragma("unroll") for (int m = 0; m < 4; ++m) if (ai == 0 || !hf)
; #define PK8(v0, v1) ({ const u32x2 h0_ = pk4(v0), h1_ = pk4(v1); (u32x4){h0_.x, h0_.y, h1_.x, h1_.y}; })
;     DI void operator()(const Acc& acc, const Unit& u, int wr, int wc, int fr, int fq) const {
;     ...
;                     ROWS8 { const int r = row0 + ai * HALF + m * 16; f32x4 v0 = acc[ai][bj][m][0] * rsc[bj][0], v1 = acc[ai][bj][m][1] * rsc[bj][1];
;                         v0[0] = gelu_tanh(v0[0]); v0[1] = gelu_tanh(v0[1]); v0[2] = gelu_tanh(v0[2]); v0[3] = gelu_tanh(v0[3]);
;                         v1[0] = gelu_tanh(v1[0]); v1[1] = gelu_tanh(v1[1]); v1[2] = gelu_tanh(v1[2]); v1[3] = gelu_tanh(v1[3]);
;                         sq0 += v0 * v0; sq1 += v1 * v1; *(u32x4*)(WSB(OFF_VT) + (size_t)r * 8192 + cc) = PK8(v0, v1); }
	v_fmaak_f32 v167, v181, v167, 0x3fcc422a
	v_mul_f32_e32 v200, v180, v200
	v_mul_f32_e32 v167, v181, v167
	v_add_f32_e32 v192, 1.0, v192
	v_mul_f32_e32 v200, 0xbfb8aa3b, v200
	v_mul_f32_e32 v167, 0xbfb8aa3b, v167
	v_rcp_f32_e32 v197, v192
	v_pk_mul_f32 v[192:193], v[176:177], v[168:169]
	v_pk_mul_f32 v[168:169], v[92:93], v[190:191]
	v_exp_f32_e32 v200, v200
	v_exp_f32_e32 v167, v167
	v_pk_mul_f32 v[176:177], v[188:189], v[198:199]
	v_mul_f32_e32 v188, 0x3d922279, v168
	v_fmaak_f32 v188, v168, v188, 0x3fcc422a
	v_mul_f32_e32 v188, v168, v188
	v_mul_f32_e32 v188, 0xbfb8aa3b, v188
	v_add_f32_e32 v166, 1.0, v200
	v_add_f32_e32 v167, 1.0, v167
	v_exp_f32_e32 v198, v188
	v_pk_mul_f32 v[188:189], v[94:95], v[186:187]
	v_mul_f32_e32 v199, 0x3d922279, v169
	v_rcp_f32_e32 v166, v166
	v_rcp_f32_e32 v167, v167
	v_fmaak_f32 v199, v169, v199, 0x3fcc422a
	v_mul_f32_e32 v200, 0x3d922279, v188
	v_mul_f32_e32 v199, v169, v199
	v_fmaak_f32 v200, v188, v200, 0x3fcc422a
	v_mul_f32_e32 v199, 0xbfb8aa3b, v199
	v_mul_f32_e32 v200, v188, v200
	v_exp_f32_e32 v199, v199
	v_mul_f32_e32 v200, 0xbfb8aa3b, v200
	v_pk_mul_f32 v[210:211], v[180:181], v[166:167]
	v_lshlrev_b64 v[166:167], 14, v[164:165]
	v_exp_f32_e32 v204, v200
	v_pk_mul_f32 v[180:181], v[194:195], v[196:197]
	v_lshl_add_u64 v[166:167], s[20:21], 0, v[166:167]
	v_cvt_pk_bf16_f32 v194, v210, v211
	v_cvt_pk_bf16_f32 v195, v192, v193
	v_cvt_pk_bf16_f32 v196, v180, v181
	v_cvt_pk_bf16_f32 v197, v176, v177
	v_lshl_add_u64 v[166:167], v[166:167], 0, v[170:171]
	v_add_f32_e32 v198, 1.0, v198
	global_store_dwordx4 v[166:167], v[194:197], off
	v_rcp_f32_e32 v200, v198
	v_add_f32_e32 v198, 1.0, v199
	v_pk_mul_f32 v[194:195], v[90:91], v[184:185]
	v_pk_mul_f32 v[196:197], v[88:89], v[182:183]
	v_rcp_f32_e32 v201, v198
	v_add_f32_e32 v198, 1.0, v204
	v_mul_f32_e32 v199, 0x3d922279, v189
	v_mul_f32_e32 v204, 0x3d922279, v196
	v_mul_f32_e32 v205, 0x3d922279, v197
	v_mul_f32_e32 v206, 0x3d922279, v194
	v_mul_f32_e32 v207, 0x3d922279, v195
	v_fmaak_f32 v199, v189, v199, 0x3fcc422a
	v_fmaak_f32 v204, v196, v204, 0x3fcc422a
	v_fmaak_f32 v205, v197, v205, 0x3fcc422a
	v_fmaak_f32 v206, v194, v206, 0x3fcc422a
	v_fmaak_f32 v207, v195, v207, 0x3fcc422a
	v_mul_f32_e32 v199, v189, v199
	v_mul_f32_e32 v204, v196, v204
	v_mul_f32_e32 v205, v197, v205
	v_mul_f32_e32 v206, v194, v206
	v_mul_f32_e32 v207, v195, v207
	v_mul_f32_e32 v199, 0xbfb8aa3b, v199
	v_mul_f32_e32 v204, 0xbfb8aa3b, v204
	v_mul_f32_e32 v205, 0xbfb8aa3b, v205
	v_mul_f32_e32 v206, 0xbfb8aa3b, v206
	v_mul_f32_e32 v207, 0xbfb8aa3b, v207
	v_exp_f32_e32 v199, v199
	v_exp_f32_e32 v204, v204
	v_exp_f32_e32 v205, v205
	v_exp_f32_e32 v206, v206
	v_exp_f32_e32 v207, v207
	v_add_f32_e32 v199, 1.0, v199
	v_add_f32_e32 v204, 1.0, v204
	v_add_f32_e32 v205, 1.0, v205
	v_add_f32_e32 v206, 1.0, v206
	v_add_f32_e32 v207, 1.0, v207
	v_rcp_f32_e32 v198, v198
	v_rcp_f32_e32 v199, v199
	v_rcp_f32_e32 v204, v204
	v_rcp_f32_e32 v206, v206
	v_rcp_f32_e32 v207, v207
	v_rcp_f32_e32 v205, v205
	v_pk_mul_f32 v[198:199], v[188:189], v[198:199]
	v_pk_mul_f32 v[212:213], v[168:169], v[200:201]
	v_pk_mul_f32 v[188:189], v[194:195], v[206:207]
	v_pk_mul_f32 v[194:195], v[196:197], v[204:205]
	v_pk_mul_f32 v[196:197], v[76:77], v[190:191]
	v_lshlrev_b64 v[168:169], 14, v[162:163]
	v_mul_f32_e32 v200, 0x3d922279, v196
	v_fmaak_f32 v200, v196, v200, 0x3fcc422a
	v_lshl_add_u64 v[168:169], s[20:21], 0, v[168:169]
	v_mul_f32_e32 v200, v196, v200
	v_cvt_pk_bf16_f32 v204, v212, v213
	v_cvt_pk_bf16_f32 v205, v198, v199
	v_cvt_pk_bf16_f32 v206, v194, v195
	v_cvt_pk_bf16_f32 v207, v188, v189
	v_lshl_add_u64 v[168:169], v[168:169], 0, v[170:171]
	v_mul_f32_e32 v200, 0xbfb8aa3b, v200
	global_store_dwordx4 v[168:169], v[204:207], off
	v_pk_mul_f32 v[208:209], v[72:73], v[182:183]
	s_nop 0
	v_exp_f32_e32 v204, v200
	v_pk_mul_f32 v[200:201], v[78:79], v[186:187]
	v_mul_f32_e32 v205, 0x3d922279, v197
	v_fmaak_f32 v205, v197, v205, 0x3fcc422a
	v_mul_f32_e32 v214, 0x3d922279, v200
	v_mul_f32_e32 v205, v197, v205
	v_fmaak_f32 v214, v200, v214, 0x3fcc422a
	v_mul_f32_e32 v205, 0xbfb8aa3b, v205
	v_mul_f32_e32 v214, v200, v214
	v_exp_f32_e32 v205, v205
	v_mul_f32_e32 v214, 0xbfb8aa3b, v214
	v_exp_f32_e32 v216, v214
	v_add_f32_e32 v204, 1.0, v204
	v_rcp_f32_e32 v214, v204
	v_add_f32_e32 v204, 1.0, v205
	v_pk_mul_f32 v[206:207], v[74:75], v[184:185]
	v_rcp_f32_e32 v215, v204
	v_add_f32_e32 v204, 1.0, v216
	v_mul_f32_e32 v205, 0x3d922279, v201
	v_mul_f32_e32 v216, 0x3d922279, v208
	v_mul_f32_e32 v217, 0x3d922279, v209
	v_fmaak_f32 v205, v201, v205, 0x3fcc422a
	v_fmaak_f32 v216, v208, v216, 0x3fcc422a
	v_fmaak_f32 v217, v209, v217, 0x3fcc422a
	v_mul_f32_e32 v218, 0x3d922279, v206
	v_mul_f32_e32 v219, 0x3d922279, v207
	v_mul_f32_e32 v205, v201, v205
	v_mul_f32_e32 v216, v208, v216
	v_mul_f32_e32 v217, v209, v217
	v_fmaak_f32 v218, v206, v218, 0x3fcc422a
	v_fmaak_f32 v219, v207, v219, 0x3fcc422a
	v_mul_f32_e32 v205, 0xbfb8aa3b, v205
	v_mul_f32_e32 v216, 0xbfb8aa3b, v216
	v_mul_f32_e32 v217, 0xbfb8aa3b, v217
	v_mul_f32_e32 v218, v206, v218
	v_mul_f32_e32 v219, v207, v219
	v_exp_f32_e32 v205, v205
	v_exp_f32_e32 v216, v216
	v_exp_f32_e32 v217, v217
	v_mul_f32_e32 v218, 0xbfb8aa3b, v218
	v_mul_f32_e32 v219, 0xbfb8aa3b, v219
	v_exp_f32_e32 v218, v218
	v_exp_f32_e32 v219, v219
	v_add_f32_e32 v205, 1.0, v205
	v_add_f32_e32 v216, 1.0, v216
	v_add_f32_e32 v217, 1.0, v217
	v_rcp_f32_e32 v204, v204
	v_rcp_f32_e32 v205, v205
	v_rcp_f32_e32 v216, v216
	v_add_f32_e32 v218, 1.0, v218
	v_add_f32_e32 v219, 1.0, v219
	v_rcp_f32_e32 v217, v217
	v_rcp_f32_e32 v218, v218
	v_rcp_f32_e32 v219, v219
	v_pk_mul_f32 v[204:205], v[200:201], v[204:205]
; DI float gelu_tanh(float x) { const float t = x * (1.5957691216f + 0.0713548163f * x * x); return x * __builtin_amdgcn_rcpf(1.f + __builtin_amdgcn_exp2f(-1.4426950409f * t)); }
; #define ROWS8 _Pragma("unroll") for (int ai = 0; ai < 2; ++ai) _Pragma("unroll") for (int m = 0; m < 4; ++m) if (ai == 0 || !hf)
; #define PK8(v0, v1) ({ const u32x2 h0_ = pk4(v0), h1_ = pk4(v1); (u32x4){h0_.x, h0_.y, h1_.x, h1_.y}; })
;     DI void operator()(const Acc& acc, const Unit& u, int wr, int wc, int fr, int fq) const {
;     ...
;                     ROWS8 { const int r = row0 + ai * HALF + m * 16; f32x4 v0 = acc[ai][bj][m][0] * rsc[bj][0], v1 = acc[ai][bj][m][1] * rsc[bj][1];
;                         v0[0] = gelu_tanh(v0[0]); v0[1] = gelu_tanh(v0[1]); v0[2] = gelu_tanh(v0[2]); v0[3] = gelu_tanh(v0[3]);
;                         v1[0] = gelu_tanh(v1[0]); v1[1] = gelu_tanh(v1[1]); v1[2] = gelu_tanh(v1[2]); v1[3] = gelu_tanh(v1[3]);
;                         sq0 += v0 * v0; sq1 += v1 * v1; *(u32x4*)(WSB(OFF_VT) + (size_t)r * 8192 + cc) = PK8(v0, v1); }
; #pragma unroll
;                     for (int j = 0; j < 8; ++j) { float t = j < 4 ? sq0[j & 3] : sq1[j & 3];
;                         t += __shfl_xor(t, 1); t += __shfl_xor(t, 2); t += __shfl_xor(t, 4); t += __shfl_xor(t, 8);
;                         if (fr == 0) unsafeAtomicAdd(ssqv + cc + j, t); }
	v_pk_mul_f32 v[200:201], v[208:209], v[216:217]
	v_lshlrev_b64 v[216:217], 14, v[160:161]
	v_pk_mul_f32 v[214:215], v[196:197], v[214:215]
	v_pk_mul_f32 v[196:197], v[206:207], v[218:219]
	v_lshl_add_u64 v[216:217], s[20:21], 0, v[216:217]
	v_cvt_pk_bf16_f32 v206, v214, v215
	v_cvt_pk_bf16_f32 v207, v204, v205
	v_cvt_pk_bf16_f32 v208, v200, v201
	v_cvt_pk_bf16_f32 v209, v196, v197
	v_lshl_add_u64 v[170:171], v[216:217], 0, v[170:171]
	global_store_dwordx4 v[170:171], v[206:209], off
	s_nop 1
	v_pk_mul_f32 v[206:207], v[210:211], v[210:211]
	s_nop 0
	v_pk_fma_f32 v[202:203], v[202:203], v[202:203], v[206:207]
	s_nop 0
	v_pk_fma_f32 v[202:203], v[212:213], v[212:213], v[202:203]
	v_pk_mul_f32 v[212:213], v[58:59], v[184:185]
	v_pk_fma_f32 v[208:209], v[214:215], v[214:215], v[202:203]
	v_pk_mul_f32 v[202:203], v[60:61], v[190:191]
	v_pk_mul_f32 v[214:215], v[56:57], v[182:183]
	v_mul_f32_e32 v206, 0x3d922279, v202
	v_fmaak_f32 v206, v202, v206, 0x3fcc422a
	v_mul_f32_e32 v206, v202, v206
	v_mul_f32_e32 v206, 0xbfb8aa3b, v206
	v_exp_f32_e32 v210, v206
	v_pk_mul_f32 v[206:207], v[62:63], v[186:187]
	v_mul_f32_e32 v211, 0x3d922279, v203
	v_fmaak_f32 v211, v203, v211, 0x3fcc422a
	v_mul_f32_e32 v216, 0x3d922279, v206
	v_mul_f32_e32 v211, v203, v211
	v_fmaak_f32 v216, v206, v216, 0x3fcc422a
	v_mul_f32_e32 v211, 0xbfb8aa3b, v211
	v_mul_f32_e32 v216, v206, v216
	v_exp_f32_e32 v211, v211
	v_mul_f32_e32 v216, 0xbfb8aa3b, v216
	v_exp_f32_e32 v218, v216
	v_add_f32_e32 v210, 1.0, v210
	v_rcp_f32_e32 v216, v210
	v_add_f32_e32 v210, 1.0, v211
	v_rcp_f32_e32 v217, v210
	v_add_f32_e32 v210, 1.0, v218
	v_mul_f32_e32 v211, 0x3d922279, v207
	v_mul_f32_e32 v218, 0x3d922279, v214
	v_mul_f32_e32 v219, 0x3d922279, v215
	v_mul_f32_e32 v220, 0x3d922279, v212
	v_mul_f32_e32 v221, 0x3d922279, v213
	v_fmaak_f32 v211, v207, v211, 0x3fcc422a
	v_fmaak_f32 v218, v214, v218, 0x3fcc422a
	v_fmaak_f32 v219, v215, v219, 0x3fcc422a
	v_fmaak_f32 v220, v212, v220, 0x3fcc422a
	v_fmaak_f32 v221, v213, v221, 0x3fcc422a
	v_mul_f32_e32 v211, v207, v211
	v_mul_f32_e32 v218, v214, v218
	v_mul_f32_e32 v219, v215, v219
	v_mul_f32_e32 v220, v212, v220
	v_mul_f32_e32 v221, v213, v221
	v_mul_f32_e32 v211, 0xbfb8aa3b, v211
	v_mul_f32_e32 v218, 0xbfb8aa3b, v218
	v_mul_f32_e32 v219, 0xbfb8aa3b, v219
	v_mul_f32_e32 v220, 0xbfb8aa3b, v220
	v_mul_f32_e32 v221, 0xbfb8aa3b, v221
	v_exp_f32_e32 v211, v211
	v_exp_f32_e32 v218, v218
	v_exp_f32_e32 v219, v219
	v_exp_f32_e32 v220, v220
	v_exp_f32_e32 v221, v221
	v_add_f32_e32 v211, 1.0, v211
	v_add_f32_e32 v218, 1.0, v218
	v_add_f32_e32 v219, 1.0, v219
	v_add_f32_e32 v220, 1.0, v220
	v_add_f32_e32 v221, 1.0, v221
	v_rcp_f32_e32 v210, v210
	v_rcp_f32_e32 v211, v211
	v_rcp_f32_e32 v218, v218
	v_rcp_f32_e32 v220, v220
	v_rcp_f32_e32 v221, v221
	v_rcp_f32_e32 v219, v219
	v_pk_mul_f32 v[216:217], v[202:203], v[216:217]
	v_pk_mul_f32 v[210:211], v[206:207], v[210:211]
	v_pk_mul_f32 v[202:203], v[212:213], v[220:221]
	v_pk_mul_f32 v[206:207], v[214:215], v[218:219]
	v_pk_fma_f32 v[218:219], v[216:217], v[216:217], v[208:209]
	v_add_co_u32_e32 v208, vcc, s69, v138
	v_cvt_pk_bf16_f32 v212, v216, v217
	v_cvt_pk_bf16_f32 v213, v210, v211
	v_cvt_pk_bf16_f32 v214, v206, v207
	v_cvt_pk_bf16_f32 v215, v202, v203
	v_addc_co_u32_e32 v209, vcc, 0, v139, vcc
	global_store_dwordx4 v[208:209], v[212:215], off
	v_pk_mul_f32 v[208:209], v[44:45], v[190:191]
	v_pk_mul_f32 v[220:221], v[40:41], v[182:183]
	v_mul_f32_e32 v212, 0x3d922279, v208
	v_fmaak_f32 v212, v208, v212, 0x3fcc422a
	v_mul_f32_e32 v212, v208, v212
	v_mul_f32_e32 v212, 0xbfb8aa3b, v212
	v_exp_f32_e32 v216, v212
	v_pk_mul_f32 v[212:213], v[46:47], v[186:187]
	v_pk_mul_f32 v[214:215], v[42:43], v[184:185]
	v_mul_f32_e32 v234, 0x3d922279, v213
	v_fmaak_f32 v234, v213, v234, 0x3fcc422a
	v_mul_f32_e32 v222, 0x3d922279, v212
	v_mul_f32_e32 v234, v213, v234
	v_fmaak_f32 v222, v212, v222, 0x3fcc422a
	v_mul_f32_e32 v234, 0xbfb8aa3b, v234
	v_mul_f32_e32 v222, v212, v222
	v_exp_f32_e32 v235, v234
	v_mul_f32_e32 v234, 0x3d922279, v220
	v_mul_f32_e32 v222, 0xbfb8aa3b, v222
	v_fmaak_f32 v234, v220, v234, 0x3fcc422a
	v_exp_f32_e32 v222, v222
	v_mul_f32_e32 v234, v220, v234
	v_mul_f32_e32 v234, 0xbfb8aa3b, v234
	v_exp_f32_e32 v236, v234
	v_add_f32_e32 v222, 1.0, v222
	v_rcp_f32_e32 v234, v222
	v_add_f32_e32 v222, 1.0, v235
	v_rcp_f32_e32 v235, v222
	v_add_f32_e32 v222, 1.0, v236
	v_mul_f32_e32 v237, 0x3d922279, v214
	v_mul_f32_e32 v217, 0x3d922279, v209
	v_rcp_f32_e32 v236, v222
	v_mul_f32_e32 v222, 0x3d922279, v221
	v_fmaak_f32 v237, v214, v237, 0x3fcc422a
	v_mul_f32_e32 v238, 0x3d922279, v215
	v_fmaak_f32 v217, v209, v217, 0x3fcc422a
	v_fmaak_f32 v222, v221, v222, 0x3fcc422a
	v_mul_f32_e32 v237, v214, v237
	v_fmaak_f32 v238, v215, v238, 0x3fcc422a
	v_mul_f32_e32 v217, v209, v217
	v_mul_f32_e32 v222, v221, v222
	v_mul_f32_e32 v237, 0xbfb8aa3b, v237
	v_mul_f32_e32 v238, v215, v238
	v_mul_f32_e32 v217, 0xbfb8aa3b, v217
	v_mul_f32_e32 v222, 0xbfb8aa3b, v222
	v_exp_f32_e32 v237, v237
	v_mul_f32_e32 v238, 0xbfb8aa3b, v238
	v_exp_f32_e32 v217, v217
	v_exp_f32_e32 v222, v222
	v_exp_f32_e32 v239, v238
	v_add_f32_e32 v237, 1.0, v237
	v_add_f32_e32 v216, 1.0, v216
	v_add_f32_e32 v217, 1.0, v217
	v_add_f32_e32 v222, 1.0, v222
	v_rcp_f32_e32 v238, v237
	v_add_f32_e32 v237, 1.0, v239
	v_rcp_f32_e32 v216, v216
	v_rcp_f32_e32 v217, v217
	v_rcp_f32_e32 v239, v237
	v_rcp_f32_e32 v237, v222
	v_pk_mul_f32 v[240:241], v[208:209], v[216:217]
	v_pk_mul_f32 v[216:217], v[212:213], v[234:235]
	v_pk_mul_f32 v[208:209], v[214:215], v[238:239]
	v_pk_mul_f32 v[212:213], v[220:221], v[236:237]
	v_add_co_u32_e32 v214, vcc, s70, v138
; DI float gelu_tanh(float x) { const float t = x * (1.5957691216f + 0.0713548163f * x * x); return x * __builtin_amdgcn_rcpf(1.f + __builtin_amdgcn_exp2f(-1.4426950409f * t)); }
; #define ROWS8 _Pragma("unroll") for (int ai = 0; ai < 2; ++ai) _Pragma("unroll") for (int m = 0; m < 4; ++m) if (ai == 0 || !hf)
; #define PK8(v0, v1) ({ const u32x2 h0_ = pk4(v0), h1_ = pk4(v1); (u32x4){h0_.x, h0_.y, h1_.x, h1_.y}; })
;     DI void operator()(const Acc& acc, const Unit& u, int wr, int wc, int fr, int fq) const {
;     ...
;                     ROWS8 { const int r = row0 + ai * HALF + m * 16; f32x4 v0 = acc[ai][bj][m][0] * rsc[bj][0], v1 = acc[ai][bj][m][1] * rsc[bj][1];
;                         v0[0] = gelu_tanh(v0[0]); v0[1] = gelu_tanh(v0[1]); v0[2] = gelu_tanh(v0[2]); v0[3] = gelu_tanh(v0[3]);
;                         v1[0] = gelu_tanh(v1[0]); v1[1] = gelu_tanh(v1[1]); v1[2] = gelu_tanh(v1[2]); v1[3] = gelu_tanh(v1[3]);
;                         sq0 += v0 * v0; sq1 += v1 * v1; *(u32x4*)(WSB(OFF_VT) + (size_t)r * 8192 + cc) = PK8(v0, v1); }
; #pragma unroll
;                     for (int j = 0; j < 8; ++j) { float t = j < 4 ? sq0[j & 3] : sq1[j & 3];
;                         t += __shfl_xor(t, 1); t += __shfl_xor(t, 2); t += __shfl_xor(t, 4); t += __shfl_xor(t, 8);
;                         if (fr == 0) unsafeAtomicAdd(ssqv + cc + j, t); }
	v_pk_fma_f32 v[234:235], v[240:241], v[240:241], v[218:219]
	v_cvt_pk_bf16_f32 v218, v240, v241
	v_cvt_pk_bf16_f32 v219, v216, v217
	v_cvt_pk_bf16_f32 v220, v212, v213
	v_cvt_pk_bf16_f32 v221, v208, v209
	v_addc_co_u32_e32 v215, vcc, 0, v139, vcc
	global_store_dwordx4 v[214:215], v[218:221], off
	v_pk_mul_f32 v[214:215], v[28:29], v[190:191]
	v_pk_mul_f32 v[238:239], v[24:25], v[182:183]
	v_mul_f32_e32 v218, 0x3d922279, v214
	v_fmaak_f32 v218, v214, v218, 0x3fcc422a
	v_mul_f32_e32 v218, v214, v218
	v_mul_f32_e32 v218, 0xbfb8aa3b, v218
	v_exp_f32_e32 v220, v218
	v_pk_mul_f32 v[218:219], v[30:31], v[186:187]
	v_mul_f32_e32 v221, 0x3d922279, v215
	v_fmaak_f32 v221, v215, v221, 0x3fcc422a
	v_mul_f32_e32 v222, 0x3d922279, v218
	v_mul_f32_e32 v221, v215, v221
	v_fmaak_f32 v222, v218, v222, 0x3fcc422a
	v_mul_f32_e32 v221, 0xbfb8aa3b, v221
	v_mul_f32_e32 v222, v218, v222
	v_exp_f32_e32 v221, v221
	v_mul_f32_e32 v222, 0xbfb8aa3b, v222
	v_exp_f32_e32 v222, v222
	v_add_f32_e32 v220, 1.0, v220
	v_rcp_f32_e32 v240, v220
	v_add_f32_e32 v220, 1.0, v221
	v_rcp_f32_e32 v241, v220
	v_add_f32_e32 v220, 1.0, v222
	v_mul_f32_e32 v222, 0x3d922279, v238
	v_fmaak_f32 v222, v238, v222, 0x3fcc422a
	v_mul_f32_e32 v222, v238, v222
	v_mul_f32_e32 v222, 0xbfb8aa3b, v222
	v_exp_f32_e32 v222, v222
	v_pk_mul_f32 v[236:237], v[26:27], v[184:185]
	v_mul_f32_e32 v221, 0x3d922279, v219
	v_mul_f32_e32 v243, 0x3d922279, v236
	v_add_f32_e32 v222, 1.0, v222
	v_rcp_f32_e32 v242, v222
	v_mul_f32_e32 v222, 0x3d922279, v239
	v_fmaak_f32 v243, v236, v243, 0x3fcc422a
	v_mul_f32_e32 v244, 0x3d922279, v237
	v_fmaak_f32 v221, v219, v221, 0x3fcc422a
	v_fmaak_f32 v222, v239, v222, 0x3fcc422a
	v_mul_f32_e32 v243, v236, v243
	v_fmaak_f32 v244, v237, v244, 0x3fcc422a
	v_mul_f32_e32 v221, v219, v221
	v_mul_f32_e32 v222, v239, v222
	v_mul_f32_e32 v243, 0xbfb8aa3b, v243
	v_mul_f32_e32 v244, v237, v244
	v_mul_f32_e32 v221, 0xbfb8aa3b, v221
	v_mul_f32_e32 v222, 0xbfb8aa3b, v222
	v_exp_f32_e32 v243, v243
	v_mul_f32_e32 v244, 0xbfb8aa3b, v244
	v_exp_f32_e32 v221, v221
	v_exp_f32_e32 v222, v222
	v_exp_f32_e32 v245, v244
	v_add_f32_e32 v243, 1.0, v243
	v_add_f32_e32 v221, 1.0, v221
	v_add_f32_e32 v222, 1.0, v222
	v_rcp_f32_e32 v244, v243
	v_add_f32_e32 v243, 1.0, v245
	v_rcp_f32_e32 v220, v220
	v_rcp_f32_e32 v221, v221
	v_rcp_f32_e32 v245, v243
	v_rcp_f32_e32 v243, v222
	v_pk_mul_f32 v[240:241], v[214:215], v[240:241]
	v_pk_mul_f32 v[220:221], v[218:219], v[220:221]
	v_pk_mul_f32 v[214:215], v[236:237], v[244:245]
	v_pk_mul_f32 v[218:219], v[238:239], v[242:243]
	v_pk_fma_f32 v[238:239], v[240:241], v[240:241], v[234:235]
	v_cvt_pk_bf16_f32 v234, v240, v241
	v_add_co_u32_e32 v240, vcc, s71, v138
	v_pk_mul_f32 v[190:191], v[12:13], v[190:191]
	v_cvt_pk_bf16_f32 v235, v220, v221
	v_cvt_pk_bf16_f32 v236, v218, v219
	v_cvt_pk_bf16_f32 v237, v214, v215
	v_addc_co_u32_e32 v241, vcc, 0, v139, vcc
	v_mul_f32_e32 v222, 0x3d922279, v190
	global_store_dwordx4 v[240:241], v[234:237], off
	v_fmaak_f32 v222, v190, v222, 0x3fcc422a
	v_mul_f32_e32 v222, v190, v222
	v_mul_f32_e32 v234, 0x3d922279, v191
	v_fmaak_f32 v234, v191, v234, 0x3fcc422a
	v_mul_f32_e32 v222, 0xbfb8aa3b, v222
	v_mul_f32_e32 v234, v191, v234
	v_exp_f32_e32 v222, v222
	v_mul_f32_e32 v234, 0xbfb8aa3b, v234
	v_exp_f32_e32 v235, v234
	v_pk_mul_f32 v[186:187], v[14:15], v[186:187]
	v_add_f32_e32 v222, 1.0, v222
	v_rcp_f32_e32 v234, v222
	v_add_f32_e32 v222, 1.0, v235
	v_mul_f32_e32 v235, 0x3d922279, v186
	v_fmaak_f32 v235, v186, v235, 0x3fcc422a
	v_mul_f32_e32 v235, v186, v235
	v_mul_f32_e32 v235, 0xbfb8aa3b, v235
	v_exp_f32_e32 v236, v235
	v_mul_f32_e32 v235, 0x3d922279, v187
	v_fmaak_f32 v235, v187, v235, 0x3fcc422a
	v_mul_f32_e32 v235, v187, v235
	v_mul_f32_e32 v235, 0xbfb8aa3b, v235
	v_exp_f32_e32 v237, v235
	v_rcp_f32_e32 v235, v222
	v_pk_mul_f32 v[240:241], v[8:9], v[182:183]
	v_pk_mul_f32 v[184:185], v[10:11], v[184:185]
	v_mul_f32_e32 v182, 0x3d922279, v240
	v_pk_mul_f32 v[234:235], v[190:191], v[234:235]
	v_fmaak_f32 v182, v240, v182, 0x3fcc422a
	v_mul_f32_e32 v190, 0x3d922279, v184
	v_mul_f32_e32 v182, v240, v182
	v_fmaak_f32 v190, v184, v190, 0x3fcc422a
	v_add_f32_e32 v222, 1.0, v236
	v_mul_f32_e32 v182, 0xbfb8aa3b, v182
	v_mul_f32_e32 v190, v184, v190
	v_rcp_f32_e32 v236, v222
	v_add_f32_e32 v222, 1.0, v237
	v_exp_f32_e32 v182, v182
	v_mul_f32_e32 v190, 0xbfb8aa3b, v190
	v_rcp_f32_e32 v237, v222
	v_exp_f32_e32 v190, v190
	v_mul_f32_e32 v183, 0x3d922279, v241
	v_fmaak_f32 v183, v241, v183, 0x3fcc422a
	v_add_f32_e32 v182, 1.0, v182
	v_pk_mul_f32 v[186:187], v[186:187], v[236:237]
	v_mul_f32_e32 v183, v241, v183
	v_rcp_f32_e32 v236, v182
	v_add_f32_e32 v182, 1.0, v190
	v_pk_fma_f32 v[190:191], v[234:235], v[234:235], v[238:239]
	v_mul_f32_e32 v183, 0xbfb8aa3b, v183
	ds_bpermute_b32 v238, v226, v190
	v_exp_f32_e32 v183, v183
	v_rcp_f32_e32 v182, v182
	v_add_f32_e32 v222, 1.0, v183
	v_mul_f32_e32 v183, 0x3d922279, v185
	s_waitcnt lgkmcnt(0)
	v_add_f32_e32 v190, v190, v238
	v_fmaak_f32 v183, v185, v183, 0x3fcc422a
	v_rcp_f32_e32 v237, v222
	ds_bpermute_b32 v222, v227, v190
	v_mul_f32_e32 v183, v185, v183
	v_mul_f32_e32 v183, 0xbfb8aa3b, v183
	v_exp_f32_e32 v183, v183
	s_waitcnt lgkmcnt(0)
	v_add_f32_e32 v190, v190, v222
	ds_bpermute_b32 v222, v228, v190
	v_add_f32_e32 v183, 1.0, v183
	v_rcp_f32_e32 v183, v183
	s_waitcnt lgkmcnt(0)
	v_add_f32_e32 v190, v190, v222
	v_pk_mul_f32 v[182:183], v[184:185], v[182:183]
	v_pk_mul_f32 v[184:185], v[240:241], v[236:237]
	v_cvt_pk_bf16_f32 v236, v234, v235
	ds_bpermute_b32 v234, v229, v190
	v_add_co_u32_e32 v240, vcc, 0x2c0000, v138
	v_cvt_pk_bf16_f32 v237, v186, v187
	v_cvt_pk_bf16_f32 v238, v184, v185
	v_cvt_pk_bf16_f32 v239, v182, v183
	v_addc_co_u32_e32 v241, vcc, 0, v139, vcc
	global_store_dwordx4 v[240:241], v[236:239], off
	s_and_saveexec_b64 s[4:5], s[2:3]
	s_cbranch_execz .LBB0_331
	s_waitcnt lgkmcnt(0)
	v_add_f32_e32 v190, v190, v234
	global_atomic_add_f32 v[136:137], v190, off

; #define PG8_STAGE(bufoff, gbase, voff) do { _Pragma("unroll") for (int _i = 0; _i < 2; ++_i) \
;         __builtin_amdgcn_global_load_lds((const unsigned*)((const char*)(gbase) + (voff)[_i]), (LAS unsigned*)(lds + (bufoff) + ldsw + _i * 8192), 16, 0, 0); } while (0)
; #define PG8_LDA(dst, b, h) do { _Pragma("unroll") for (int m = 0; m < 4; ++m) _Pragma("unroll") for (int k = 0; k < 2; ++k) dst[m][k] = *(const LAS bf16x8*)(lds + PG8_SA(b, h) + aoff + m * 2048 + k * 1024); } while (0)
; #define PG8_LDB(dst, b, h) do { _Pragma("unroll") for (int n = 0; n < 2; ++n) _Pragma("unroll") for (int k = 0; k < 2; ++k) dst[n][k] = *(const LAS bf16x8*)(lds + PG8_SB(b, h) + boff + n * 2048 + k * 1024); } while (0)
; #define PG8_MMA(ai, bj, At, Bt) do { __builtin_amdgcn_s_setprio(1); _Pragma("unroll") for (int m = 0; m < 4; ++m) _Pragma("unroll") for (int n = 0; n < 2; ++n) _Pragma("unroll") for (int k = 0; k < 2; ++k) \
;         acc[ai][bj][m][n] = __builtin_amdgcn_mfma_f32_16x16x32_bf16(Bt[n][k], At[m][k], acc[ai][bj][m][n], 0, 0, 0); __builtin_amdgcn_s_setprio(0); } while (0)
; #define PG8_WAIT_L(n) asm volatile("s_waitcnt lgkmcnt(" #n ")" ::: "memory")
; #define PG8_BAR __builtin_amdgcn_s_barrier()
; #define PG8_SCHED __builtin_amdgcn_sched_barrier(0)
; template <class Epi>
; DI void gemm_phase(LAS unsigned char* lds, int wid, int K, int lda, int ldb, bool bperm, const Sched3& S, const Epi& E) {
;     ...
;             PG8_LDB(B0, 0, 0); PG8_SCHED; PG8_LDA(At, 0, 0); PG8_STAGE(PG8_SA(1, 1), a1 + hA, voffA);
;             PG8_WAIT_L(8); PG8_BAR; PG8_WAIT_L(0); PG8_MMA(0, 0, At, B0); PG8_BAR; PG8_SCHED;
;             PG8_LDB(B1, 0, 1); PG8_STAGE(PG8_SB(0, 0), b2, voffB);
;             PG8_BAR; PG8_WAIT_L(0); PG8_MMA(0, 1, At, B1); PG8_BAR;
;             PG8_LDA(At, 0, 1); PG8_STAGE(PG8_SA(0, 0), a2, voffA);
;             PG8_BAR; PG8_WAIT_L(0); if (full) PG8_MMA(1, 0, At, B0); PG8_BAR; PG8_SCHED;
.LBB0_620:
	s_add_u32 s38, s38, 0x80080
	s_addc_u32 s39, s39, 0
	s_add_u32 s21, s40, 0x100
	s_nop 0
	s_addc_u32 s23, s41, 0
	s_mov_b32 s29, -2
	s_waitcnt lgkmcnt(0)
	ds_read_b128 v[128:131], v203
	ds_read_b128 v[132:135], v203 offset:1024
	ds_read_b128 v[136:139], v203 offset:2048
	ds_read_b128 v[140:143], v203 offset:3072
	s_add_u32 s40, s38, 0xfff80080
	s_addc_u32 s41, s39, -1
	s_cmp_eq_u32 s29, 28
	s_cselect_b32 s43, s31, s41
	s_cselect_b32 s42, s30, s40
	s_cselect_b32 s41, s37, s23
	s_cselect_b32 s40, s36, s21
	v_lshl_add_u64 v[186:187], s[38:39], 0, v[180:181]
	s_add_i32 m0, s50, 0xc000
	ds_read_b128 v[144:147], v204
	ds_read_b128 v[148:151], v204 offset:1024
	ds_read_b128 v[152:155], v204 offset:2048
	ds_read_b128 v[156:159], v204 offset:3072
	ds_read_b128 v[160:163], v204 offset:4096
	ds_read_b128 v[164:167], v204 offset:5120
	ds_read_b128 v[168:171], v204 offset:6144
	ds_read_b128 v[172:175], v204 offset:7168
	global_load_lds_dwordx4 v[186:187], off
	v_lshl_add_u64 v[186:187], s[38:39], 0, v[182:183]
	s_add_i32 m0, s50, 0xe000
	s_nop 0
	global_load_lds_dwordx4 v[186:187], off
	s_waitcnt lgkmcnt(8)
	s_barrier
	s_waitcnt lgkmcnt(0)
	s_setprio 1
	s_waitcnt lgkmcnt(0)
	v_mfma_f32_16x16x32_bf16 v[124:127], v[128:131], v[144:147], 0
	v_mfma_f32_16x16x32_bf16 v[120:123], v[136:139], v[144:147], 0
	v_mfma_f32_16x16x32_bf16 v[108:111], v[128:131], v[152:155], 0
	v_mfma_f32_16x16x32_bf16 v[104:107], v[136:139], v[152:155], 0
	v_mfma_f32_16x16x32_bf16 v[92:95], v[128:131], v[160:163], 0
	v_mfma_f32_16x16x32_bf16 v[88:91], v[136:139], v[160:163], 0
	v_mfma_f32_16x16x32_bf16 v[76:79], v[128:131], v[168:171], 0
	v_mfma_f32_16x16x32_bf16 v[72:75], v[136:139], v[168:171], 0
	v_mfma_f32_16x16x32_bf16 v[124:127], v[132:135], v[148:151], v[124:127]
	v_mfma_f32_16x16x32_bf16 v[120:123], v[140:143], v[148:151], v[120:123]
	v_mfma_f32_16x16x32_bf16 v[108:111], v[132:135], v[156:159], v[108:111]
	v_mfma_f32_16x16x32_bf16 v[104:107], v[140:143], v[156:159], v[104:107]
	v_mfma_f32_16x16x32_bf16 v[92:95], v[132:135], v[164:167], v[92:95]
	v_mfma_f32_16x16x32_bf16 v[88:91], v[140:143], v[164:167], v[88:91]
	v_mfma_f32_16x16x32_bf16 v[76:79], v[132:135], v[172:175], v[76:79]
	v_mfma_f32_16x16x32_bf16 v[72:75], v[140:143], v[172:175], v[72:75]
	s_setprio 0
	s_barrier
	s_add_i32 s63, s59, s49
	v_lshl_add_u64 v[210:211], s[40:41], 0, v[176:177]
	s_mov_b32 m0, s63
	ds_read_b128 v[186:189], v205
	ds_read_b128 v[190:193], v205 offset:1024
	ds_read_b128 v[194:197], v205 offset:2048
	ds_read_b128 v[206:209], v205 offset:3072
	global_load_lds_dwordx4 v[210:211], off
	v_lshl_add_u64 v[212:213], s[40:41], 0, v[178:179]
	s_add_i32 m0, s63, 0x2000
	s_nop 0
	global_load_lds_dwordx4 v[212:213], off
	s_barrier
	s_waitcnt lgkmcnt(0)
	s_setprio 1
	s_waitcnt lgkmcnt(0)
	v_mfma_f32_16x16x32_bf16 v[116:119], v[186:189], v[144:147], 0
	v_mfma_f32_16x16x32_bf16 v[112:115], v[194:197], v[144:147], 0
	v_mfma_f32_16x16x32_bf16 v[100:103], v[186:189], v[152:155], 0
	v_mfma_f32_16x16x32_bf16 v[96:99], v[194:197], v[152:155], 0
	v_mfma_f32_16x16x32_bf16 v[84:87], v[186:189], v[160:163], 0
	v_mfma_f32_16x16x32_bf16 v[80:83], v[194:197], v[160:163], 0
	v_mfma_f32_16x16x32_bf16 v[68:71], v[186:189], v[168:171], 0
	v_mfma_f32_16x16x32_bf16 v[64:67], v[194:197], v[168:171], 0
	v_mfma_f32_16x16x32_bf16 v[116:119], v[190:193], v[148:151], v[116:119]
	v_mfma_f32_16x16x32_bf16 v[112:115], v[206:209], v[148:151], v[112:115]
	v_mfma_f32_16x16x32_bf16 v[100:103], v[190:193], v[156:159], v[100:103]
	v_mfma_f32_16x16x32_bf16 v[96:99], v[206:209], v[156:159], v[96:99]
	v_mfma_f32_16x16x32_bf16 v[84:87], v[190:193], v[164:167], v[84:87]
	v_mfma_f32_16x16x32_bf16 v[80:83], v[206:209], v[164:167], v[80:83]
	v_mfma_f32_16x16x32_bf16 v[68:71], v[190:193], v[172:175], v[68:71]
	v_mfma_f32_16x16x32_bf16 v[64:67], v[206:209], v[172:175], v[64:67]
	s_setprio 0
	s_mov_b32 m0, s50
	v_lshl_add_u64 v[214:215], s[42:43], 0, v[176:177]
	s_barrier
	ds_read_b128 v[144:147], v204 offset:16384
	ds_read_b128 v[148:151], v204 offset:17408
	ds_read_b128 v[152:155], v204 offset:18432
	ds_read_b128 v[156:159], v204 offset:19456
	ds_read_b128 v[160:163], v204 offset:20480
	ds_read_b128 v[164:167], v204 offset:21504
	ds_read_b128 v[168:171], v204 offset:22528
	ds_read_b128 v[172:175], v204 offset:23552
	global_load_lds_dwordx4 v[214:215], off
	v_lshl_add_u64 v[216:217], s[42:43], 0, v[178:179]
	s_mov_b32 m0, s51
	s_nop 0
	global_load_lds_dwordx4 v[216:217], off
	s_barrier
	s_waitcnt lgkmcnt(0)
	s_setprio 1
	s_waitcnt lgkmcnt(0)
	v_mfma_f32_16x16x32_bf16 v[60:63], v[128:131], v[144:147], 0
	v_mfma_f32_16x16x32_bf16 v[56:59], v[136:139], v[144:147], 0
	v_mfma_f32_16x16x32_bf16 v[44:47], v[128:131], v[152:155], 0
	v_mfma_f32_16x16x32_bf16 v[40:43], v[136:139], v[152:155], 0
	v_mfma_f32_16x16x32_bf16 v[28:31], v[128:131], v[160:163], 0
	v_mfma_f32_16x16x32_bf16 v[24:27], v[136:139], v[160:163], 0
	v_mfma_f32_16x16x32_bf16 v[12:15], v[128:131], v[168:171], 0
	v_mfma_f32_16x16x32_bf16 v[8:11], v[136:139], v[168:171], 0
	v_mfma_f32_16x16x32_bf16 v[60:63], v[132:135], v[148:151], v[60:63]
	v_mfma_f32_16x16x32_bf16 v[56:59], v[140:143], v[148:151], v[56:59]
	v_mfma_f32_16x16x32_bf16 v[44:47], v[132:135], v[156:159], v[44:47]
	v_mfma_f32_16x16x32_bf16 v[40:43], v[140:143], v[156:159], v[40:43]
	v_mfma_f32_16x16x32_bf16 v[28:31], v[132:135], v[164:167], v[28:31]
	v_mfma_f32_16x16x32_bf16 v[24:27], v[140:143], v[164:167], v[24:27]
	v_mfma_f32_16x16x32_bf16 v[12:15], v[132:135], v[172:175], v[12:15]
	v_mfma_f32_16x16x32_bf16 v[8:11], v[140:143], v[172:175], v[8:11]
	s_setprio 0
	s_barrier
; #define PG8_STAGE(bufoff, gbase, voff) do { _Pragma("unroll") for (int _i = 0; _i < 2; ++_i) \
;         __builtin_amdgcn_global_load_lds((const unsigned*)((const char*)(gbase) + (voff)[_i]), (LAS unsigned*)(lds + (bufoff) + ldsw + _i * 8192), 16, 0, 0); } while (0)
; #define PG8_LDA(dst, b, h) do { _Pragma("unroll") for (int m = 0; m < 4; ++m) _Pragma("unroll") for (int k = 0; k < 2; ++k) dst[m][k] = *(const LAS bf16x8*)(lds + PG8_SA(b, h) + aoff + m * 2048 + k * 1024); } while (0)
; #define PG8_LDB(dst, b, h) do { _Pragma("unroll") for (int n = 0; n < 2; ++n) _Pragma("unroll") for (int k = 0; k < 2; ++k) dst[n][k] = *(const LAS bf16x8*)(lds + PG8_SB(b, h) + boff + n * 2048 + k * 1024); } while (0)
; #define PG8_MMA(ai, bj, At, Bt) do { __builtin_amdgcn_s_setprio(1); _Pragma("unroll") for (int m = 0; m < 4; ++m) _Pragma("unroll") for (int n = 0; n < 2; ++n) _Pragma("unroll") for (int k = 0; k < 2; ++k) \
;         acc[ai][bj][m][n] = __builtin_amdgcn_mfma_f32_16x16x32_bf16(Bt[n][k], At[m][k], acc[ai][bj][m][n], 0, 0, 0); __builtin_amdgcn_s_setprio(0); } while (0)
; #define PG8_WAIT_V(n) asm volatile("s_waitcnt vmcnt(" #n ")" ::: "memory")
; #define PG8_WAIT_L(n) asm volatile("s_waitcnt lgkmcnt(" #n ")" ::: "memory")
; #define PG8_BAR __builtin_amdgcn_s_barrier()
; #define PG8_SCHED __builtin_amdgcn_sched_barrier(0)
; template <class Epi>
; DI void gemm_phase(LAS unsigned char* lds, int wid, int K, int lda, int ldb, bool bperm, const Sched3& S, const Epi& E) {
;     ...
;             PG8_STAGE(PG8_SB(0, 1), b2 + hstepB, voffB);
;             PG8_WAIT_V(6); PG8_BAR; if (full) PG8_MMA(1, 1, At, B1); PG8_BAR;
;             PG8_LDB(B0, 1, 0); PG8_SCHED; PG8_LDA(At, 1, 0); PG8_STAGE(PG8_SA(0, 1), a2 + h2, voffA);
;             PG8_WAIT_L(8); PG8_BAR; PG8_WAIT_L(0); PG8_MMA(0, 0, At, B0); PG8_BAR; PG8_SCHED;
;             PG8_LDB(B1, 1, 1); PG8_STAGE(PG8_SB(1, 0), b3, voffB);
;             PG8_BAR; PG8_WAIT_L(0); PG8_MMA(0, 1, At, B1); PG8_BAR;
	s_add_u32 s64, s40, 0x80000
	s_addc_u32 s65, s41, 0
	s_add_i32 s63, s60, s49
	v_lshl_add_u64 v[128:129], s[64:65], 0, v[176:177]
	s_mov_b32 m0, s63
	s_nop 0
	global_load_lds_dwordx4 v[128:129], off
	v_lshl_add_u64 v[128:129], s[64:65], 0, v[178:179]
	s_add_i32 m0, s63, 0x2000
	s_nop 0
	global_load_lds_dwordx4 v[128:129], off
	s_waitcnt vmcnt(6)
	s_barrier
	s_setprio 1
	v_mfma_f32_16x16x32_bf16 v[52:55], v[186:189], v[144:147], 0
	v_mfma_f32_16x16x32_bf16 v[48:51], v[194:197], v[144:147], 0
	v_mfma_f32_16x16x32_bf16 v[36:39], v[186:189], v[152:155], 0
	v_mfma_f32_16x16x32_bf16 v[32:35], v[194:197], v[152:155], 0
	v_mfma_f32_16x16x32_bf16 v[20:23], v[186:189], v[160:163], 0
	v_mfma_f32_16x16x32_bf16 v[16:19], v[194:197], v[160:163], 0
	v_mfma_f32_16x16x32_bf16 v[4:7], v[186:189], v[168:171], 0
	v_mfma_f32_16x16x32_bf16 v[0:3], v[194:197], v[168:171], 0
	v_mfma_f32_16x16x32_bf16 v[52:55], v[190:193], v[148:151], v[52:55]
	v_mfma_f32_16x16x32_bf16 v[48:51], v[206:209], v[148:151], v[48:51]
	v_mfma_f32_16x16x32_bf16 v[36:39], v[190:193], v[156:159], v[36:39]
	v_mfma_f32_16x16x32_bf16 v[32:35], v[206:209], v[156:159], v[32:35]
	v_mfma_f32_16x16x32_bf16 v[20:23], v[190:193], v[164:167], v[20:23]
	v_mfma_f32_16x16x32_bf16 v[16:19], v[206:209], v[164:167], v[16:19]
	v_mfma_f32_16x16x32_bf16 v[4:7], v[190:193], v[172:175], v[4:7]
	v_mfma_f32_16x16x32_bf16 v[0:3], v[206:209], v[172:175], v[0:3]
	s_setprio 0
	s_add_i32 s63, 0, 0x18000
	v_add_u32_e32 v140, s63, v199
	s_barrier
	ds_read_b128 v[128:131], v140
	ds_read_b128 v[132:135], v140 offset:1024
	ds_read_b128 v[136:139], v140 offset:2048
	ds_read_b128 v[140:143], v140 offset:3072
	s_add_u32 s42, s42, 0x80000
	s_addc_u32 s43, s43, 0
	s_mov_b32 m0, s52
	v_lshl_add_u64 v[186:187], s[42:43], 0, v[176:177]
	ds_read_b128 v[144:147], v204 offset:32768
	ds_read_b128 v[148:151], v204 offset:33792
	ds_read_b128 v[152:155], v204 offset:34816
	ds_read_b128 v[156:159], v204 offset:35840
	ds_read_b128 v[160:163], v204 offset:36864
	ds_read_b128 v[164:167], v204 offset:37888
	ds_read_b128 v[168:171], v204 offset:38912
	ds_read_b128 v[172:175], v204 offset:39936
	global_load_lds_dwordx4 v[186:187], off
	v_lshl_add_u64 v[186:187], s[42:43], 0, v[178:179]
	s_mov_b32 m0, s53
	s_nop 0
	global_load_lds_dwordx4 v[186:187], off
	s_waitcnt lgkmcnt(8)
	s_barrier
	s_waitcnt lgkmcnt(0)
	s_setprio 1
	s_waitcnt lgkmcnt(0)
	v_mfma_f32_16x16x32_bf16 v[124:127], v[128:131], v[144:147], v[124:127]
	v_mfma_f32_16x16x32_bf16 v[120:123], v[136:139], v[144:147], v[120:123]
	v_mfma_f32_16x16x32_bf16 v[108:111], v[128:131], v[152:155], v[108:111]
	v_mfma_f32_16x16x32_bf16 v[104:107], v[136:139], v[152:155], v[104:107]
	v_mfma_f32_16x16x32_bf16 v[92:95], v[128:131], v[160:163], v[92:95]
	v_mfma_f32_16x16x32_bf16 v[88:91], v[136:139], v[160:163], v[88:91]
	v_mfma_f32_16x16x32_bf16 v[76:79], v[128:131], v[168:171], v[76:79]
	v_mfma_f32_16x16x32_bf16 v[72:75], v[136:139], v[168:171], v[72:75]
	v_mfma_f32_16x16x32_bf16 v[124:127], v[132:135], v[148:151], v[124:127]
	v_mfma_f32_16x16x32_bf16 v[120:123], v[140:143], v[148:151], v[120:123]
	v_mfma_f32_16x16x32_bf16 v[108:111], v[132:135], v[156:159], v[108:111]
	v_mfma_f32_16x16x32_bf16 v[104:107], v[140:143], v[156:159], v[104:107]
	v_mfma_f32_16x16x32_bf16 v[92:95], v[132:135], v[164:167], v[92:95]
	v_mfma_f32_16x16x32_bf16 v[88:91], v[140:143], v[164:167], v[88:91]
	v_mfma_f32_16x16x32_bf16 v[76:79], v[132:135], v[172:175], v[76:79]
	v_mfma_f32_16x16x32_bf16 v[72:75], v[140:143], v[172:175], v[72:75]
	s_setprio 0
	s_barrier
	s_add_i32 s42, 0, 0x1c000
	s_add_i32 s43, s63, s49
	v_add_u32_e32 v206, s42, v199
	v_lshl_add_u64 v[210:211], v[210:211], 0, s[12:13]
	s_mov_b32 m0, s43
	ds_read_b128 v[186:189], v206
	ds_read_b128 v[190:193], v206 offset:1024
	ds_read_b128 v[194:197], v206 offset:2048
	ds_read_b128 v[206:209], v206 offset:3072
	global_load_lds_dwordx4 v[210:211], off
	v_lshl_add_u64 v[210:211], v[212:213], 0, s[12:13]
	s_add_i32 m0, s43, 0x2000
	s_nop 0
	global_load_lds_dwordx4 v[210:211], off
	s_barrier
; #define PG8_STAGE(bufoff, gbase, voff) do { _Pragma("unroll") for (int _i = 0; _i < 2; ++_i) \
;         __builtin_amdgcn_global_load_lds((const unsigned*)((const char*)(gbase) + (voff)[_i]), (LAS unsigned*)(lds + (bufoff) + ldsw + _i * 8192), 16, 0, 0); } while (0)
; #define PG8_LDA(dst, b, h) do { _Pragma("unroll") for (int m = 0; m < 4; ++m) _Pragma("unroll") for (int k = 0; k < 2; ++k) dst[m][k] = *(const LAS bf16x8*)(lds + PG8_SA(b, h) + aoff + m * 2048 + k * 1024); } while (0)
; #define PG8_MMA(ai, bj, At, Bt) do { __builtin_amdgcn_s_setprio(1); _Pragma("unroll") for (int m = 0; m < 4; ++m) _Pragma("unroll") for (int n = 0; n < 2; ++n) _Pragma("unroll") for (int k = 0; k < 2; ++k) \
;         acc[ai][bj][m][n] = __builtin_amdgcn_mfma_f32_16x16x32_bf16(Bt[n][k], At[m][k], acc[ai][bj][m][n], 0, 0, 0); __builtin_amdgcn_s_setprio(0); } while (0)
; #define PG8_WAIT_V(n) asm volatile("s_waitcnt vmcnt(" #n ")" ::: "memory")
; #define PG8_WAIT_L(n) asm volatile("s_waitcnt lgkmcnt(" #n ")" ::: "memory")
; #define PG8_BAR __builtin_amdgcn_s_barrier()
; #define PG8_SCHED __builtin_amdgcn_sched_barrier(0)
; template <class Epi>
; DI void gemm_phase(LAS unsigned char* lds, int wid, int K, int lda, int ldb, bool bperm, const Sched3& S, const Epi& E) {
;     ...
;             PG8_BAR; PG8_WAIT_L(0); PG8_MMA(0, 1, At, B1); PG8_BAR;
;             PG8_LDA(At, 1, 1); PG8_STAGE(PG8_SA(1, 0), a3, voffA);
;             PG8_BAR; PG8_WAIT_L(0); if (full) PG8_MMA(1, 0, At, B0); PG8_BAR; PG8_SCHED;
;             PG8_STAGE(PG8_SB(1, 1), b3 + hstepB, voffB);
;             PG8_WAIT_V(6); PG8_BAR; if (full) PG8_MMA(1, 1, At, B1); PG8_BAR;
;         }
	s_waitcnt lgkmcnt(0)
	s_setprio 1
	s_waitcnt lgkmcnt(0)
	v_mfma_f32_16x16x32_bf16 v[116:119], v[186:189], v[144:147], v[116:119]
	v_mfma_f32_16x16x32_bf16 v[112:115], v[194:197], v[144:147], v[112:115]
	v_mfma_f32_16x16x32_bf16 v[100:103], v[186:189], v[152:155], v[100:103]
	v_mfma_f32_16x16x32_bf16 v[96:99], v[194:197], v[152:155], v[96:99]
	v_mfma_f32_16x16x32_bf16 v[84:87], v[186:189], v[160:163], v[84:87]
	v_mfma_f32_16x16x32_bf16 v[80:83], v[194:197], v[160:163], v[80:83]
	v_mfma_f32_16x16x32_bf16 v[68:71], v[186:189], v[168:171], v[68:71]
	v_mfma_f32_16x16x32_bf16 v[64:67], v[194:197], v[168:171], v[64:67]
	v_mfma_f32_16x16x32_bf16 v[116:119], v[190:193], v[148:151], v[116:119]
	v_mfma_f32_16x16x32_bf16 v[112:115], v[206:209], v[148:151], v[112:115]
	v_mfma_f32_16x16x32_bf16 v[100:103], v[190:193], v[156:159], v[100:103]
	v_mfma_f32_16x16x32_bf16 v[96:99], v[206:209], v[156:159], v[96:99]
	v_mfma_f32_16x16x32_bf16 v[84:87], v[190:193], v[164:167], v[84:87]
	v_mfma_f32_16x16x32_bf16 v[80:83], v[206:209], v[164:167], v[80:83]
	v_mfma_f32_16x16x32_bf16 v[68:71], v[190:193], v[172:175], v[68:71]
	v_mfma_f32_16x16x32_bf16 v[64:67], v[206:209], v[172:175], v[64:67]
	s_setprio 0
	s_mov_b32 m0, s55
	v_lshl_add_u64 v[210:211], v[214:215], 0, s[12:13]
	s_barrier
	ds_read_b128 v[144:147], v204 offset:49152
	ds_read_b128 v[148:151], v204 offset:50176
	ds_read_b128 v[152:155], v204 offset:51200
	ds_read_b128 v[156:159], v204 offset:52224
	ds_read_b128 v[160:163], v204 offset:53248
	ds_read_b128 v[164:167], v204 offset:54272
	ds_read_b128 v[168:171], v204 offset:55296
	ds_read_b128 v[172:175], v204 offset:56320
	global_load_lds_dwordx4 v[210:211], off
	v_lshl_add_u64 v[210:211], v[216:217], 0, s[12:13]
	s_mov_b32 m0, s56
	s_nop 0
	global_load_lds_dwordx4 v[210:211], off
	s_barrier
	s_waitcnt lgkmcnt(0)
	s_setprio 1
	s_waitcnt lgkmcnt(0)
	v_mfma_f32_16x16x32_bf16 v[60:63], v[128:131], v[144:147], v[60:63]
	v_mfma_f32_16x16x32_bf16 v[56:59], v[136:139], v[144:147], v[56:59]
	v_mfma_f32_16x16x32_bf16 v[44:47], v[128:131], v[152:155], v[44:47]
	v_mfma_f32_16x16x32_bf16 v[40:43], v[136:139], v[152:155], v[40:43]
	v_mfma_f32_16x16x32_bf16 v[28:31], v[128:131], v[160:163], v[28:31]
	v_mfma_f32_16x16x32_bf16 v[24:27], v[136:139], v[160:163], v[24:27]
	v_mfma_f32_16x16x32_bf16 v[12:15], v[128:131], v[168:171], v[12:15]
	v_mfma_f32_16x16x32_bf16 v[8:11], v[136:139], v[168:171], v[8:11]
	v_mfma_f32_16x16x32_bf16 v[60:63], v[132:135], v[148:151], v[60:63]
	v_mfma_f32_16x16x32_bf16 v[56:59], v[140:143], v[148:151], v[56:59]
	v_mfma_f32_16x16x32_bf16 v[44:47], v[132:135], v[156:159], v[44:47]
	v_mfma_f32_16x16x32_bf16 v[40:43], v[140:143], v[156:159], v[40:43]
	v_mfma_f32_16x16x32_bf16 v[28:31], v[132:135], v[164:167], v[28:31]
	v_mfma_f32_16x16x32_bf16 v[24:27], v[140:143], v[164:167], v[24:27]
	v_mfma_f32_16x16x32_bf16 v[12:15], v[132:135], v[172:175], v[12:15]
	v_mfma_f32_16x16x32_bf16 v[8:11], v[140:143], v[172:175], v[8:11]
	s_setprio 0
	s_barrier
	s_add_u32 s40, s40, 0x80080
	s_addc_u32 s41, s41, 0
	s_add_i32 s42, s42, s49
	v_lshl_add_u64 v[128:129], s[40:41], 0, v[176:177]
	s_mov_b32 m0, s42
	s_nop 0
	global_load_lds_dwordx4 v[128:129], off
	v_lshl_add_u64 v[128:129], s[40:41], 0, v[178:179]
	s_add_i32 m0, s42, 0x2000
	s_nop 0
	global_load_lds_dwordx4 v[128:129], off
	s_waitcnt vmcnt(6)
	s_barrier
	s_setprio 1
	v_mfma_f32_16x16x32_bf16 v[52:55], v[186:189], v[144:147], v[52:55]
	v_mfma_f32_16x16x32_bf16 v[48:51], v[194:197], v[144:147], v[48:51]
	v_mfma_f32_16x16x32_bf16 v[36:39], v[186:189], v[152:155], v[36:39]
	v_mfma_f32_16x16x32_bf16 v[32:35], v[194:197], v[152:155], v[32:35]
	v_mfma_f32_16x16x32_bf16 v[20:23], v[186:189], v[160:163], v[20:23]
	v_mfma_f32_16x16x32_bf16 v[16:19], v[194:197], v[160:163], v[16:19]
	v_mfma_f32_16x16x32_bf16 v[4:7], v[186:189], v[168:171], v[4:7]
	v_mfma_f32_16x16x32_bf16 v[0:3], v[194:197], v[168:171], v[0:3]
	v_mfma_f32_16x16x32_bf16 v[52:55], v[190:193], v[148:151], v[52:55]
	v_mfma_f32_16x16x32_bf16 v[48:51], v[206:209], v[148:151], v[48:51]
	v_mfma_f32_16x16x32_bf16 v[36:39], v[190:193], v[156:159], v[36:39]
	v_mfma_f32_16x16x32_bf16 v[32:35], v[206:209], v[156:159], v[32:35]
	v_mfma_f32_16x16x32_bf16 v[20:23], v[190:193], v[164:167], v[20:23]
	v_mfma_f32_16x16x32_bf16 v[16:19], v[206:209], v[164:167], v[16:19]
	v_mfma_f32_16x16x32_bf16 v[4:7], v[190:193], v[172:175], v[4:7]
	v_mfma_f32_16x16x32_bf16 v[0:3], v[206:209], v[172:175], v[0:3]
	s_setprio 0
	s_add_i32 s29, s29, 2
	s_add_u32 s38, s38, 0x100
	s_addc_u32 s39, s39, 0
	s_add_u32 s21, s21, 0x100
	s_addc_u32 s23, s23, 0
	s_cmp_gt_u32 s29, 29
	s_barrier
	s_cbranch_scc0 .LBB0_621
	s_branch .Lpeel_1_exit

; DI u32x2 pk4(f32x4 v) { u32x2 r; r.x = pk2(v[0], v[1]); r.y = pk2(v[2], v[3]); return r; }
; DI float bf_lo(unsigned w) { return __uint_as_float(w << 16); }
; DI float bf_hi(unsigned w) { return __uint_as_float(w & 0xffff0000u); }
; #define COLS4 _Pragma("unroll") for (int bj = 0; bj < 2; ++bj) _Pragma("unroll") for (int n = 0; n < 2; ++n)
;     DI void operator()(const Acc& acc, const Unit& u, int wr, int wc, int fr, int fq) const {
;     ...
;                 for (int m = 0; m < 4; ++m) { const size_t o = (size_t)(row0 + ai * HALF + m * 16) * 2048 + colp;
;                     if (PH == 4) { COLS4 xo[m][bj][n] = *(const f32x4*)(p.x + o + bj * HALF + n * 4); }
;                     else {
; #pragma unroll
;                         for (int bj = 0; bj < 2; ++bj) { const u32x4 w = *(const u32x4*)(WSB(OFF_XB) + o + bj * HALF);
;                             xo[m][bj][0] = (f32x4){bf_lo(w.x), bf_hi(w.x), bf_lo(w.y), bf_hi(w.y)}; xo[m][bj][1] = (f32x4){bf_lo(w.z), bf_hi(w.z), bf_lo(w.w), bf_hi(w.w)}; } } }
; #pragma unroll
;                 for (int m = 0; m < 4; ++m) { const int r = row0 + ai * HALF + m * 16; const size_t o = (size_t)r * 2048 + colp; float part = 0.f;
; #pragma unroll
;                     for (int bj = 0; bj < 2; ++bj) { const f32x4 x0 = xo[m][bj][0] + acc[ai][bj][m][0], x1 = xo[m][bj][1] + acc[ai][bj][m][1];
;                         const u32x2 h0 = pk4(x0), h1 = pk4(x1);
;                         *(u32x4*)(WSB(OFF_XB) + o + bj * HALF) = (u32x4){h0.x, h0.y, h1.x, h1.y};
;                         part += x0[0] * x0[0] + x0[1] * x0[1] + x0[2] * x0[2] + x0[3] * x0[3] + x1[0] * x1[0] + x1[1] * x1[1] + x1[2] * x1[2] + x1[3] * x1[3]; }
;                     part += __shfl_xor(part, 16); part += __shfl_xor(part, 32);
;                     if (fq == 0) unsafeAtomicAdd(ssq + r, part);
.Lpeel_1_exit:
	v_lshl_add_u32 v190, s28, 8, v198
	v_lshl_add_u32 v186, s62, 8, v200
	v_ashrrev_i32_e32 v187, 31, v186
	v_ashrrev_i32_e32 v191, 31, v190
	v_lshl_add_u64 v[188:189], v[186:187], 2, s[16:17]
	v_lshlrev_b64 v[128:129], 13, v[190:191]
	v_lshl_add_u64 v[128:129], v[188:189], 0, v[128:129]
	global_load_dwordx4 v[206:209], v[128:129], off
	global_load_dwordx4 v[210:213], v[128:129], off offset:16
	global_load_dwordx4 v[214:217], v[128:129], off offset:512
	global_load_dwordx4 v[218:221], v[128:129], off offset:528
	v_or_b32_e32 v196, 16, v190
	v_or_b32_e32 v194, 32, v190
	v_or_b32_e32 v192, 48, v190
	v_ashrrev_i32_e32 v197, 31, v196
	v_ashrrev_i32_e32 v195, 31, v194
	v_ashrrev_i32_e32 v193, 31, v192
	v_lshlrev_b64 v[128:129], 13, v[196:197]
	v_lshlrev_b64 v[130:131], 13, v[194:195]
	v_lshlrev_b64 v[132:133], 13, v[192:193]
	v_lshl_add_u64 v[128:129], v[188:189], 0, v[128:129]
	v_lshl_add_u64 v[130:131], v[188:189], 0, v[130:131]
	v_lshl_add_u64 v[132:133], v[188:189], 0, v[132:133]
	global_load_dwordx4 v[168:171], v[128:129], off offset:16
	global_load_dwordx4 v[172:175], v[128:129], off
	global_load_dwordx4 v[160:163], v[128:129], off offset:528
	global_load_dwordx4 v[164:167], v[128:129], off offset:512
	global_load_dwordx4 v[152:155], v[130:131], off offset:16
	global_load_dwordx4 v[156:159], v[130:131], off
	global_load_dwordx4 v[144:147], v[130:131], off offset:528
	global_load_dwordx4 v[148:151], v[130:131], off offset:512
	global_load_dwordx4 v[136:139], v[132:133], off offset:16
	global_load_dwordx4 v[140:143], v[132:133], off
	s_nop 0
	global_load_dwordx4 v[128:131], v[132:133], off offset:528
	s_nop 0
	global_load_dwordx4 v[132:135], v[132:133], off offset:512
	v_lshlrev_b64 v[222:223], 12, v[190:191]
	v_lshlrev_b64 v[186:187], 1, v[186:187]
	v_lshl_add_u64 v[224:225], s[18:19], 0, v[222:223]
	v_lshl_add_u64 v[224:225], v[224:225], 0, v[186:187]
	v_lshl_add_u64 v[222:223], s[10:11], 0, v[222:223]
	v_lshl_add_u64 v[222:223], v[222:223], 0, v[186:187]
	s_waitcnt vmcnt(0)
	v_pk_add_f32 v[124:125], v[124:125], v[206:207]
	v_pk_add_f32 v[120:121], v[120:121], v[210:211]
	v_pk_add_f32 v[206:207], v[116:117], v[214:215]
	v_pk_add_f32 v[210:211], v[112:113], v[218:219]
	v_cvt_pk_bf16_f32 v112, v124, v125
	v_mul_f32_e32 v117, v125, v125
	v_mul_f32_e32 v125, v207, v207
	v_pk_add_f32 v[126:127], v[126:127], v[208:209]
	v_pk_add_f32 v[118:119], v[118:119], v[216:217]
	v_fmac_f32_e32 v117, v124, v124
	v_fmac_f32_e32 v125, v206, v206
	v_fmac_f32_e32 v117, v126, v126
	v_fmac_f32_e32 v125, v118, v118
	v_fmac_f32_e32 v117, v127, v127
	v_fmac_f32_e32 v125, v119, v119
	v_fmac_f32_e32 v117, v120, v120
	v_fmac_f32_e32 v125, v210, v210
	v_pk_add_f32 v[122:123], v[122:123], v[212:213]
	v_pk_add_f32 v[208:209], v[114:115], v[220:221]
	v_fmac_f32_e32 v117, v121, v121
	v_fmac_f32_e32 v125, v211, v211
	v_fmac_f32_e32 v117, v122, v122
	v_fmac_f32_e32 v125, v208, v208
	v_fmac_f32_e32 v117, v123, v123
	v_fmac_f32_e32 v125, v209, v209
	v_cvt_pk_bf16_f32 v114, v120, v121
	v_add_f32_e32 v120, v117, v125
	ds_bpermute_b32 v121, v201, v120
	v_cvt_pk_bf16_f32 v113, v126, v127
	v_cvt_pk_bf16_f32 v115, v122, v123
	global_store_dwordx4 v[224:225], v[112:115], off sc1
	v_cvt_pk_bf16_f32 v116, v206, v207
	v_cvt_pk_bf16_f32 v117, v118, v119
	s_waitcnt lgkmcnt(0)
	v_add_f32_e32 v112, v120, v121
	ds_bpermute_b32 v113, v202, v112
	v_add_co_u32_e32 v114, vcc, s61, v222
	v_cvt_pk_bf16_f32 v118, v210, v211
	v_cvt_pk_bf16_f32 v119, v208, v209
	v_addc_co_u32_e32 v115, vcc, 0, v223, vcc
	global_store_dwordx4 v[114:115], v[116:119], off offset:256 sc1
	s_and_saveexec_b64 s[28:29], s[2:3]
	s_cbranch_execz .LBB0_624
	s_waitcnt lgkmcnt(0)
	v_add_f32_e32 v114, v112, v113
	v_lshl_add_u64 v[112:113], v[190:191], 2, s[14:15]
	global_atomic_add_f32 v[112:113], v114, off

; #define PG8_STAGE(bufoff, gbase, voff) do { _Pragma("unroll") for (int _i = 0; _i < 2; ++_i) \
;         __builtin_amdgcn_global_load_lds((const unsigned*)((const char*)(gbase) + (voff)[_i]), (LAS unsigned*)(lds + (bufoff) + ldsw + _i * 8192), 16, 0, 0); } while (0)
; #define PG8_LDA(dst, b, h) do { _Pragma("unroll") for (int m = 0; m < 4; ++m) _Pragma("unroll") for (int k = 0; k < 2; ++k) dst[m][k] = *(const LAS bf16x8*)(lds + PG8_SA(b, h) + aoff + m * 2048 + k * 1024); } while (0)
; #define PG8_LDB(dst, b, h) do { _Pragma("unroll") for (int n = 0; n < 2; ++n) _Pragma("unroll") for (int k = 0; k < 2; ++k) dst[n][k] = *(const LAS bf16x8*)(lds + PG8_SB(b, h) + boff + n * 2048 + k * 1024); } while (0)
; #define PG8_MMA(ai, bj, At, Bt) do { __builtin_amdgcn_s_setprio(1); _Pragma("unroll") for (int m = 0; m < 4; ++m) _Pragma("unroll") for (int n = 0; n < 2; ++n) _Pragma("unroll") for (int k = 0; k < 2; ++k) \
;         acc[ai][bj][m][n] = __builtin_amdgcn_mfma_f32_16x16x32_bf16(Bt[n][k], At[m][k], acc[ai][bj][m][n], 0, 0, 0); __builtin_amdgcn_s_setprio(0); } while (0)
; #define PG8_WAIT_L(n) asm volatile("s_waitcnt lgkmcnt(" #n ")" ::: "memory")
; #define PG8_BAR __builtin_amdgcn_s_barrier()
; #define PG8_SCHED __builtin_amdgcn_sched_barrier(0)
; template <class Epi>
; DI void gemm_phase(LAS unsigned char* lds, int wid, int K, int lda, int ldb, bool bperm, const Sched3& S, const Epi& E) {
;     ...
;             PG8_LDB(B0, 0, 0); PG8_SCHED; PG8_LDA(At, 0, 0); PG8_STAGE(PG8_SA(1, 1), a1 + hA, voffA);
;             PG8_WAIT_L(8); PG8_BAR; PG8_WAIT_L(0); PG8_MMA(0, 0, At, B0); PG8_BAR; PG8_SCHED;
;             PG8_LDB(B1, 0, 1); PG8_STAGE(PG8_SB(0, 0), b2, voffB);
;             PG8_BAR; PG8_WAIT_L(0); PG8_MMA(0, 1, At, B1); PG8_BAR;
;             PG8_LDA(At, 0, 1); PG8_STAGE(PG8_SA(0, 0), a2, voffA);
;             PG8_BAR; PG8_WAIT_L(0); if (full) PG8_MMA(1, 0, At, B0); PG8_BAR; PG8_SCHED;
.LBB0_704:
	v_lshl_add_u32 v218, s22, 8, v155
	v_lshlrev_b32_e32 v218, 2, v218
	global_load_dword v220, v218, s[10:11]
	global_load_dword v221, v218, s[10:11] offset:64
	global_load_dword v222, v218, s[10:11] offset:128
	global_load_dword v223, v218, s[10:11] offset:192
	global_load_dword v224, v218, s[10:11] offset:512
	global_load_dword v225, v218, s[10:11] offset:576
	global_load_dword v226, v218, s[10:11] offset:640
	global_load_dword v227, v218, s[10:11] offset:704
	s_add_u32 s28, s28, 0x80080
	s_addc_u32 s29, s29, 0
	s_add_u32 s15, s30, 0x100
	s_nop 0
	s_addc_u32 s17, s31, 0
	s_mov_b32 s57, -2
	ds_read_b128 v[138:141], v160
	ds_read_b128 v[142:145], v160 offset:1024
	ds_read_b128 v[146:149], v160 offset:2048
	ds_read_b128 v[150:153], v160 offset:3072
	s_add_u32 s30, s28, 0xfff80080
	s_addc_u32 s31, s29, -1
	s_cmp_eq_u32 s57, 28
	s_cselect_b32 s37, s25, s31
	s_cselect_b32 s36, s24, s30
	s_cselect_b32 s31, s27, s17
	s_cselect_b32 s30, s26, s15
	v_lshl_add_u64 v[156:157], s[28:29], 0, v[132:133]
	s_add_i32 m0, s23, 0xc000
	ds_read_b128 v[164:167], v161
	ds_read_b128 v[168:171], v161 offset:1024
	ds_read_b128 v[172:175], v161 offset:2048
	ds_read_b128 v[176:179], v161 offset:3072
	ds_read_b128 v[180:183], v161 offset:4096
	ds_read_b128 v[184:187], v161 offset:5120
	ds_read_b128 v[188:191], v161 offset:6144
	ds_read_b128 v[192:195], v161 offset:7168
	global_load_lds_dwordx4 v[156:157], off
	v_lshl_add_u64 v[156:157], s[28:29], 0, v[134:135]
	s_add_i32 m0, s23, 0xe000
	s_nop 0
	global_load_lds_dwordx4 v[156:157], off
	s_waitcnt lgkmcnt(8)
	s_barrier
	s_waitcnt lgkmcnt(0)
	s_setprio 1
	s_waitcnt lgkmcnt(0)
	v_mfma_f32_16x16x32_bf16 v[124:127], v[138:141], v[164:167], 0
	v_mfma_f32_16x16x32_bf16 v[120:123], v[146:149], v[164:167], 0
	v_mfma_f32_16x16x32_bf16 v[116:119], v[138:141], v[172:175], 0
	v_mfma_f32_16x16x32_bf16 v[104:107], v[146:149], v[172:175], 0
	v_mfma_f32_16x16x32_bf16 v[96:99], v[138:141], v[180:183], 0
	v_mfma_f32_16x16x32_bf16 v[88:91], v[146:149], v[180:183], 0
	v_mfma_f32_16x16x32_bf16 v[80:83], v[138:141], v[188:191], 0
	v_mfma_f32_16x16x32_bf16 v[72:75], v[146:149], v[188:191], 0
	v_mfma_f32_16x16x32_bf16 v[124:127], v[142:145], v[168:171], v[124:127]
	v_mfma_f32_16x16x32_bf16 v[120:123], v[150:153], v[168:171], v[120:123]
	v_mfma_f32_16x16x32_bf16 v[116:119], v[142:145], v[176:179], v[116:119]
	v_mfma_f32_16x16x32_bf16 v[104:107], v[150:153], v[176:179], v[104:107]
	v_mfma_f32_16x16x32_bf16 v[96:99], v[142:145], v[184:187], v[96:99]
	v_mfma_f32_16x16x32_bf16 v[88:91], v[150:153], v[184:187], v[88:91]
	v_mfma_f32_16x16x32_bf16 v[80:83], v[142:145], v[192:195], v[80:83]
	v_mfma_f32_16x16x32_bf16 v[72:75], v[150:153], v[192:195], v[72:75]
	s_setprio 0
	s_barrier
	s_add_i32 s58, s53, s43
	v_lshl_add_u64 v[156:157], s[30:31], 0, v[130:131]
	s_mov_b32 m0, s58
	ds_read_b128 v[196:199], v162
	ds_read_b128 v[200:203], v162 offset:1024
	ds_read_b128 v[204:207], v162 offset:2048
	ds_read_b128 v[208:211], v162 offset:3072
	global_load_lds_dwordx4 v[156:157], off
	v_lshl_add_u64 v[212:213], s[30:31], 0, v[128:129]
	s_add_i32 m0, s58, 0x2000
	s_nop 0
	global_load_lds_dwordx4 v[212:213], off
	s_barrier
	s_waitcnt lgkmcnt(0)
	s_setprio 1
	s_waitcnt lgkmcnt(0)
	v_mfma_f32_16x16x32_bf16 v[112:115], v[196:199], v[164:167], 0
	v_mfma_f32_16x16x32_bf16 v[108:111], v[204:207], v[164:167], 0
	v_mfma_f32_16x16x32_bf16 v[100:103], v[196:199], v[172:175], 0
	v_mfma_f32_16x16x32_bf16 v[92:95], v[204:207], v[172:175], 0
	v_mfma_f32_16x16x32_bf16 v[84:87], v[196:199], v[180:183], 0
	v_mfma_f32_16x16x32_bf16 v[76:79], v[204:207], v[180:183], 0
	v_mfma_f32_16x16x32_bf16 v[68:71], v[196:199], v[188:191], 0
	v_mfma_f32_16x16x32_bf16 v[64:67], v[204:207], v[188:191], 0
	v_mfma_f32_16x16x32_bf16 v[112:115], v[200:203], v[168:171], v[112:115]
	v_mfma_f32_16x16x32_bf16 v[108:111], v[208:211], v[168:171], v[108:111]
	v_mfma_f32_16x16x32_bf16 v[100:103], v[200:203], v[176:179], v[100:103]
	v_mfma_f32_16x16x32_bf16 v[92:95], v[208:211], v[176:179], v[92:95]
	v_mfma_f32_16x16x32_bf16 v[84:87], v[200:203], v[184:187], v[84:87]
	v_mfma_f32_16x16x32_bf16 v[76:79], v[208:211], v[184:187], v[76:79]
	v_mfma_f32_16x16x32_bf16 v[68:71], v[200:203], v[192:195], v[68:71]
	v_mfma_f32_16x16x32_bf16 v[64:67], v[208:211], v[192:195], v[64:67]
	s_setprio 0
	s_mov_b32 m0, s23
	v_lshl_add_u64 v[214:215], s[36:37], 0, v[130:131]
	s_barrier
	ds_read_b128 v[164:167], v161 offset:16384
	ds_read_b128 v[168:171], v161 offset:17408
	ds_read_b128 v[172:175], v161 offset:18432
	ds_read_b128 v[176:179], v161 offset:19456
	ds_read_b128 v[180:183], v161 offset:20480
	ds_read_b128 v[184:187], v161 offset:21504
	ds_read_b128 v[188:191], v161 offset:22528
	ds_read_b128 v[192:195], v161 offset:23552
	global_load_lds_dwordx4 v[214:215], off
	v_lshl_add_u64 v[216:217], s[36:37], 0, v[128:129]
	s_mov_b32 m0, s46
	s_nop 0
	global_load_lds_dwordx4 v[216:217], off
	s_barrier
	s_waitcnt lgkmcnt(0)
	s_setprio 1
	s_waitcnt lgkmcnt(0)
	v_mfma_f32_16x16x32_bf16 v[60:63], v[138:141], v[164:167], 0
	v_mfma_f32_16x16x32_bf16 v[56:59], v[146:149], v[164:167], 0
	v_mfma_f32_16x16x32_bf16 v[48:51], v[138:141], v[172:175], 0
	v_mfma_f32_16x16x32_bf16 v[40:43], v[146:149], v[172:175], 0
	v_mfma_f32_16x16x32_bf16 v[32:35], v[138:141], v[180:183], 0
	v_mfma_f32_16x16x32_bf16 v[24:27], v[146:149], v[180:183], 0
	v_mfma_f32_16x16x32_bf16 v[16:19], v[138:141], v[188:191], 0
	v_mfma_f32_16x16x32_bf16 v[8:11], v[146:149], v[188:191], 0
	v_mfma_f32_16x16x32_bf16 v[60:63], v[142:145], v[168:171], v[60:63]
	v_mfma_f32_16x16x32_bf16 v[56:59], v[150:153], v[168:171], v[56:59]
	v_mfma_f32_16x16x32_bf16 v[48:51], v[142:145], v[176:179], v[48:51]
	v_mfma_f32_16x16x32_bf16 v[40:43], v[150:153], v[176:179], v[40:43]
	v_mfma_f32_16x16x32_bf16 v[32:35], v[142:145], v[184:187], v[32:35]
	v_mfma_f32_16x16x32_bf16 v[24:27], v[150:153], v[184:187], v[24:27]
	v_mfma_f32_16x16x32_bf16 v[16:19], v[142:145], v[192:195], v[16:19]
	v_mfma_f32_16x16x32_bf16 v[8:11], v[150:153], v[192:195], v[8:11]
	s_setprio 0
	s_barrier
; #define PG8_STAGE(bufoff, gbase, voff) do { _Pragma("unroll") for (int _i = 0; _i < 2; ++_i) \
;         __builtin_amdgcn_global_load_lds((const unsigned*)((const char*)(gbase) + (voff)[_i]), (LAS unsigned*)(lds + (bufoff) + ldsw + _i * 8192), 16, 0, 0); } while (0)
; #define PG8_LDA(dst, b, h) do { _Pragma("unroll") for (int m = 0; m < 4; ++m) _Pragma("unroll") for (int k = 0; k < 2; ++k) dst[m][k] = *(const LAS bf16x8*)(lds + PG8_SA(b, h) + aoff + m * 2048 + k * 1024); } while (0)
; #define PG8_LDB(dst, b, h) do { _Pragma("unroll") for (int n = 0; n < 2; ++n) _Pragma("unroll") for (int k = 0; k < 2; ++k) dst[n][k] = *(const LAS bf16x8*)(lds + PG8_SB(b, h) + boff + n * 2048 + k * 1024); } while (0)
; #define PG8_MMA(ai, bj, At, Bt) do { __builtin_amdgcn_s_setprio(1); _Pragma("unroll") for (int m = 0; m < 4; ++m) _Pragma("unroll") for (int n = 0; n < 2; ++n) _Pragma("unroll") for (int k = 0; k < 2; ++k) \
;         acc[ai][bj][m][n] = __builtin_amdgcn_mfma_f32_16x16x32_bf16(Bt[n][k], At[m][k], acc[ai][bj][m][n], 0, 0, 0); __builtin_amdgcn_s_setprio(0); } while (0)
; #define PG8_WAIT_V(n) asm volatile("s_waitcnt vmcnt(" #n ")" ::: "memory")
; #define PG8_WAIT_L(n) asm volatile("s_waitcnt lgkmcnt(" #n ")" ::: "memory")
; #define PG8_BAR __builtin_amdgcn_s_barrier()
; #define PG8_SCHED __builtin_amdgcn_sched_barrier(0)
; template <class Epi>
; DI void gemm_phase(LAS unsigned char* lds, int wid, int K, int lda, int ldb, bool bperm, const Sched3& S, const Epi& E) {
;     ...
;             PG8_STAGE(PG8_SB(0, 1), b2 + hstepB, voffB);
;             PG8_WAIT_V(6); PG8_BAR; if (full) PG8_MMA(1, 1, At, B1); PG8_BAR;
;             PG8_LDB(B0, 1, 0); PG8_SCHED; PG8_LDA(At, 1, 0); PG8_STAGE(PG8_SA(0, 1), a2 + h2, voffA);
;             PG8_WAIT_L(8); PG8_BAR; PG8_WAIT_L(0); PG8_MMA(0, 0, At, B0); PG8_BAR; PG8_SCHED;
;             PG8_LDB(B1, 1, 1); PG8_STAGE(PG8_SB(1, 0), b3, voffB);
;             PG8_BAR; PG8_WAIT_L(0); PG8_MMA(0, 1, At, B1); PG8_BAR;
	s_add_u32 s58, s30, 0x80000
	s_addc_u32 s59, s31, 0
	s_add_i32 s60, s54, s43
	v_lshl_add_u64 v[138:139], s[58:59], 0, v[130:131]
	s_mov_b32 m0, s60
	s_nop 0
	global_load_lds_dwordx4 v[138:139], off
	v_lshl_add_u64 v[138:139], s[58:59], 0, v[128:129]
	s_add_i32 m0, s60, 0x2000
	s_nop 0
	global_load_lds_dwordx4 v[138:139], off
	s_waitcnt vmcnt(6)
	s_barrier
	s_setprio 1
	v_mfma_f32_16x16x32_bf16 v[52:55], v[196:199], v[164:167], 0
	v_mfma_f32_16x16x32_bf16 v[44:47], v[204:207], v[164:167], 0
	v_mfma_f32_16x16x32_bf16 v[36:39], v[196:199], v[172:175], 0
	v_mfma_f32_16x16x32_bf16 v[28:31], v[204:207], v[172:175], 0
	v_mfma_f32_16x16x32_bf16 v[20:23], v[196:199], v[180:183], 0
	v_mfma_f32_16x16x32_bf16 v[12:15], v[204:207], v[180:183], 0
	v_mfma_f32_16x16x32_bf16 v[4:7], v[196:199], v[188:191], 0
	v_mfma_f32_16x16x32_bf16 v[0:3], v[204:207], v[188:191], 0
	v_mfma_f32_16x16x32_bf16 v[52:55], v[200:203], v[168:171], v[52:55]
	v_mfma_f32_16x16x32_bf16 v[44:47], v[208:211], v[168:171], v[44:47]
	v_mfma_f32_16x16x32_bf16 v[36:39], v[200:203], v[176:179], v[36:39]
	v_mfma_f32_16x16x32_bf16 v[28:31], v[208:211], v[176:179], v[28:31]
	v_mfma_f32_16x16x32_bf16 v[20:23], v[200:203], v[184:187], v[20:23]
	v_mfma_f32_16x16x32_bf16 v[12:15], v[208:211], v[184:187], v[12:15]
	v_mfma_f32_16x16x32_bf16 v[4:7], v[200:203], v[192:195], v[4:7]
	v_mfma_f32_16x16x32_bf16 v[0:3], v[208:211], v[192:195], v[0:3]
	s_setprio 0
	s_add_i32 s58, 0, 0x18000
	v_add_u32_e32 v150, s58, v158
	s_barrier
	ds_read_b128 v[138:141], v150
	ds_read_b128 v[142:145], v150 offset:1024
	ds_read_b128 v[146:149], v150 offset:2048
	ds_read_b128 v[150:153], v150 offset:3072
	s_add_u32 s36, s36, 0x80000
	s_addc_u32 s37, s37, 0
	s_mov_b32 m0, s47
	v_lshl_add_u64 v[196:197], s[36:37], 0, v[130:131]
	ds_read_b128 v[164:167], v161 offset:32768
	ds_read_b128 v[168:171], v161 offset:33792
	ds_read_b128 v[172:175], v161 offset:34816
	ds_read_b128 v[176:179], v161 offset:35840
	ds_read_b128 v[180:183], v161 offset:36864
	ds_read_b128 v[184:187], v161 offset:37888
	ds_read_b128 v[188:191], v161 offset:38912
	ds_read_b128 v[192:195], v161 offset:39936
	global_load_lds_dwordx4 v[196:197], off
	v_lshl_add_u64 v[196:197], s[36:37], 0, v[128:129]
	s_mov_b32 m0, s48
	s_nop 0
	global_load_lds_dwordx4 v[196:197], off
	s_waitcnt lgkmcnt(8)
	s_barrier
	s_waitcnt lgkmcnt(0)
	s_setprio 1
	s_waitcnt lgkmcnt(0)
	v_mfma_f32_16x16x32_bf16 v[124:127], v[138:141], v[164:167], v[124:127]
	v_mfma_f32_16x16x32_bf16 v[120:123], v[146:149], v[164:167], v[120:123]
	v_mfma_f32_16x16x32_bf16 v[116:119], v[138:141], v[172:175], v[116:119]
	v_mfma_f32_16x16x32_bf16 v[104:107], v[146:149], v[172:175], v[104:107]
	v_mfma_f32_16x16x32_bf16 v[96:99], v[138:141], v[180:183], v[96:99]
	v_mfma_f32_16x16x32_bf16 v[88:91], v[146:149], v[180:183], v[88:91]
	v_mfma_f32_16x16x32_bf16 v[80:83], v[138:141], v[188:191], v[80:83]
	v_mfma_f32_16x16x32_bf16 v[72:75], v[146:149], v[188:191], v[72:75]
	v_mfma_f32_16x16x32_bf16 v[124:127], v[142:145], v[168:171], v[124:127]
	v_mfma_f32_16x16x32_bf16 v[120:123], v[150:153], v[168:171], v[120:123]
	v_mfma_f32_16x16x32_bf16 v[116:119], v[142:145], v[176:179], v[116:119]
	v_mfma_f32_16x16x32_bf16 v[104:107], v[150:153], v[176:179], v[104:107]
	v_mfma_f32_16x16x32_bf16 v[96:99], v[142:145], v[184:187], v[96:99]
	v_mfma_f32_16x16x32_bf16 v[88:91], v[150:153], v[184:187], v[88:91]
	v_mfma_f32_16x16x32_bf16 v[80:83], v[142:145], v[192:195], v[80:83]
	v_mfma_f32_16x16x32_bf16 v[72:75], v[150:153], v[192:195], v[72:75]
	s_setprio 0
	s_barrier
	s_add_i32 s36, 0, 0x1c000
	s_add_i32 s37, s58, s43
	v_add_u32_e32 v154, s36, v158
	v_lshl_add_u64 v[156:157], v[156:157], 0, s[8:9]
	s_mov_b32 m0, s37
	ds_read_b128 v[196:199], v154
	ds_read_b128 v[200:203], v154 offset:1024
	ds_read_b128 v[204:207], v154 offset:2048
	ds_read_b128 v[208:211], v154 offset:3072
	global_load_lds_dwordx4 v[156:157], off
	v_lshl_add_u64 v[156:157], v[212:213], 0, s[8:9]
	s_add_i32 m0, s37, 0x2000
	s_nop 0
	global_load_lds_dwordx4 v[156:157], off
	s_barrier
; #define PG8_STAGE(bufoff, gbase, voff) do { _Pragma("unroll") for (int _i = 0; _i < 2; ++_i) \
;         __builtin_amdgcn_global_load_lds((const unsigned*)((const char*)(gbase) + (voff)[_i]), (LAS unsigned*)(lds + (bufoff) + ldsw + _i * 8192), 16, 0, 0); } while (0)
; #define PG8_LDA(dst, b, h) do { _Pragma("unroll") for (int m = 0; m < 4; ++m) _Pragma("unroll") for (int k = 0; k < 2; ++k) dst[m][k] = *(const LAS bf16x8*)(lds + PG8_SA(b, h) + aoff + m * 2048 + k * 1024); } while (0)
; #define PG8_MMA(ai, bj, At, Bt) do { __builtin_amdgcn_s_setprio(1); _Pragma("unroll") for (int m = 0; m < 4; ++m) _Pragma("unroll") for (int n = 0; n < 2; ++n) _Pragma("unroll") for (int k = 0; k < 2; ++k) \
;         acc[ai][bj][m][n] = __builtin_amdgcn_mfma_f32_16x16x32_bf16(Bt[n][k], At[m][k], acc[ai][bj][m][n], 0, 0, 0); __builtin_amdgcn_s_setprio(0); } while (0)
; #define PG8_WAIT_V(n) asm volatile("s_waitcnt vmcnt(" #n ")" ::: "memory")
; #define PG8_WAIT_L(n) asm volatile("s_waitcnt lgkmcnt(" #n ")" ::: "memory")
; #define PG8_BAR __builtin_amdgcn_s_barrier()
; #define PG8_SCHED __builtin_amdgcn_sched_barrier(0)
; template <class Epi>
; DI void gemm_phase(LAS unsigned char* lds, int wid, int K, int lda, int ldb, bool bperm, const Sched3& S, const Epi& E) {
;     ...
;             PG8_BAR; PG8_WAIT_L(0); PG8_MMA(0, 1, At, B1); PG8_BAR;
;             PG8_LDA(At, 1, 1); PG8_STAGE(PG8_SA(1, 0), a3, voffA);
;             PG8_BAR; PG8_WAIT_L(0); if (full) PG8_MMA(1, 0, At, B0); PG8_BAR; PG8_SCHED;
;             PG8_STAGE(PG8_SB(1, 1), b3 + hstepB, voffB);
;             PG8_WAIT_V(6); PG8_BAR; if (full) PG8_MMA(1, 1, At, B1); PG8_BAR;
;         }
	s_waitcnt lgkmcnt(0)
	s_setprio 1
	s_waitcnt lgkmcnt(0)
	v_mfma_f32_16x16x32_bf16 v[112:115], v[196:199], v[164:167], v[112:115]
	v_mfma_f32_16x16x32_bf16 v[108:111], v[204:207], v[164:167], v[108:111]
	v_mfma_f32_16x16x32_bf16 v[100:103], v[196:199], v[172:175], v[100:103]
	v_mfma_f32_16x16x32_bf16 v[92:95], v[204:207], v[172:175], v[92:95]
	v_mfma_f32_16x16x32_bf16 v[84:87], v[196:199], v[180:183], v[84:87]
	v_mfma_f32_16x16x32_bf16 v[76:79], v[204:207], v[180:183], v[76:79]
	v_mfma_f32_16x16x32_bf16 v[68:71], v[196:199], v[188:191], v[68:71]
	v_mfma_f32_16x16x32_bf16 v[64:67], v[204:207], v[188:191], v[64:67]
	v_mfma_f32_16x16x32_bf16 v[112:115], v[200:203], v[168:171], v[112:115]
	v_mfma_f32_16x16x32_bf16 v[108:111], v[208:211], v[168:171], v[108:111]
	v_mfma_f32_16x16x32_bf16 v[100:103], v[200:203], v[176:179], v[100:103]
	v_mfma_f32_16x16x32_bf16 v[92:95], v[208:211], v[176:179], v[92:95]
	v_mfma_f32_16x16x32_bf16 v[84:87], v[200:203], v[184:187], v[84:87]
	v_mfma_f32_16x16x32_bf16 v[76:79], v[208:211], v[184:187], v[76:79]
	v_mfma_f32_16x16x32_bf16 v[68:71], v[200:203], v[192:195], v[68:71]
	v_mfma_f32_16x16x32_bf16 v[64:67], v[208:211], v[192:195], v[64:67]
	s_setprio 0
	s_mov_b32 m0, s49
	v_lshl_add_u64 v[156:157], v[214:215], 0, s[8:9]
	s_barrier
	ds_read_b128 v[164:167], v161 offset:49152
	ds_read_b128 v[168:171], v161 offset:50176
	ds_read_b128 v[172:175], v161 offset:51200
	ds_read_b128 v[176:179], v161 offset:52224
	ds_read_b128 v[180:183], v161 offset:53248
	ds_read_b128 v[184:187], v161 offset:54272
	ds_read_b128 v[188:191], v161 offset:55296
	ds_read_b128 v[192:195], v161 offset:56320
	global_load_lds_dwordx4 v[156:157], off
	v_lshl_add_u64 v[156:157], v[216:217], 0, s[8:9]
	s_mov_b32 m0, s50
	s_nop 0
	global_load_lds_dwordx4 v[156:157], off
	s_barrier
	s_waitcnt lgkmcnt(0)
	s_setprio 1
	s_waitcnt lgkmcnt(0)
	v_mfma_f32_16x16x32_bf16 v[60:63], v[138:141], v[164:167], v[60:63]
	v_mfma_f32_16x16x32_bf16 v[56:59], v[146:149], v[164:167], v[56:59]
	v_mfma_f32_16x16x32_bf16 v[48:51], v[138:141], v[172:175], v[48:51]
	v_mfma_f32_16x16x32_bf16 v[40:43], v[146:149], v[172:175], v[40:43]
	v_mfma_f32_16x16x32_bf16 v[32:35], v[138:141], v[180:183], v[32:35]
	v_mfma_f32_16x16x32_bf16 v[24:27], v[146:149], v[180:183], v[24:27]
	v_mfma_f32_16x16x32_bf16 v[16:19], v[138:141], v[188:191], v[16:19]
	v_mfma_f32_16x16x32_bf16 v[8:11], v[146:149], v[188:191], v[8:11]
	v_mfma_f32_16x16x32_bf16 v[60:63], v[142:145], v[168:171], v[60:63]
	v_mfma_f32_16x16x32_bf16 v[56:59], v[150:153], v[168:171], v[56:59]
	v_mfma_f32_16x16x32_bf16 v[48:51], v[142:145], v[176:179], v[48:51]
	v_mfma_f32_16x16x32_bf16 v[40:43], v[150:153], v[176:179], v[40:43]
	v_mfma_f32_16x16x32_bf16 v[32:35], v[142:145], v[184:187], v[32:35]
	v_mfma_f32_16x16x32_bf16 v[24:27], v[150:153], v[184:187], v[24:27]
	v_mfma_f32_16x16x32_bf16 v[16:19], v[142:145], v[192:195], v[16:19]
	v_mfma_f32_16x16x32_bf16 v[8:11], v[150:153], v[192:195], v[8:11]
	s_setprio 0
	s_barrier
	s_add_u32 s30, s30, 0x80080
	s_addc_u32 s31, s31, 0
	s_add_i32 s36, s36, s43
	v_lshl_add_u64 v[138:139], s[30:31], 0, v[130:131]
	s_mov_b32 m0, s36
	s_nop 0
	global_load_lds_dwordx4 v[138:139], off
	v_lshl_add_u64 v[138:139], s[30:31], 0, v[128:129]
	s_add_i32 m0, s36, 0x2000
	s_nop 0
	global_load_lds_dwordx4 v[138:139], off
	s_waitcnt vmcnt(6)
	s_barrier
	s_setprio 1
	v_mfma_f32_16x16x32_bf16 v[52:55], v[196:199], v[164:167], v[52:55]
	v_mfma_f32_16x16x32_bf16 v[44:47], v[204:207], v[164:167], v[44:47]
	v_mfma_f32_16x16x32_bf16 v[36:39], v[196:199], v[172:175], v[36:39]
	v_mfma_f32_16x16x32_bf16 v[28:31], v[204:207], v[172:175], v[28:31]
	v_mfma_f32_16x16x32_bf16 v[20:23], v[196:199], v[180:183], v[20:23]
	v_mfma_f32_16x16x32_bf16 v[12:15], v[204:207], v[180:183], v[12:15]
	v_mfma_f32_16x16x32_bf16 v[4:7], v[196:199], v[188:191], v[4:7]
	v_mfma_f32_16x16x32_bf16 v[0:3], v[204:207], v[188:191], v[0:3]
	v_mfma_f32_16x16x32_bf16 v[52:55], v[200:203], v[168:171], v[52:55]
	v_mfma_f32_16x16x32_bf16 v[44:47], v[208:211], v[168:171], v[44:47]
	v_mfma_f32_16x16x32_bf16 v[36:39], v[200:203], v[176:179], v[36:39]
	v_mfma_f32_16x16x32_bf16 v[28:31], v[208:211], v[176:179], v[28:31]
	v_mfma_f32_16x16x32_bf16 v[20:23], v[200:203], v[184:187], v[20:23]
	v_mfma_f32_16x16x32_bf16 v[12:15], v[208:211], v[184:187], v[12:15]
	v_mfma_f32_16x16x32_bf16 v[4:7], v[200:203], v[192:195], v[4:7]
	v_mfma_f32_16x16x32_bf16 v[0:3], v[208:211], v[192:195], v[0:3]
	s_setprio 0
	s_add_i32 s57, s57, 2
	s_add_u32 s28, s28, 0x100
	s_addc_u32 s29, s29, 0
	s_add_u32 s15, s15, 0x100
	s_addc_u32 s17, s17, 0
	s_cmp_gt_u32 s57, 29
	s_barrier
	s_cbranch_scc0 .LBB0_705
	s_branch .Lpeel_2_exit

; DI u32x2 pk4(f32x4 v) { u32x2 r; r.x = pk2(v[0], v[1]); r.y = pk2(v[2], v[3]); return r; }
; DI float silu_f(float x) { return x * __builtin_amdgcn_rcpf(1.f + __builtin_amdgcn_exp2f(-1.4426950409f * x)); }
; #define ROWS8 _Pragma("unroll") for (int ai = 0; ai < 2; ++ai) _Pragma("unroll") for (int m = 0; m < 4; ++m) if (ai == 0 || !hf)
; #define LOAD_ROW_RS(rsv, ssqp, invn) float rsv[2][4]; ROWS8_ALL rsv[ai][m] = (ssqp)[row0 + ai * HALF + m * 16]; ROWS8_ALL rsv[ai][m] = rstd_of(rsv[ai][m], invn)
;     DI void operator()(const Acc& acc, const Unit& u, int wr, int wc, int fr, int fq) const {
;     ...
;             LOAD_ROW_RS(rsv, SSQ(PH == 5 ? 2 : 6), 1.f / 2048.f);
;             const int ac0 = u.pn * 128 + wc * 32 + 8 * fq;
;             ROWS8 { const int r = row0 + ai * HALF + m * 16; const float rs = rsv[ai][m];
;                 u32x4 w;
; #pragma unroll
;                 for (int bj = 0; bj < 2; ++bj) { const f32x4 g = acc[ai][bj][m][0] * rs, uu = acc[ai][bj][m][1] * rs;
;                     f32x4 a; a[0] = silu_f(g[0]) * uu[0]; a[1] = silu_f(g[1]) * uu[1]; a[2] = silu_f(g[2]) * uu[2]; a[3] = silu_f(g[3]) * uu[3];
;                     const u32x2 h = pk4(a); if (bj == 0) { w.x = h.x; w.y = h.y; } else { w.z = h.x; w.w = h.y; } }
;                 *(u32x4*)(WSB(OFF_ACT) + (size_t)r * DFF + ac0) = w;
.Lpeel_2_exit:
	v_lshl_add_u32 v142, s22, 8, v155
	v_or_b32_e32 v156, 16, v142
	v_ashrrev_i32_e32 v157, 31, v156
	v_or_b32_e32 v152, 32, v142
	v_or_b32_e32 v150, 48, v142
	v_lshl_add_u64 v[138:139], v[156:157], 2, s[10:11]
	v_ashrrev_i32_e32 v153, 31, v152
	v_ashrrev_i32_e32 v151, 31, v150
	v_ashrrev_i32_e32 v143, 31, v142
	v_lshl_add_u64 v[140:141], v[152:153], 2, s[10:11]
	v_lshl_add_u64 v[144:145], v[150:151], 2, s[10:11]
	v_lshl_add_u64 v[146:147], v[142:143], 2, s[10:11]
	v_add_u32_e32 v148, 0x80, v142
	v_add_u32_e32 v146, 0x90, v142
	v_add_u32_e32 v144, 0xa0, v142
	v_add_u32_e32 v138, 0xb0, v142
	v_ashrrev_i32_e32 v149, 31, v148
	v_ashrrev_i32_e32 v147, 31, v146
	v_ashrrev_i32_e32 v145, 31, v144
	v_ashrrev_i32_e32 v139, 31, v138
	v_lshl_add_u64 v[140:141], v[148:149], 2, s[10:11]
	v_lshl_add_u64 v[164:165], v[146:147], 2, s[10:11]
	v_lshl_add_u64 v[166:167], v[144:145], 2, s[10:11]
	v_lshl_add_u64 v[168:169], v[138:139], 2, s[10:11]
	v_lshl_add_u32 v164, s56, 7, v159
	v_mov_b64_e32 v[140:141], s[12:13]
	v_ashrrev_i32_e32 v165, 31, v164
	v_mad_i64_i32 v[166:167], s[24:25], v142, s55, v[140:141]
	v_lshlrev_b64 v[142:143], 1, v[164:165]
	v_lshl_add_u64 v[164:165], v[166:167], 0, v[142:143]
	s_and_b64 vcc, exec, s[2:3]
	s_mov_b32 s56, s14
	s_mov_b32 s22, s16
	s_mov_b64 s[30:31], s[18:19]
	s_mov_b64 s[28:29], s[20:21]
	v_mov_b32_e32 v151, v221
	v_mov_b32_e32 v153, v222
	v_mov_b32_e32 v154, v223
	v_mov_b32_e32 v157, v220
	v_mov_b32_e32 v139, v224
	v_mov_b32_e32 v145, v225
	v_mov_b32_e32 v147, v226
	v_mov_b32_e32 v149, v227
	v_fmamk_f32 v151, v151, 0x3a000000, v163
	v_rsq_f32_e32 v168, v151
	v_fmamk_f32 v153, v153, 0x3a000000, v163
	v_fmamk_f32 v157, v157, 0x3a000000, v163
	v_rsq_f32_e32 v166, v157
	v_rsq_f32_e32 v170, v153
	v_pk_mul_f32 v[118:119], v[118:119], v[168:169] op_sel_hi:[1,0]
	v_pk_mul_f32 v[116:117], v[116:117], v[168:169] op_sel_hi:[1,0]
	v_pk_mul_f32 v[126:127], v[126:127], v[166:167] op_sel_hi:[1,0]
	v_pk_mul_f32 v[124:125], v[124:125], v[166:167] op_sel_hi:[1,0]
	v_pk_mul_f32 v[114:115], v[114:115], v[166:167] op_sel_hi:[1,0]
	v_pk_mul_f32 v[112:113], v[112:113], v[166:167] op_sel_hi:[1,0]
	v_pk_mul_f32 v[122:123], v[122:123], v[166:167] op_sel_hi:[1,0]
	v_pk_mul_f32 v[120:121], v[120:121], v[166:167] op_sel_hi:[1,0]
	v_pk_mul_f32 v[110:111], v[110:111], v[166:167] op_sel_hi:[1,0]
	v_pk_mul_f32 v[108:109], v[108:109], v[166:167] op_sel_hi:[1,0]
	v_mul_f32_e32 v151, 0xbfb8aa3b, v124
	v_mul_f32_e32 v153, 0xbfb8aa3b, v125
	v_mul_f32_e32 v157, 0xbfb8aa3b, v126
	v_mul_f32_e32 v166, 0xbfb8aa3b, v127
	v_mul_f32_e32 v167, 0xbfb8aa3b, v112
	v_mul_f32_e32 v169, 0xbfb8aa3b, v113
	v_mul_f32_e32 v171, 0xbfb8aa3b, v114
	v_mul_f32_e32 v172, 0xbfb8aa3b, v115
	v_exp_f32_e32 v151, v151
	v_exp_f32_e32 v153, v153
	v_exp_f32_e32 v157, v157
	v_exp_f32_e32 v166, v166
	v_exp_f32_e32 v167, v167
	v_exp_f32_e32 v169, v169
	v_exp_f32_e32 v171, v171
	v_exp_f32_e32 v172, v172
	v_mul_f32_e32 v173, 0xbfb8aa3b, v116
	v_exp_f32_e32 v178, v173
	v_add_f32_e32 v151, 1.0, v151
	v_add_f32_e32 v153, 1.0, v153
	v_add_f32_e32 v157, 1.0, v157
	v_add_f32_e32 v173, 1.0, v166
	v_add_f32_e32 v174, 1.0, v167
	v_add_f32_e32 v169, 1.0, v169
	v_add_f32_e32 v171, 1.0, v171
	v_add_f32_e32 v177, 1.0, v172
	v_rcp_f32_e32 v166, v151
	v_rcp_f32_e32 v167, v153
	v_rcp_f32_e32 v172, v157
	v_rcp_f32_e32 v173, v173
	v_rcp_f32_e32 v174, v174
	v_rcp_f32_e32 v175, v169
	v_rcp_f32_e32 v176, v171
	v_rcp_f32_e32 v177, v177
	v_pk_mul_f32 v[124:125], v[124:125], v[166:167]
	v_pk_mul_f32 v[126:127], v[126:127], v[172:173]
	v_pk_mul_f32 v[112:113], v[112:113], v[174:175]
	v_pk_mul_f32 v[114:115], v[114:115], v[176:177]
	v_pk_mul_f32 v[120:121], v[120:121], v[124:125]
	v_pk_mul_f32 v[122:123], v[122:123], v[126:127]
	v_pk_mul_f32 v[112:113], v[108:109], v[112:113]
	v_pk_mul_f32 v[114:115], v[110:111], v[114:115]
	v_cvt_pk_bf16_f32 v108, v120, v121
	v_cvt_pk_bf16_f32 v109, v122, v123
	v_cvt_pk_bf16_f32 v110, v112, v113
	v_cvt_pk_bf16_f32 v111, v114, v115
	global_store_dwordx4 v[164:165], v[108:111], off
	v_pk_mul_f32 v[104:105], v[104:105], v[168:169] op_sel_hi:[1,0]
	v_pk_mul_f32 v[106:107], v[106:107], v[168:169] op_sel_hi:[1,0]
	v_mul_f32_e32 v108, 0xbfb8aa3b, v117
	v_exp_f32_e32 v109, v108
	v_mul_f32_e32 v110, 0xbfb8aa3b, v118
	v_mul_f32_e32 v111, 0xbfb8aa3b, v119
	v_exp_f32_e32 v110, v110
	v_exp_f32_e32 v111, v111
	v_add_f32_e32 v108, 1.0, v178
	v_add_f32_e32 v109, 1.0, v109
	v_rcp_f32_e32 v108, v108
	v_rcp_f32_e32 v109, v109
	v_add_f32_e32 v110, 1.0, v110
	v_add_f32_e32 v111, 1.0, v111
	v_rcp_f32_e32 v110, v110
	v_rcp_f32_e32 v111, v111
	v_pk_mul_f32 v[108:109], v[116:117], v[108:109]
	v_pk_mul_f32 v[100:101], v[100:101], v[168:169] op_sel_hi:[1,0]
	v_pk_mul_f32 v[104:105], v[104:105], v[108:109]
	v_pk_mul_f32 v[108:109], v[118:119], v[110:111]
	v_cvt_pk_bf16_f32 v104, v104, v105
	v_pk_mul_f32 v[106:107], v[106:107], v[108:109]
	v_pk_mul_f32 v[102:103], v[102:103], v[168:169] op_sel_hi:[1,0]
	v_cvt_pk_bf16_f32 v105, v106, v107
	v_mul_f32_e32 v106, 0xbfb8aa3b, v100
	v_mul_f32_e32 v107, 0xbfb8aa3b, v101
	v_exp_f32_e32 v106, v106
	v_exp_f32_e32 v107, v107
	v_mul_f32_e32 v108, 0xbfb8aa3b, v102
	v_mul_f32_e32 v109, 0xbfb8aa3b, v103
	v_exp_f32_e32 v108, v108
	v_exp_f32_e32 v109, v109
	v_add_f32_e32 v106, 1.0, v106
	v_add_f32_e32 v107, 1.0, v107
	v_rcp_f32_e32 v106, v106
	v_rcp_f32_e32 v107, v107
	v_add_f32_e32 v108, 1.0, v108
	v_add_f32_e32 v109, 1.0, v109
	v_rcp_f32_e32 v108, v108
	v_rcp_f32_e32 v109, v109
	v_pk_mul_f32 v[92:93], v[92:93], v[168:169] op_sel_hi:[1,0]
	v_pk_mul_f32 v[100:101], v[100:101], v[106:107]
	v_pk_mul_f32 v[94:95], v[94:95], v[168:169] op_sel_hi:[1,0]
; DI u32x2 pk4(f32x4 v) { u32x2 r; r.x = pk2(v[0], v[1]); r.y = pk2(v[2], v[3]); return r; }
; DI float silu_f(float x) { return x * __builtin_amdgcn_rcpf(1.f + __builtin_amdgcn_exp2f(-1.4426950409f * x)); }
; #define ROWS8 _Pragma("unroll") for (int ai = 0; ai < 2; ++ai) _Pragma("unroll") for (int m = 0; m < 4; ++m) if (ai == 0 || !hf)
;     DI void operator()(const Acc& acc, const Unit& u, int wr, int wc, int fr, int fq) const {
;     ...
;             ROWS8 { const int r = row0 + ai * HALF + m * 16; const float rs = rsv[ai][m];
;                 u32x4 w;
; #pragma unroll
;                 for (int bj = 0; bj < 2; ++bj) { const f32x4 g = acc[ai][bj][m][0] * rs, uu = acc[ai][bj][m][1] * rs;
;                     f32x4 a; a[0] = silu_f(g[0]) * uu[0]; a[1] = silu_f(g[1]) * uu[1]; a[2] = silu_f(g[2]) * uu[2]; a[3] = silu_f(g[3]) * uu[3];
;                     const u32x2 h = pk4(a); if (bj == 0) { w.x = h.x; w.y = h.y; } else { w.z = h.x; w.w = h.y; } }
;                 *(u32x4*)(WSB(OFF_ACT) + (size_t)r * DFF + ac0) = w;
	v_pk_mul_f32 v[92:93], v[92:93], v[100:101]
	v_pk_mul_f32 v[100:101], v[102:103], v[108:109]
	v_cvt_pk_bf16_f32 v106, v92, v93
	v_pk_mul_f32 v[94:95], v[94:95], v[100:101]
	v_mad_i64_i32 v[92:93], s[24:25], v156, s55, v[140:141]
	v_cvt_pk_bf16_f32 v107, v94, v95
	v_lshl_add_u64 v[92:93], v[92:93], 0, v[142:143]
	global_store_dwordx4 v[92:93], v[104:107], off
	v_pk_mul_f32 v[92:93], v[98:99], v[170:171] op_sel_hi:[1,0]
	v_pk_mul_f32 v[94:95], v[96:97], v[170:171] op_sel_hi:[1,0]
	v_mul_f32_e32 v98, 0xbfb8aa3b, v92
	v_mul_f32_e32 v96, 0xbfb8aa3b, v94
	v_mul_f32_e32 v97, 0xbfb8aa3b, v95
	v_mul_f32_e32 v99, 0xbfb8aa3b, v93
	v_exp_f32_e32 v96, v96
	v_exp_f32_e32 v97, v97
	v_exp_f32_e32 v98, v98
	v_exp_f32_e32 v99, v99
	v_add_f32_e32 v96, 1.0, v96
	v_add_f32_e32 v97, 1.0, v97
	v_add_f32_e32 v98, 1.0, v98
	v_add_f32_e32 v99, 1.0, v99
	v_rcp_f32_e32 v96, v96
	v_rcp_f32_e32 v97, v97
	v_rcp_f32_e32 v98, v98
	v_rcp_f32_e32 v99, v99
	v_pk_mul_f32 v[90:91], v[90:91], v[170:171] op_sel_hi:[1,0]
	v_pk_mul_f32 v[88:89], v[88:89], v[170:171] op_sel_hi:[1,0]
	v_pk_mul_f32 v[94:95], v[94:95], v[96:97]
	v_pk_mul_f32 v[92:93], v[92:93], v[98:99]
	v_pk_mul_f32 v[88:89], v[88:89], v[94:95]
	v_pk_mul_f32 v[90:91], v[90:91], v[92:93]
	v_pk_mul_f32 v[84:85], v[84:85], v[170:171] op_sel_hi:[1,0]
	v_cvt_pk_bf16_f32 v88, v88, v89
	v_cvt_pk_bf16_f32 v89, v90, v91
	v_pk_mul_f32 v[86:87], v[86:87], v[170:171] op_sel_hi:[1,0]
	v_mul_f32_e32 v90, 0xbfb8aa3b, v84
	v_mul_f32_e32 v91, 0xbfb8aa3b, v85
	v_exp_f32_e32 v90, v90
	v_exp_f32_e32 v91, v91
	v_mul_f32_e32 v92, 0xbfb8aa3b, v86
	v_mul_f32_e32 v93, 0xbfb8aa3b, v87
	v_exp_f32_e32 v92, v92
	v_exp_f32_e32 v93, v93
	v_add_f32_e32 v90, 1.0, v90
	v_add_f32_e32 v91, 1.0, v91
	v_rcp_f32_e32 v90, v90
	v_rcp_f32_e32 v91, v91
	v_add_f32_e32 v92, 1.0, v92
	v_add_f32_e32 v93, 1.0, v93
	v_rcp_f32_e32 v92, v92
	v_rcp_f32_e32 v93, v93
	v_fmamk_f32 v154, v154, 0x3a000000, v163
	v_rsq_f32_e32 v154, v154
	v_pk_mul_f32 v[76:77], v[76:77], v[170:171] op_sel_hi:[1,0]
	v_pk_mul_f32 v[84:85], v[84:85], v[90:91]
	v_pk_mul_f32 v[78:79], v[78:79], v[170:171] op_sel_hi:[1,0]
	v_pk_mul_f32 v[76:77], v[76:77], v[84:85]
	v_pk_mul_f32 v[84:85], v[86:87], v[92:93]
	v_cvt_pk_bf16_f32 v90, v76, v77
	v_pk_mul_f32 v[78:79], v[78:79], v[84:85]
	v_mad_i64_i32 v[76:77], s[24:25], v152, s55, v[140:141]
	v_cvt_pk_bf16_f32 v91, v78, v79
	v_lshl_add_u64 v[76:77], v[76:77], 0, v[142:143]
	global_store_dwordx4 v[76:77], v[88:91], off
	v_pk_mul_f32 v[76:77], v[82:83], v[154:155] op_sel_hi:[1,0]
	v_pk_mul_f32 v[78:79], v[80:81], v[154:155] op_sel_hi:[1,0]
	v_mul_f32_e32 v82, 0xbfb8aa3b, v76
	v_mul_f32_e32 v80, 0xbfb8aa3b, v78
	v_mul_f32_e32 v81, 0xbfb8aa3b, v79
	v_mul_f32_e32 v83, 0xbfb8aa3b, v77
	v_exp_f32_e32 v80, v80
	v_exp_f32_e32 v81, v81
	v_exp_f32_e32 v82, v82
	v_exp_f32_e32 v83, v83
	v_add_f32_e32 v80, 1.0, v80
	v_add_f32_e32 v81, 1.0, v81
	v_add_f32_e32 v82, 1.0, v82
	v_add_f32_e32 v83, 1.0, v83
	v_rcp_f32_e32 v80, v80
	v_rcp_f32_e32 v81, v81
	v_rcp_f32_e32 v82, v82
	v_rcp_f32_e32 v83, v83
	v_pk_mul_f32 v[74:75], v[74:75], v[154:155] op_sel_hi:[1,0]
	v_pk_mul_f32 v[72:73], v[72:73], v[154:155] op_sel_hi:[1,0]
	v_pk_mul_f32 v[78:79], v[78:79], v[80:81]
	v_pk_mul_f32 v[76:77], v[76:77], v[82:83]
	v_pk_mul_f32 v[72:73], v[72:73], v[78:79]
	v_pk_mul_f32 v[74:75], v[74:75], v[76:77]
	v_pk_mul_f32 v[68:69], v[68:69], v[154:155] op_sel_hi:[1,0]
	v_cvt_pk_bf16_f32 v72, v72, v73
	v_cvt_pk_bf16_f32 v73, v74, v75
	v_pk_mul_f32 v[70:71], v[70:71], v[154:155] op_sel_hi:[1,0]
	v_mul_f32_e32 v74, 0xbfb8aa3b, v68
	v_mul_f32_e32 v75, 0xbfb8aa3b, v69
	v_exp_f32_e32 v74, v74
	v_exp_f32_e32 v75, v75
	v_mul_f32_e32 v76, 0xbfb8aa3b, v70
	v_mul_f32_e32 v77, 0xbfb8aa3b, v71
	v_exp_f32_e32 v76, v76
	v_exp_f32_e32 v77, v77
	v_add_f32_e32 v74, 1.0, v74
	v_add_f32_e32 v75, 1.0, v75
	v_rcp_f32_e32 v74, v74
	v_rcp_f32_e32 v75, v75
	v_add_f32_e32 v76, 1.0, v76
	v_add_f32_e32 v77, 1.0, v77
	v_rcp_f32_e32 v76, v76
	v_rcp_f32_e32 v77, v77
	v_pk_mul_f32 v[64:65], v[64:65], v[154:155] op_sel_hi:[1,0]
	v_pk_mul_f32 v[68:69], v[68:69], v[74:75]
	v_pk_mul_f32 v[66:67], v[66:67], v[154:155] op_sel_hi:[1,0]
	v_pk_mul_f32 v[64:65], v[64:65], v[68:69]
	v_pk_mul_f32 v[68:69], v[70:71], v[76:77]
	v_cvt_pk_bf16_f32 v74, v64, v65
	v_pk_mul_f32 v[66:67], v[66:67], v[68:69]
	v_mad_i64_i32 v[64:65], s[24:25], v150, s55, v[140:141]
	v_cvt_pk_bf16_f32 v75, v66, v67
	v_fmamk_f32 v66, v139, 0x3a000000, v163
	v_rsq_f32_e32 v68, v66
	v_lshl_add_u64 v[64:65], v[64:65], 0, v[142:143]
	global_store_dwordx4 v[64:65], v[72:75], off
	v_fmamk_f32 v65, v147, 0x3a000000, v163
	v_rsq_f32_e32 v66, v65
	v_fmamk_f32 v65, v145, 0x3a000000, v163
	v_pk_mul_f32 v[60:61], v[60:61], v[68:69] op_sel_hi:[1,0]
	v_rsq_f32_e32 v70, v65
	v_mul_f32_e32 v65, 0xbfb8aa3b, v60
	v_exp_f32_e32 v65, v65
	v_mul_f32_e32 v67, 0xbfb8aa3b, v61
	v_exp_f32_e32 v67, v67
	v_pk_mul_f32 v[62:63], v[62:63], v[68:69] op_sel_hi:[1,0]
	v_add_f32_e32 v65, 1.0, v65
	v_rcp_f32_e32 v72, v65
	v_add_f32_e32 v65, 1.0, v67
	v_mul_f32_e32 v67, 0xbfb8aa3b, v62
	v_pk_mul_f32 v[58:59], v[58:59], v[68:69] op_sel_hi:[1,0]
	v_exp_f32_e32 v67, v67
	v_mul_f32_e32 v69, 0xbfb8aa3b, v63
	v_exp_f32_e32 v69, v69
	v_rcp_f32_e32 v73, v65
	v_add_f32_e32 v65, 1.0, v67
	v_rcp_f32_e32 v74, v65
	v_add_f32_e32 v65, 1.0, v69
	v_rcp_f32_e32 v75, v65
	v_pk_mul_f32 v[56:57], v[56:57], v[68:69] op_sel_hi:[1,0]
	v_pk_mul_f32 v[60:61], v[60:61], v[72:73]
	v_pk_mul_f32 v[52:53], v[52:53], v[68:69] op_sel_hi:[1,0]
	v_pk_mul_f32 v[56:57], v[56:57], v[60:61]
	v_pk_mul_f32 v[60:61], v[62:63], v[74:75]
	v_cvt_pk_bf16_f32 v56, v56, v57
	v_pk_mul_f32 v[58:59], v[58:59], v[60:61]
; DI u32x2 pk4(f32x4 v) { u32x2 r; r.x = pk2(v[0], v[1]); r.y = pk2(v[2], v[3]); return r; }
; DI float silu_f(float x) { return x * __builtin_amdgcn_rcpf(1.f + __builtin_amdgcn_exp2f(-1.4426950409f * x)); }
; #define ROWS8 _Pragma("unroll") for (int ai = 0; ai < 2; ++ai) _Pragma("unroll") for (int m = 0; m < 4; ++m) if (ai == 0 || !hf)
;     DI void operator()(const Acc& acc, const Unit& u, int wr, int wc, int fr, int fq) const {
;     ...
;             ROWS8 { const int r = row0 + ai * HALF + m * 16; const float rs = rsv[ai][m];
;                 u32x4 w;
; #pragma unroll
;                 for (int bj = 0; bj < 2; ++bj) { const f32x4 g = acc[ai][bj][m][0] * rs, uu = acc[ai][bj][m][1] * rs;
;                     f32x4 a; a[0] = silu_f(g[0]) * uu[0]; a[1] = silu_f(g[1]) * uu[1]; a[2] = silu_f(g[2]) * uu[2]; a[3] = silu_f(g[3]) * uu[3];
;                     const u32x2 h = pk4(a); if (bj == 0) { w.x = h.x; w.y = h.y; } else { w.z = h.x; w.w = h.y; } }
;                 *(u32x4*)(WSB(OFF_ACT) + (size_t)r * DFF + ac0) = w;
	v_pk_mul_f32 v[54:55], v[54:55], v[68:69] op_sel_hi:[1,0]
	v_cvt_pk_bf16_f32 v57, v58, v59
	v_mul_f32_e32 v58, 0xbfb8aa3b, v52
	v_mul_f32_e32 v59, 0xbfb8aa3b, v53
	v_exp_f32_e32 v58, v58
	v_exp_f32_e32 v59, v59
	v_mul_f32_e32 v60, 0xbfb8aa3b, v54
	v_mul_f32_e32 v61, 0xbfb8aa3b, v55
	v_exp_f32_e32 v60, v60
	v_exp_f32_e32 v61, v61
	v_add_f32_e32 v58, 1.0, v58
	v_add_f32_e32 v59, 1.0, v59
	v_rcp_f32_e32 v58, v58
	v_rcp_f32_e32 v59, v59
	v_add_f32_e32 v60, 1.0, v60
	v_add_f32_e32 v61, 1.0, v61
	v_rcp_f32_e32 v60, v60
	v_rcp_f32_e32 v61, v61
	v_pk_mul_f32 v[44:45], v[44:45], v[68:69] op_sel_hi:[1,0]
	v_pk_mul_f32 v[52:53], v[52:53], v[58:59]
	v_pk_mul_f32 v[46:47], v[46:47], v[68:69] op_sel_hi:[1,0]
	v_pk_mul_f32 v[44:45], v[44:45], v[52:53]
	v_pk_mul_f32 v[52:53], v[54:55], v[60:61]
	v_cvt_pk_bf16_f32 v58, v44, v45
	v_pk_mul_f32 v[46:47], v[46:47], v[52:53]
	v_mad_i64_i32 v[44:45], s[24:25], v148, s55, v[140:141]
	v_cvt_pk_bf16_f32 v59, v46, v47
	v_lshl_add_u64 v[44:45], v[44:45], 0, v[142:143]
	global_store_dwordx4 v[44:45], v[56:59], off
	v_pk_mul_f32 v[44:45], v[50:51], v[70:71] op_sel_hi:[1,0]
	v_pk_mul_f32 v[46:47], v[48:49], v[70:71] op_sel_hi:[1,0]
	v_mul_f32_e32 v50, 0xbfb8aa3b, v44
	v_mul_f32_e32 v48, 0xbfb8aa3b, v46
	v_mul_f32_e32 v49, 0xbfb8aa3b, v47
	v_mul_f32_e32 v51, 0xbfb8aa3b, v45
	v_exp_f32_e32 v48, v48
	v_exp_f32_e32 v49, v49
	v_exp_f32_e32 v50, v50
	v_exp_f32_e32 v51, v51
	v_add_f32_e32 v48, 1.0, v48
	v_add_f32_e32 v49, 1.0, v49
	v_add_f32_e32 v50, 1.0, v50
	v_add_f32_e32 v51, 1.0, v51
	v_rcp_f32_e32 v48, v48
	v_rcp_f32_e32 v49, v49
	v_rcp_f32_e32 v50, v50
	v_rcp_f32_e32 v51, v51
	v_pk_mul_f32 v[42:43], v[42:43], v[70:71] op_sel_hi:[1,0]
	v_pk_mul_f32 v[40:41], v[40:41], v[70:71] op_sel_hi:[1,0]
	v_pk_mul_f32 v[46:47], v[46:47], v[48:49]
	v_pk_mul_f32 v[44:45], v[44:45], v[50:51]
	v_pk_mul_f32 v[40:41], v[40:41], v[46:47]
	v_pk_mul_f32 v[42:43], v[42:43], v[44:45]
	v_pk_mul_f32 v[36:37], v[36:37], v[70:71] op_sel_hi:[1,0]
	v_cvt_pk_bf16_f32 v40, v40, v41
	v_cvt_pk_bf16_f32 v41, v42, v43
	v_pk_mul_f32 v[38:39], v[38:39], v[70:71] op_sel_hi:[1,0]
	v_mul_f32_e32 v42, 0xbfb8aa3b, v36
	v_mul_f32_e32 v43, 0xbfb8aa3b, v37
	v_exp_f32_e32 v42, v42
	v_exp_f32_e32 v43, v43
	v_mul_f32_e32 v44, 0xbfb8aa3b, v38
	v_mul_f32_e32 v45, 0xbfb8aa3b, v39
	v_exp_f32_e32 v44, v44
	v_exp_f32_e32 v45, v45
	v_add_f32_e32 v42, 1.0, v42
	v_add_f32_e32 v43, 1.0, v43
	v_rcp_f32_e32 v42, v42
	v_rcp_f32_e32 v43, v43
	v_add_f32_e32 v44, 1.0, v44
	v_add_f32_e32 v45, 1.0, v45
	v_rcp_f32_e32 v44, v44
	v_rcp_f32_e32 v45, v45
	v_pk_mul_f32 v[28:29], v[28:29], v[70:71] op_sel_hi:[1,0]
	v_pk_mul_f32 v[36:37], v[36:37], v[42:43]
	v_pk_mul_f32 v[30:31], v[30:31], v[70:71] op_sel_hi:[1,0]
	v_pk_mul_f32 v[28:29], v[28:29], v[36:37]
	v_pk_mul_f32 v[36:37], v[38:39], v[44:45]
	v_cvt_pk_bf16_f32 v42, v28, v29
	v_pk_mul_f32 v[30:31], v[30:31], v[36:37]
	v_mad_i64_i32 v[28:29], s[24:25], v146, s55, v[140:141]
	v_cvt_pk_bf16_f32 v43, v30, v31
	v_lshl_add_u64 v[28:29], v[28:29], 0, v[142:143]
	global_store_dwordx4 v[28:29], v[40:43], off
	v_pk_mul_f32 v[28:29], v[34:35], v[66:67] op_sel_hi:[1,0]
	v_pk_mul_f32 v[30:31], v[32:33], v[66:67] op_sel_hi:[1,0]
	v_mul_f32_e32 v34, 0xbfb8aa3b, v28
	v_mul_f32_e32 v32, 0xbfb8aa3b, v30
	v_mul_f32_e32 v33, 0xbfb8aa3b, v31
	v_mul_f32_e32 v35, 0xbfb8aa3b, v29
	v_exp_f32_e32 v32, v32
	v_exp_f32_e32 v33, v33
	v_exp_f32_e32 v34, v34
	v_exp_f32_e32 v35, v35
	v_add_f32_e32 v32, 1.0, v32
	v_add_f32_e32 v33, 1.0, v33
	v_add_f32_e32 v34, 1.0, v34
	v_add_f32_e32 v35, 1.0, v35
	v_rcp_f32_e32 v32, v32
	v_rcp_f32_e32 v33, v33
; DI u32x2 pk4(f32x4 v) { u32x2 r; r.x = pk2(v[0], v[1]); r.y = pk2(v[2], v[3]); return r; }
; DI float silu_f(float x) { return x * __builtin_amdgcn_rcpf(1.f + __builtin_amdgcn_exp2f(-1.4426950409f * x)); }
; #define PG8_WAIT_V(n) asm volatile("s_waitcnt vmcnt(" #n ")" ::: "memory")
; #define PG8_BAR __builtin_amdgcn_s_barrier()
; #define ROWS8 _Pragma("unroll") for (int ai = 0; ai < 2; ++ai) _Pragma("unroll") for (int m = 0; m < 4; ++m) if (ai == 0 || !hf)
; template <class Epi>
; DI void gemm_phase(LAS unsigned char* lds, int wid, int K, int lda, int ldb, bool bperm, const Sched3& S, const Epi& E) {
;     ...
;         E(acc, cur, wr, wc, fr, fq);
;         if (!has_next) break;
; #pragma unroll
;         for (int a = 0; a < 2; ++a)
; #pragma unroll
;             for (int b = 0; b < 2; ++b)
; #pragma unroll
;                 for (int m = 0; m < 4; ++m)
; #pragma unroll
;                     for (int n = 0; n < 2; ++n) acc[a][b][m][n] = (f32x4){0.f, 0.f, 0.f, 0.f};
;         cur = nxt; cA = nA; cB = nB; hA = nhA; ++ui;
;     }
;     PG8_WAIT_V(0);
;     if (wr == 0) PG8_BAR;
;     PG8_BAR;
;     DI void operator()(const Acc& acc, const Unit& u, int wr, int wc, int fr, int fq) const {
;     ...
;             ROWS8 { const int r = row0 + ai * HALF + m * 16; const float rs = rsv[ai][m];
;                 u32x4 w;
; #pragma unroll
;                 for (int bj = 0; bj < 2; ++bj) { const f32x4 g = acc[ai][bj][m][0] * rs, uu = acc[ai][bj][m][1] * rs;
;                     f32x4 a; a[0] = silu_f(g[0]) * uu[0]; a[1] = silu_f(g[1]) * uu[1]; a[2] = silu_f(g[2]) * uu[2]; a[3] = silu_f(g[3]) * uu[3];
;                     const u32x2 h = pk4(a); if (bj == 0) { w.x = h.x; w.y = h.y; } else { w.z = h.x; w.w = h.y; } }
;                 *(u32x4*)(WSB(OFF_ACT) + (size_t)r * DFF + ac0) = w;
	v_rcp_f32_e32 v34, v34
	v_rcp_f32_e32 v35, v35
	v_pk_mul_f32 v[26:27], v[26:27], v[66:67] op_sel_hi:[1,0]
	v_pk_mul_f32 v[24:25], v[24:25], v[66:67] op_sel_hi:[1,0]
	v_pk_mul_f32 v[30:31], v[30:31], v[32:33]
	v_pk_mul_f32 v[28:29], v[28:29], v[34:35]
	v_pk_mul_f32 v[24:25], v[24:25], v[30:31]
	v_pk_mul_f32 v[26:27], v[26:27], v[28:29]
	v_pk_mul_f32 v[20:21], v[20:21], v[66:67] op_sel_hi:[1,0]
	v_cvt_pk_bf16_f32 v24, v24, v25
	v_cvt_pk_bf16_f32 v25, v26, v27
	v_pk_mul_f32 v[22:23], v[22:23], v[66:67] op_sel_hi:[1,0]
	v_mul_f32_e32 v26, 0xbfb8aa3b, v20
	v_mul_f32_e32 v27, 0xbfb8aa3b, v21
	v_exp_f32_e32 v26, v26
	v_exp_f32_e32 v27, v27
	v_mul_f32_e32 v28, 0xbfb8aa3b, v22
	v_mul_f32_e32 v29, 0xbfb8aa3b, v23
	v_exp_f32_e32 v28, v28
	v_exp_f32_e32 v29, v29
	v_add_f32_e32 v26, 1.0, v26
	v_add_f32_e32 v27, 1.0, v27
	v_rcp_f32_e32 v26, v26
	v_rcp_f32_e32 v27, v27
	v_add_f32_e32 v28, 1.0, v28
	v_add_f32_e32 v29, 1.0, v29
	v_rcp_f32_e32 v28, v28
	v_rcp_f32_e32 v29, v29
	v_fmamk_f32 v64, v149, 0x3a000000, v163
	v_rsq_f32_e32 v64, v64
	v_pk_mul_f32 v[12:13], v[12:13], v[66:67] op_sel_hi:[1,0]
	v_pk_mul_f32 v[20:21], v[20:21], v[26:27]
	v_pk_mul_f32 v[14:15], v[14:15], v[66:67] op_sel_hi:[1,0]
	v_pk_mul_f32 v[12:13], v[12:13], v[20:21]
	v_pk_mul_f32 v[20:21], v[22:23], v[28:29]
	v_cvt_pk_bf16_f32 v26, v12, v13
	v_pk_mul_f32 v[14:15], v[14:15], v[20:21]
	v_mad_i64_i32 v[12:13], s[24:25], v144, s55, v[140:141]
	v_cvt_pk_bf16_f32 v27, v14, v15
	v_lshl_add_u64 v[12:13], v[12:13], 0, v[142:143]
	global_store_dwordx4 v[12:13], v[24:27], off
	v_pk_mul_f32 v[12:13], v[18:19], v[64:65] op_sel_hi:[1,0]
	v_pk_mul_f32 v[14:15], v[16:17], v[64:65] op_sel_hi:[1,0]
	v_mul_f32_e32 v18, 0xbfb8aa3b, v12
	v_mul_f32_e32 v16, 0xbfb8aa3b, v14
	v_mul_f32_e32 v17, 0xbfb8aa3b, v15
	v_mul_f32_e32 v19, 0xbfb8aa3b, v13
	v_exp_f32_e32 v16, v16
	v_exp_f32_e32 v17, v17
	v_exp_f32_e32 v18, v18
	v_exp_f32_e32 v19, v19
	v_add_f32_e32 v16, 1.0, v16
	v_add_f32_e32 v17, 1.0, v17
	v_add_f32_e32 v18, 1.0, v18
	v_add_f32_e32 v19, 1.0, v19
	v_rcp_f32_e32 v16, v16
	v_rcp_f32_e32 v17, v17
	v_rcp_f32_e32 v18, v18
	v_rcp_f32_e32 v19, v19
	v_pk_mul_f32 v[10:11], v[10:11], v[64:65] op_sel_hi:[1,0]
	v_pk_mul_f32 v[8:9], v[8:9], v[64:65] op_sel_hi:[1,0]
	v_pk_mul_f32 v[14:15], v[14:15], v[16:17]
	v_pk_mul_f32 v[12:13], v[12:13], v[18:19]
	v_pk_mul_f32 v[8:9], v[8:9], v[14:15]
	v_pk_mul_f32 v[10:11], v[10:11], v[12:13]
	v_pk_mul_f32 v[4:5], v[4:5], v[64:65] op_sel_hi:[1,0]
	v_cvt_pk_bf16_f32 v8, v8, v9
	v_cvt_pk_bf16_f32 v9, v10, v11
	v_pk_mul_f32 v[6:7], v[6:7], v[64:65] op_sel_hi:[1,0]
	v_mul_f32_e32 v10, 0xbfb8aa3b, v4
	v_mul_f32_e32 v11, 0xbfb8aa3b, v5
	v_exp_f32_e32 v10, v10
	v_exp_f32_e32 v11, v11
	v_mul_f32_e32 v12, 0xbfb8aa3b, v6
	v_mul_f32_e32 v13, 0xbfb8aa3b, v7
	v_exp_f32_e32 v12, v12
	v_exp_f32_e32 v13, v13
	v_add_f32_e32 v10, 1.0, v10
	v_add_f32_e32 v11, 1.0, v11
	v_rcp_f32_e32 v10, v10
	v_rcp_f32_e32 v11, v11
	v_add_f32_e32 v12, 1.0, v12
	v_add_f32_e32 v13, 1.0, v13
	v_rcp_f32_e32 v12, v12
	v_rcp_f32_e32 v13, v13
	v_pk_mul_f32 v[0:1], v[0:1], v[64:65] op_sel_hi:[1,0]
	v_pk_mul_f32 v[4:5], v[4:5], v[10:11]
	v_pk_mul_f32 v[2:3], v[2:3], v[64:65] op_sel_hi:[1,0]
	v_pk_mul_f32 v[0:1], v[0:1], v[4:5]
	v_pk_mul_f32 v[4:5], v[6:7], v[12:13]
	v_cvt_pk_bf16_f32 v10, v0, v1
	v_pk_mul_f32 v[2:3], v[2:3], v[4:5]
	v_mad_i64_i32 v[0:1], s[24:25], v138, s55, v[140:141]
	v_cvt_pk_bf16_f32 v11, v2, v3
	v_lshl_add_u64 v[0:1], v[0:1], 0, v[142:143]
	global_store_dwordx4 v[0:1], v[8:11], off
	s_cbranch_vccz .LBB0_702
	s_waitcnt vmcnt(0)
	s_cmpk_gt_u32 s88, 0xff
	s_cbranch_scc1 .LBB0_709
	s_barrier

; #define PG8_STAGE(bufoff, gbase, voff) do { _Pragma("unroll") for (int _i = 0; _i < 2; ++_i) \
;         __builtin_amdgcn_global_load_lds((const unsigned*)((const char*)(gbase) + (voff)[_i]), (LAS unsigned*)(lds + (bufoff) + ldsw + _i * 8192), 16, 0, 0); } while (0)
; #define PG8_LDA(dst, b, h) do { _Pragma("unroll") for (int m = 0; m < 4; ++m) _Pragma("unroll") for (int k = 0; k < 2; ++k) dst[m][k] = *(const LAS bf16x8*)(lds + PG8_SA(b, h) + aoff + m * 2048 + k * 1024); } while (0)
; #define PG8_LDB(dst, b, h) do { _Pragma("unroll") for (int n = 0; n < 2; ++n) _Pragma("unroll") for (int k = 0; k < 2; ++k) dst[n][k] = *(const LAS bf16x8*)(lds + PG8_SB(b, h) + boff + n * 2048 + k * 1024); } while (0)
; #define PG8_MMA(ai, bj, At, Bt) do { __builtin_amdgcn_s_setprio(1); _Pragma("unroll") for (int m = 0; m < 4; ++m) _Pragma("unroll") for (int n = 0; n < 2; ++n) _Pragma("unroll") for (int k = 0; k < 2; ++k) \
;         acc[ai][bj][m][n] = __builtin_amdgcn_mfma_f32_16x16x32_bf16(Bt[n][k], At[m][k], acc[ai][bj][m][n], 0, 0, 0); __builtin_amdgcn_s_setprio(0); } while (0)
; #define PG8_WAIT_L(n) asm volatile("s_waitcnt lgkmcnt(" #n ")" ::: "memory")
; #define PG8_BAR __builtin_amdgcn_s_barrier()
; #define PG8_SCHED __builtin_amdgcn_sched_barrier(0)
; template <class Epi>
; DI void gemm_phase(LAS unsigned char* lds, int wid, int K, int lda, int ldb, bool bperm, const Sched3& S, const Epi& E) {
;     ...
;             PG8_LDB(B0, 0, 0); PG8_SCHED; PG8_LDA(At, 0, 0); PG8_STAGE(PG8_SA(1, 1), a1 + hA, voffA);
;             PG8_WAIT_L(8); PG8_BAR; PG8_WAIT_L(0); PG8_MMA(0, 0, At, B0); PG8_BAR; PG8_SCHED;
;             PG8_LDB(B1, 0, 1); PG8_STAGE(PG8_SB(0, 0), b2, voffB);
;             PG8_BAR; PG8_WAIT_L(0); PG8_MMA(0, 1, At, B1); PG8_BAR;
;             PG8_LDA(At, 0, 1); PG8_STAGE(PG8_SA(0, 0), a2, voffA);
;             PG8_BAR; PG8_WAIT_L(0); if (full) PG8_MMA(1, 0, At, B0); PG8_BAR; PG8_SCHED;
.LBB0_784:
	s_add_u32 s60, s28, 0x100
	s_nop 0
	s_addc_u32 s61, s29, 0
	s_mov_b32 s62, -2
	s_waitcnt lgkmcnt(0)
	ds_read_b128 v[128:131], v185
	ds_read_b128 v[132:135], v185 offset:1024
	ds_read_b128 v[136:139], v185 offset:2048
	ds_read_b128 v[140:143], v185 offset:3072
	s_add_u32 s28, s26, 0x100
	s_addc_u32 s29, s27, 0
	s_cmpk_eq_i32 s62, 0x54
	s_cselect_b32 s37, s23, s29
	s_cselect_b32 s36, s22, s28
	s_cselect_b32 s31, s25, s61
	s_cselect_b32 s30, s24, s60
	v_lshl_add_u64 v[178:179], s[26:27], 0, v[156:157]
	s_add_i32 m0, s44, 0xc000
	ds_read_b128 v[144:147], v186
	ds_read_b128 v[148:151], v186 offset:1024
	ds_read_b128 v[162:165], v186 offset:2048
	ds_read_b128 v[166:169], v186 offset:3072
	ds_read_b128 v[170:173], v186 offset:4096
	ds_read_b128 v[174:177], v186 offset:5120
	ds_read_b128 v[188:191], v186 offset:6144
	ds_read_b128 v[192:195], v186 offset:7168
	global_load_lds_dwordx4 v[178:179], off
	v_lshl_add_u64 v[178:179], s[26:27], 0, v[158:159]
	s_add_i32 m0, s44, 0xe000
	s_nop 0
	global_load_lds_dwordx4 v[178:179], off
	s_waitcnt lgkmcnt(8)
	s_barrier
	s_waitcnt lgkmcnt(0)
	s_setprio 1
	s_waitcnt lgkmcnt(0)
	v_mfma_f32_16x16x32_bf16 v[124:127], v[128:131], v[144:147], 0
	v_mfma_f32_16x16x32_bf16 v[120:123], v[136:139], v[144:147], 0
	v_mfma_f32_16x16x32_bf16 v[108:111], v[128:131], v[162:165], 0
	v_mfma_f32_16x16x32_bf16 v[104:107], v[136:139], v[162:165], 0
	v_mfma_f32_16x16x32_bf16 v[92:95], v[128:131], v[170:173], 0
	v_mfma_f32_16x16x32_bf16 v[88:91], v[136:139], v[170:173], 0
	v_mfma_f32_16x16x32_bf16 v[76:79], v[128:131], v[188:191], 0
	v_mfma_f32_16x16x32_bf16 v[72:75], v[136:139], v[188:191], 0
	v_mfma_f32_16x16x32_bf16 v[124:127], v[132:135], v[148:151], v[124:127]
	v_mfma_f32_16x16x32_bf16 v[120:123], v[140:143], v[148:151], v[120:123]
	v_mfma_f32_16x16x32_bf16 v[108:111], v[132:135], v[166:169], v[108:111]
	v_mfma_f32_16x16x32_bf16 v[104:107], v[140:143], v[166:169], v[104:107]
	v_mfma_f32_16x16x32_bf16 v[92:95], v[132:135], v[174:177], v[92:95]
	v_mfma_f32_16x16x32_bf16 v[88:91], v[140:143], v[174:177], v[88:91]
	v_mfma_f32_16x16x32_bf16 v[76:79], v[132:135], v[192:195], v[76:79]
	v_mfma_f32_16x16x32_bf16 v[72:75], v[140:143], v[192:195], v[72:75]
	s_setprio 0
	s_barrier
	s_add_i32 s26, s53, s43
	v_lshl_add_u64 v[178:179], s[30:31], 0, v[152:153]
	s_mov_b32 m0, s26
	ds_read_b128 v[196:199], v187
	ds_read_b128 v[200:203], v187 offset:1024
	ds_read_b128 v[204:207], v187 offset:2048
	ds_read_b128 v[208:211], v187 offset:3072
	global_load_lds_dwordx4 v[178:179], off
	v_lshl_add_u64 v[212:213], s[30:31], 0, v[154:155]
	s_add_i32 m0, s26, 0x2000
	s_nop 0
	global_load_lds_dwordx4 v[212:213], off
	s_barrier
	s_waitcnt lgkmcnt(0)
	s_setprio 1
	s_waitcnt lgkmcnt(0)
	v_mfma_f32_16x16x32_bf16 v[116:119], v[196:199], v[144:147], 0
	v_mfma_f32_16x16x32_bf16 v[112:115], v[204:207], v[144:147], 0
	v_mfma_f32_16x16x32_bf16 v[100:103], v[196:199], v[162:165], 0
	v_mfma_f32_16x16x32_bf16 v[96:99], v[204:207], v[162:165], 0
	v_mfma_f32_16x16x32_bf16 v[84:87], v[196:199], v[170:173], 0
	v_mfma_f32_16x16x32_bf16 v[80:83], v[204:207], v[170:173], 0
	v_mfma_f32_16x16x32_bf16 v[68:71], v[196:199], v[188:191], 0
	v_mfma_f32_16x16x32_bf16 v[64:67], v[204:207], v[188:191], 0
	v_mfma_f32_16x16x32_bf16 v[116:119], v[200:203], v[148:151], v[116:119]
	v_mfma_f32_16x16x32_bf16 v[112:115], v[208:211], v[148:151], v[112:115]
	v_mfma_f32_16x16x32_bf16 v[100:103], v[200:203], v[166:169], v[100:103]
	v_mfma_f32_16x16x32_bf16 v[96:99], v[208:211], v[166:169], v[96:99]
	v_mfma_f32_16x16x32_bf16 v[84:87], v[200:203], v[174:177], v[84:87]
	v_mfma_f32_16x16x32_bf16 v[80:83], v[208:211], v[174:177], v[80:83]
	v_mfma_f32_16x16x32_bf16 v[68:71], v[200:203], v[192:195], v[68:71]
	v_mfma_f32_16x16x32_bf16 v[64:67], v[208:211], v[192:195], v[64:67]
	s_setprio 0
	s_mov_b32 m0, s44
	v_lshl_add_u64 v[214:215], s[36:37], 0, v[152:153]
	s_barrier
	ds_read_b128 v[144:147], v186 offset:16384
	ds_read_b128 v[148:151], v186 offset:17408
	ds_read_b128 v[162:165], v186 offset:18432
	ds_read_b128 v[166:169], v186 offset:19456
	ds_read_b128 v[170:173], v186 offset:20480
	ds_read_b128 v[174:177], v186 offset:21504
	ds_read_b128 v[188:191], v186 offset:22528
	ds_read_b128 v[192:195], v186 offset:23552
	global_load_lds_dwordx4 v[214:215], off
	v_lshl_add_u64 v[216:217], s[36:37], 0, v[154:155]
	s_mov_b32 m0, s45
	s_nop 0
	global_load_lds_dwordx4 v[216:217], off
	s_barrier
	s_waitcnt lgkmcnt(0)
	s_setprio 1
	s_waitcnt lgkmcnt(0)
	v_mfma_f32_16x16x32_bf16 v[60:63], v[128:131], v[144:147], 0
	v_mfma_f32_16x16x32_bf16 v[56:59], v[136:139], v[144:147], 0
	v_mfma_f32_16x16x32_bf16 v[44:47], v[128:131], v[162:165], 0
	v_mfma_f32_16x16x32_bf16 v[40:43], v[136:139], v[162:165], 0
	v_mfma_f32_16x16x32_bf16 v[28:31], v[128:131], v[170:173], 0
	v_mfma_f32_16x16x32_bf16 v[24:27], v[136:139], v[170:173], 0
	v_mfma_f32_16x16x32_bf16 v[12:15], v[128:131], v[188:191], 0
	v_mfma_f32_16x16x32_bf16 v[8:11], v[136:139], v[188:191], 0
	v_mfma_f32_16x16x32_bf16 v[60:63], v[132:135], v[148:151], v[60:63]
	v_mfma_f32_16x16x32_bf16 v[56:59], v[140:143], v[148:151], v[56:59]
	v_mfma_f32_16x16x32_bf16 v[44:47], v[132:135], v[166:169], v[44:47]
	v_mfma_f32_16x16x32_bf16 v[40:43], v[140:143], v[166:169], v[40:43]
	v_mfma_f32_16x16x32_bf16 v[28:31], v[132:135], v[174:177], v[28:31]
	v_mfma_f32_16x16x32_bf16 v[24:27], v[140:143], v[174:177], v[24:27]
	v_mfma_f32_16x16x32_bf16 v[12:15], v[132:135], v[192:195], v[12:15]
	v_mfma_f32_16x16x32_bf16 v[8:11], v[140:143], v[192:195], v[8:11]
	s_setprio 0
	s_barrier
; #define PG8_STAGE(bufoff, gbase, voff) do { _Pragma("unroll") for (int _i = 0; _i < 2; ++_i) \
;         __builtin_amdgcn_global_load_lds((const unsigned*)((const char*)(gbase) + (voff)[_i]), (LAS unsigned*)(lds + (bufoff) + ldsw + _i * 8192), 16, 0, 0); } while (0)
; #define PG8_LDA(dst, b, h) do { _Pragma("unroll") for (int m = 0; m < 4; ++m) _Pragma("unroll") for (int k = 0; k < 2; ++k) dst[m][k] = *(const LAS bf16x8*)(lds + PG8_SA(b, h) + aoff + m * 2048 + k * 1024); } while (0)
; #define PG8_LDB(dst, b, h) do { _Pragma("unroll") for (int n = 0; n < 2; ++n) _Pragma("unroll") for (int k = 0; k < 2; ++k) dst[n][k] = *(const LAS bf16x8*)(lds + PG8_SB(b, h) + boff + n * 2048 + k * 1024); } while (0)
; #define PG8_MMA(ai, bj, At, Bt) do { __builtin_amdgcn_s_setprio(1); _Pragma("unroll") for (int m = 0; m < 4; ++m) _Pragma("unroll") for (int n = 0; n < 2; ++n) _Pragma("unroll") for (int k = 0; k < 2; ++k) \
;         acc[ai][bj][m][n] = __builtin_amdgcn_mfma_f32_16x16x32_bf16(Bt[n][k], At[m][k], acc[ai][bj][m][n], 0, 0, 0); __builtin_amdgcn_s_setprio(0); } while (0)
; #define PG8_WAIT_V(n) asm volatile("s_waitcnt vmcnt(" #n ")" ::: "memory")
; #define PG8_WAIT_L(n) asm volatile("s_waitcnt lgkmcnt(" #n ")" ::: "memory")
; #define PG8_BAR __builtin_amdgcn_s_barrier()
; #define PG8_SCHED __builtin_amdgcn_sched_barrier(0)
; template <class Epi>
; DI void gemm_phase(LAS unsigned char* lds, int wid, int K, int lda, int ldb, bool bperm, const Sched3& S, const Epi& E) {
;     ...
;             PG8_STAGE(PG8_SB(0, 1), b2 + hstepB, voffB);
;             PG8_WAIT_V(6); PG8_BAR; if (full) PG8_MMA(1, 1, At, B1); PG8_BAR;
;             PG8_LDB(B0, 1, 0); PG8_SCHED; PG8_LDA(At, 1, 0); PG8_STAGE(PG8_SA(0, 1), a2 + h2, voffA);
;             PG8_WAIT_L(8); PG8_BAR; PG8_WAIT_L(0); PG8_MMA(0, 0, At, B0); PG8_BAR; PG8_SCHED;
;             PG8_LDB(B1, 1, 1); PG8_STAGE(PG8_SB(1, 0), b3, voffB);
;             PG8_BAR; PG8_WAIT_L(0); PG8_MMA(0, 1, At, B1); PG8_BAR;
	s_add_u32 s26, s30, 0x160000
	s_addc_u32 s27, s31, 0
	s_add_i32 s63, s54, s43
	v_lshl_add_u64 v[128:129], s[26:27], 0, v[152:153]
	s_mov_b32 m0, s63
	s_nop 0
	global_load_lds_dwordx4 v[128:129], off
	v_lshl_add_u64 v[128:129], s[26:27], 0, v[154:155]
	s_add_i32 m0, s63, 0x2000
	s_nop 0
	global_load_lds_dwordx4 v[128:129], off
	s_waitcnt vmcnt(6)
	s_barrier
	s_setprio 1
	v_mfma_f32_16x16x32_bf16 v[52:55], v[196:199], v[144:147], 0
	v_mfma_f32_16x16x32_bf16 v[48:51], v[204:207], v[144:147], 0
	v_mfma_f32_16x16x32_bf16 v[36:39], v[196:199], v[162:165], 0
	v_mfma_f32_16x16x32_bf16 v[32:35], v[204:207], v[162:165], 0
	v_mfma_f32_16x16x32_bf16 v[20:23], v[196:199], v[170:173], 0
	v_mfma_f32_16x16x32_bf16 v[16:19], v[204:207], v[170:173], 0
	v_mfma_f32_16x16x32_bf16 v[4:7], v[196:199], v[188:191], 0
	v_mfma_f32_16x16x32_bf16 v[0:3], v[204:207], v[188:191], 0
	v_mfma_f32_16x16x32_bf16 v[52:55], v[200:203], v[148:151], v[52:55]
	v_mfma_f32_16x16x32_bf16 v[48:51], v[208:211], v[148:151], v[48:51]
	v_mfma_f32_16x16x32_bf16 v[36:39], v[200:203], v[166:169], v[36:39]
	v_mfma_f32_16x16x32_bf16 v[32:35], v[208:211], v[166:169], v[32:35]
	v_mfma_f32_16x16x32_bf16 v[20:23], v[200:203], v[174:177], v[20:23]
	v_mfma_f32_16x16x32_bf16 v[16:19], v[208:211], v[174:177], v[16:19]
	v_mfma_f32_16x16x32_bf16 v[4:7], v[200:203], v[192:195], v[4:7]
	v_mfma_f32_16x16x32_bf16 v[0:3], v[208:211], v[192:195], v[0:3]
	s_setprio 0
	s_add_i32 s63, 0, 0x18000
	v_add_u32_e32 v140, s63, v181
	s_barrier
	ds_read_b128 v[128:131], v140
	ds_read_b128 v[132:135], v140 offset:1024
	ds_read_b128 v[136:139], v140 offset:2048
	ds_read_b128 v[140:143], v140 offset:3072
	s_add_u32 s26, s36, 0x160000
	s_addc_u32 s27, s37, 0
	s_mov_b32 m0, s46
	v_lshl_add_u64 v[196:197], s[26:27], 0, v[152:153]
	ds_read_b128 v[144:147], v186 offset:32768
	ds_read_b128 v[148:151], v186 offset:33792
	ds_read_b128 v[162:165], v186 offset:34816
	ds_read_b128 v[166:169], v186 offset:35840
	ds_read_b128 v[170:173], v186 offset:36864
	ds_read_b128 v[174:177], v186 offset:37888
	ds_read_b128 v[188:191], v186 offset:38912
	ds_read_b128 v[192:195], v186 offset:39936
	global_load_lds_dwordx4 v[196:197], off
	v_lshl_add_u64 v[196:197], s[26:27], 0, v[154:155]
	s_mov_b32 m0, s47
	s_nop 0
	global_load_lds_dwordx4 v[196:197], off
	s_waitcnt lgkmcnt(8)
	s_barrier
	s_waitcnt lgkmcnt(0)
	s_setprio 1
	s_waitcnt lgkmcnt(0)
	v_mfma_f32_16x16x32_bf16 v[124:127], v[128:131], v[144:147], v[124:127]
	v_mfma_f32_16x16x32_bf16 v[120:123], v[136:139], v[144:147], v[120:123]
	v_mfma_f32_16x16x32_bf16 v[108:111], v[128:131], v[162:165], v[108:111]
	v_mfma_f32_16x16x32_bf16 v[104:107], v[136:139], v[162:165], v[104:107]
	v_mfma_f32_16x16x32_bf16 v[92:95], v[128:131], v[170:173], v[92:95]
	v_mfma_f32_16x16x32_bf16 v[88:91], v[136:139], v[170:173], v[88:91]
	v_mfma_f32_16x16x32_bf16 v[76:79], v[128:131], v[188:191], v[76:79]
	v_mfma_f32_16x16x32_bf16 v[72:75], v[136:139], v[188:191], v[72:75]
	v_mfma_f32_16x16x32_bf16 v[124:127], v[132:135], v[148:151], v[124:127]
	v_mfma_f32_16x16x32_bf16 v[120:123], v[140:143], v[148:151], v[120:123]
	v_mfma_f32_16x16x32_bf16 v[108:111], v[132:135], v[166:169], v[108:111]
	v_mfma_f32_16x16x32_bf16 v[104:107], v[140:143], v[166:169], v[104:107]
	v_mfma_f32_16x16x32_bf16 v[92:95], v[132:135], v[174:177], v[92:95]
	v_mfma_f32_16x16x32_bf16 v[88:91], v[140:143], v[174:177], v[88:91]
	v_mfma_f32_16x16x32_bf16 v[76:79], v[132:135], v[192:195], v[76:79]
	v_mfma_f32_16x16x32_bf16 v[72:75], v[140:143], v[192:195], v[72:75]
	s_setprio 0
	s_barrier
	s_add_i32 s36, 0, 0x1c000
	s_add_i32 s26, s63, s43
	v_add_u32_e32 v208, s36, v181
	v_lshl_add_u64 v[178:179], v[178:179], 0, s[12:13]
	s_mov_b32 m0, s26
	ds_read_b128 v[196:199], v208
	ds_read_b128 v[200:203], v208 offset:1024
	ds_read_b128 v[204:207], v208 offset:2048
	ds_read_b128 v[208:211], v208 offset:3072
	global_load_lds_dwordx4 v[178:179], off
	v_lshl_add_u64 v[178:179], v[212:213], 0, s[12:13]
	s_add_i32 m0, s26, 0x2000
	s_nop 0
	global_load_lds_dwordx4 v[178:179], off
	s_barrier
; #define PG8_STAGE(bufoff, gbase, voff) do { _Pragma("unroll") for (int _i = 0; _i < 2; ++_i) \
;         __builtin_amdgcn_global_load_lds((const unsigned*)((const char*)(gbase) + (voff)[_i]), (LAS unsigned*)(lds + (bufoff) + ldsw + _i * 8192), 16, 0, 0); } while (0)
; #define PG8_LDA(dst, b, h) do { _Pragma("unroll") for (int m = 0; m < 4; ++m) _Pragma("unroll") for (int k = 0; k < 2; ++k) dst[m][k] = *(const LAS bf16x8*)(lds + PG8_SA(b, h) + aoff + m * 2048 + k * 1024); } while (0)
; #define PG8_MMA(ai, bj, At, Bt) do { __builtin_amdgcn_s_setprio(1); _Pragma("unroll") for (int m = 0; m < 4; ++m) _Pragma("unroll") for (int n = 0; n < 2; ++n) _Pragma("unroll") for (int k = 0; k < 2; ++k) \
;         acc[ai][bj][m][n] = __builtin_amdgcn_mfma_f32_16x16x32_bf16(Bt[n][k], At[m][k], acc[ai][bj][m][n], 0, 0, 0); __builtin_amdgcn_s_setprio(0); } while (0)
; #define PG8_WAIT_V(n) asm volatile("s_waitcnt vmcnt(" #n ")" ::: "memory")
; #define PG8_WAIT_L(n) asm volatile("s_waitcnt lgkmcnt(" #n ")" ::: "memory")
; #define PG8_BAR __builtin_amdgcn_s_barrier()
; #define PG8_SCHED __builtin_amdgcn_sched_barrier(0)
; template <class Epi>
; DI void gemm_phase(LAS unsigned char* lds, int wid, int K, int lda, int ldb, bool bperm, const Sched3& S, const Epi& E) {
;     ...
;             PG8_BAR; PG8_WAIT_L(0); PG8_MMA(0, 1, At, B1); PG8_BAR;
;             PG8_LDA(At, 1, 1); PG8_STAGE(PG8_SA(1, 0), a3, voffA);
;             PG8_BAR; PG8_WAIT_L(0); if (full) PG8_MMA(1, 0, At, B0); PG8_BAR; PG8_SCHED;
;             PG8_STAGE(PG8_SB(1, 1), b3 + hstepB, voffB);
;             PG8_WAIT_V(6); PG8_BAR; if (full) PG8_MMA(1, 1, At, B1); PG8_BAR;
;         }
	s_waitcnt lgkmcnt(0)
	s_setprio 1
	s_waitcnt lgkmcnt(0)
	v_mfma_f32_16x16x32_bf16 v[116:119], v[196:199], v[144:147], v[116:119]
	v_mfma_f32_16x16x32_bf16 v[112:115], v[204:207], v[144:147], v[112:115]
	v_mfma_f32_16x16x32_bf16 v[100:103], v[196:199], v[162:165], v[100:103]
	v_mfma_f32_16x16x32_bf16 v[96:99], v[204:207], v[162:165], v[96:99]
	v_mfma_f32_16x16x32_bf16 v[84:87], v[196:199], v[170:173], v[84:87]
	v_mfma_f32_16x16x32_bf16 v[80:83], v[204:207], v[170:173], v[80:83]
	v_mfma_f32_16x16x32_bf16 v[68:71], v[196:199], v[188:191], v[68:71]
	v_mfma_f32_16x16x32_bf16 v[64:67], v[204:207], v[188:191], v[64:67]
	v_mfma_f32_16x16x32_bf16 v[116:119], v[200:203], v[148:151], v[116:119]
	v_mfma_f32_16x16x32_bf16 v[112:115], v[208:211], v[148:151], v[112:115]
	v_mfma_f32_16x16x32_bf16 v[100:103], v[200:203], v[166:169], v[100:103]
	v_mfma_f32_16x16x32_bf16 v[96:99], v[208:211], v[166:169], v[96:99]
	v_mfma_f32_16x16x32_bf16 v[84:87], v[200:203], v[174:177], v[84:87]
	v_mfma_f32_16x16x32_bf16 v[80:83], v[208:211], v[174:177], v[80:83]
	v_mfma_f32_16x16x32_bf16 v[68:71], v[200:203], v[192:195], v[68:71]
	v_mfma_f32_16x16x32_bf16 v[64:67], v[208:211], v[192:195], v[64:67]
	s_setprio 0
	s_mov_b32 m0, s49
	v_lshl_add_u64 v[178:179], v[214:215], 0, s[12:13]
	s_barrier
	ds_read_b128 v[144:147], v186 offset:49152
	ds_read_b128 v[148:151], v186 offset:50176
	ds_read_b128 v[162:165], v186 offset:51200
	ds_read_b128 v[166:169], v186 offset:52224
	ds_read_b128 v[170:173], v186 offset:53248
	ds_read_b128 v[174:177], v186 offset:54272
	ds_read_b128 v[188:191], v186 offset:55296
	ds_read_b128 v[192:195], v186 offset:56320
	global_load_lds_dwordx4 v[178:179], off
	v_lshl_add_u64 v[178:179], v[216:217], 0, s[12:13]
	s_mov_b32 m0, s50
	s_nop 0
	global_load_lds_dwordx4 v[178:179], off
	s_barrier
	s_waitcnt lgkmcnt(0)
	s_setprio 1
	s_waitcnt lgkmcnt(0)
	v_mfma_f32_16x16x32_bf16 v[60:63], v[128:131], v[144:147], v[60:63]
	v_mfma_f32_16x16x32_bf16 v[56:59], v[136:139], v[144:147], v[56:59]
	v_mfma_f32_16x16x32_bf16 v[44:47], v[128:131], v[162:165], v[44:47]
	v_mfma_f32_16x16x32_bf16 v[40:43], v[136:139], v[162:165], v[40:43]
	v_mfma_f32_16x16x32_bf16 v[28:31], v[128:131], v[170:173], v[28:31]
	v_mfma_f32_16x16x32_bf16 v[24:27], v[136:139], v[170:173], v[24:27]
	v_mfma_f32_16x16x32_bf16 v[12:15], v[128:131], v[188:191], v[12:15]
	v_mfma_f32_16x16x32_bf16 v[8:11], v[136:139], v[188:191], v[8:11]
	v_mfma_f32_16x16x32_bf16 v[60:63], v[132:135], v[148:151], v[60:63]
	v_mfma_f32_16x16x32_bf16 v[56:59], v[140:143], v[148:151], v[56:59]
	v_mfma_f32_16x16x32_bf16 v[44:47], v[132:135], v[166:169], v[44:47]
	v_mfma_f32_16x16x32_bf16 v[40:43], v[140:143], v[166:169], v[40:43]
	v_mfma_f32_16x16x32_bf16 v[28:31], v[132:135], v[174:177], v[28:31]
	v_mfma_f32_16x16x32_bf16 v[24:27], v[140:143], v[174:177], v[24:27]
	v_mfma_f32_16x16x32_bf16 v[12:15], v[132:135], v[192:195], v[12:15]
	v_mfma_f32_16x16x32_bf16 v[8:11], v[140:143], v[192:195], v[8:11]
	s_setprio 0
	s_barrier
	s_add_u32 s26, s30, 0x160080
	s_addc_u32 s27, s31, 0
	s_add_i32 s30, s36, s43
	v_lshl_add_u64 v[128:129], s[26:27], 0, v[152:153]
	s_mov_b32 m0, s30
	s_nop 0
	global_load_lds_dwordx4 v[128:129], off
	v_lshl_add_u64 v[128:129], s[26:27], 0, v[154:155]
	s_add_i32 m0, s30, 0x2000
	s_nop 0
	global_load_lds_dwordx4 v[128:129], off
	s_waitcnt vmcnt(6)
	s_barrier
	s_setprio 1
	v_mfma_f32_16x16x32_bf16 v[52:55], v[196:199], v[144:147], v[52:55]
	v_mfma_f32_16x16x32_bf16 v[48:51], v[204:207], v[144:147], v[48:51]
	v_mfma_f32_16x16x32_bf16 v[36:39], v[196:199], v[162:165], v[36:39]
	v_mfma_f32_16x16x32_bf16 v[32:35], v[204:207], v[162:165], v[32:35]
	v_mfma_f32_16x16x32_bf16 v[20:23], v[196:199], v[170:173], v[20:23]
	v_mfma_f32_16x16x32_bf16 v[16:19], v[204:207], v[170:173], v[16:19]
	v_mfma_f32_16x16x32_bf16 v[4:7], v[196:199], v[188:191], v[4:7]
	v_mfma_f32_16x16x32_bf16 v[0:3], v[204:207], v[188:191], v[0:3]
	v_mfma_f32_16x16x32_bf16 v[52:55], v[200:203], v[148:151], v[52:55]
	v_mfma_f32_16x16x32_bf16 v[48:51], v[208:211], v[148:151], v[48:51]
	v_mfma_f32_16x16x32_bf16 v[36:39], v[200:203], v[166:169], v[36:39]
	v_mfma_f32_16x16x32_bf16 v[32:35], v[208:211], v[166:169], v[32:35]
	v_mfma_f32_16x16x32_bf16 v[20:23], v[200:203], v[174:177], v[20:23]
	v_mfma_f32_16x16x32_bf16 v[16:19], v[208:211], v[174:177], v[16:19]
	v_mfma_f32_16x16x32_bf16 v[4:7], v[200:203], v[192:195], v[4:7]
	v_mfma_f32_16x16x32_bf16 v[0:3], v[208:211], v[192:195], v[0:3]
	s_setprio 0
	s_add_i32 s62, s62, 2
	s_add_u32 s60, s60, 0x100
	s_addc_u32 s61, s61, 0
	s_cmpk_gt_u32 s62, 0x55
	s_mov_b64 s[26:27], s[28:29]
	s_barrier
	s_cbranch_scc0 .LBB0_785
	s_branch .Lpeel_3_exit

; DI u32x2 pk4(f32x4 v) { u32x2 r; r.x = pk2(v[0], v[1]); r.y = pk2(v[2], v[3]); return r; }
; DI float bf_lo(unsigned w) { return __uint_as_float(w << 16); }
; DI float bf_hi(unsigned w) { return __uint_as_float(w & 0xffff0000u); }
; #define COLS4 _Pragma("unroll") for (int bj = 0; bj < 2; ++bj) _Pragma("unroll") for (int n = 0; n < 2; ++n)
;     DI void operator()(const Acc& acc, const Unit& u, int wr, int wc, int fr, int fq) const {
;     ...
;                 for (int m = 0; m < 4; ++m) { const size_t o = (size_t)(row0 + ai * HALF + m * 16) * 2048 + colp;
;                     if (PH == 4) { COLS4 xo[m][bj][n] = *(const f32x4*)(p.x + o + bj * HALF + n * 4); }
;                     else {
; #pragma unroll
;                         for (int bj = 0; bj < 2; ++bj) { const u32x4 w = *(const u32x4*)(WSB(OFF_XB) + o + bj * HALF);
;                             xo[m][bj][0] = (f32x4){bf_lo(w.x), bf_hi(w.x), bf_lo(w.y), bf_hi(w.y)}; xo[m][bj][1] = (f32x4){bf_lo(w.z), bf_hi(w.z), bf_lo(w.w), bf_hi(w.w)}; } } }
; #pragma unroll
;                 for (int m = 0; m < 4; ++m) { const int r = row0 + ai * HALF + m * 16; const size_t o = (size_t)r * 2048 + colp; float part = 0.f;
; #pragma unroll
;                     for (int bj = 0; bj < 2; ++bj) { const f32x4 x0 = xo[m][bj][0] + acc[ai][bj][m][0], x1 = xo[m][bj][1] + acc[ai][bj][m][1];
;                         const u32x2 h0 = pk4(x0), h1 = pk4(x1);
;                         *(u32x4*)(WSB(OFF_XB) + o + bj * HALF) = (u32x4){h0.x, h0.y, h1.x, h1.y};
;                         part += x0[0] * x0[0] + x0[1] * x0[1] + x0[2] * x0[2] + x0[3] * x0[3] + x1[0] * x1[0] + x1[1] * x1[1] + x1[2] * x1[2] + x1[3] * x1[3]; }
;                     part += __shfl_xor(part, 16); part += __shfl_xor(part, 32);
;                     if (fq == 0) unsafeAtomicAdd(ssq + r, part);
.Lpeel_3_exit:
	v_lshl_add_u32 v128, s58, 8, v182
	v_lshl_add_u32 v166, s59, 8, v180
	v_ashrrev_i32_e32 v129, 31, v128
	v_lshlrev_b64 v[162:163], 1, v[128:129]
	v_ashrrev_i32_e32 v167, 31, v166
	v_lshl_add_u64 v[164:165], s[16:17], 0, v[162:163]
	v_lshlrev_b64 v[196:197], 12, v[166:167]
	v_lshl_add_u64 v[128:129], v[164:165], 0, v[196:197]
	global_load_dwordx4 v[188:191], v[128:129], off
	global_load_dwordx4 v[192:195], v[128:129], off offset:256
	v_or_b32_e32 v176, 16, v166
	v_or_b32_e32 v172, 32, v166
	v_or_b32_e32 v168, 48, v166
	v_ashrrev_i32_e32 v177, 31, v176
	v_ashrrev_i32_e32 v173, 31, v172
	v_ashrrev_i32_e32 v169, 31, v168
	v_lshlrev_b64 v[178:179], 12, v[176:177]
	v_lshlrev_b64 v[174:175], 12, v[172:173]
	v_lshlrev_b64 v[170:171], 12, v[168:169]
	v_lshl_add_u64 v[128:129], v[164:165], 0, v[178:179]
	v_lshl_add_u64 v[130:131], v[164:165], 0, v[174:175]
	v_lshl_add_u64 v[198:199], v[164:165], 0, v[170:171]
	global_load_dwordx4 v[148:151], v[128:129], off
	global_load_dwordx4 v[144:147], v[128:129], off offset:256
	global_load_dwordx4 v[140:143], v[130:131], off
	global_load_dwordx4 v[136:139], v[130:131], off offset:256
	global_load_dwordx4 v[132:135], v[198:199], off
	s_nop 0
	global_load_dwordx4 v[128:131], v[198:199], off offset:256
	v_lshl_add_u64 v[198:199], s[16:17], 0, v[196:197]
	v_lshl_add_u64 v[198:199], v[198:199], 0, v[162:163]
	v_lshl_add_u64 v[196:197], s[10:11], 0, v[196:197]
	v_lshl_add_u64 v[196:197], v[196:197], 0, v[162:163]
	s_waitcnt vmcnt(0)
	v_lshlrev_b32_e32 v200, 16, v188
	v_and_b32_e32 v201, 0xffff0000, v188
	v_lshlrev_b32_e32 v188, 16, v189
	v_and_b32_e32 v189, 0xffff0000, v189
	v_lshlrev_b32_e32 v204, 16, v192
	v_and_b32_e32 v205, 0xffff0000, v192
	v_lshlrev_b32_e32 v192, 16, v193
	v_and_b32_e32 v193, 0xffff0000, v193
	v_lshlrev_b32_e32 v206, 16, v194
	v_and_b32_e32 v207, 0xffff0000, v194
	v_pk_add_f32 v[126:127], v[126:127], v[188:189]
	v_pk_add_f32 v[124:125], v[124:125], v[200:201]
	v_pk_add_f32 v[188:189], v[116:117], v[204:205]
	v_pk_add_f32 v[118:119], v[118:119], v[192:193]
	v_pk_add_f32 v[192:193], v[112:113], v[206:207]
	v_cvt_pk_bf16_f32 v112, v124, v125
	v_mul_f32_e32 v117, v125, v125
	v_mul_f32_e32 v125, v189, v189
	v_fmac_f32_e32 v117, v124, v124
	v_fmac_f32_e32 v125, v188, v188
	v_lshlrev_b32_e32 v202, 16, v190
	v_and_b32_e32 v203, 0xffff0000, v190
	v_fmac_f32_e32 v117, v126, v126
	v_fmac_f32_e32 v125, v118, v118
	v_pk_add_f32 v[120:121], v[120:121], v[202:203]
	v_fmac_f32_e32 v117, v127, v127
	v_fmac_f32_e32 v125, v119, v119
	v_lshlrev_b32_e32 v190, 16, v191
	v_and_b32_e32 v191, 0xffff0000, v191
	v_lshlrev_b32_e32 v194, 16, v195
	v_and_b32_e32 v195, 0xffff0000, v195
	v_fmac_f32_e32 v117, v120, v120
	v_fmac_f32_e32 v125, v192, v192
	v_pk_add_f32 v[122:123], v[122:123], v[190:191]
	v_pk_add_f32 v[190:191], v[114:115], v[194:195]
	v_fmac_f32_e32 v117, v121, v121
	v_fmac_f32_e32 v125, v193, v193
	v_fmac_f32_e32 v117, v122, v122
	v_fmac_f32_e32 v125, v190, v190
	v_fmac_f32_e32 v117, v123, v123
	v_fmac_f32_e32 v125, v191, v191
	v_cvt_pk_bf16_f32 v114, v120, v121
	v_add_f32_e32 v120, v117, v125
	ds_bpermute_b32 v121, v183, v120
	v_cvt_pk_bf16_f32 v113, v126, v127
	v_cvt_pk_bf16_f32 v115, v122, v123
	global_store_dwordx4 v[198:199], v[112:115], off sc1
	v_cvt_pk_bf16_f32 v116, v188, v189
	v_cvt_pk_bf16_f32 v117, v118, v119
	s_waitcnt lgkmcnt(0)
	v_add_f32_e32 v112, v120, v121
	ds_bpermute_b32 v113, v184, v112
	v_add_co_u32_e32 v114, vcc, s55, v196
	v_cvt_pk_bf16_f32 v118, v192, v193
	v_cvt_pk_bf16_f32 v119, v190, v191
	v_addc_co_u32_e32 v115, vcc, 0, v197, vcc
	global_store_dwordx4 v[114:115], v[116:119], off offset:256 sc1
	s_and_saveexec_b64 s[22:23], s[2:3]
	s_cbranch_execz .LBB0_788
	s_waitcnt lgkmcnt(0)
	v_add_f32_e32 v114, v112, v113
	v_lshl_add_u64 v[112:113], v[166:167], 2, s[14:15]
	global_atomic_add_f32 v[112:113], v114, off

; #define PG8_STAGE(bufoff, gbase, voff) do { _Pragma("unroll") for (int _i = 0; _i < 2; ++_i) \
;         __builtin_amdgcn_global_load_lds((const unsigned*)((const char*)(gbase) + (voff)[_i]), (LAS unsigned*)(lds + (bufoff) + ldsw + _i * 8192), 16, 0, 0); } while (0)
; #define PG8_LDA(dst, b, h) do { _Pragma("unroll") for (int m = 0; m < 4; ++m) _Pragma("unroll") for (int k = 0; k < 2; ++k) dst[m][k] = *(const LAS bf16x8*)(lds + PG8_SA(b, h) + aoff + m * 2048 + k * 1024); } while (0)
; #define PG8_LDB(dst, b, h) do { _Pragma("unroll") for (int n = 0; n < 2; ++n) _Pragma("unroll") for (int k = 0; k < 2; ++k) dst[n][k] = *(const LAS bf16x8*)(lds + PG8_SB(b, h) + boff + n * 2048 + k * 1024); } while (0)
; #define PG8_MMA(ai, bj, At, Bt) do { __builtin_amdgcn_s_setprio(1); _Pragma("unroll") for (int m = 0; m < 4; ++m) _Pragma("unroll") for (int n = 0; n < 2; ++n) _Pragma("unroll") for (int k = 0; k < 2; ++k) \
;         acc[ai][bj][m][n] = __builtin_amdgcn_mfma_f32_16x16x32_bf16(Bt[n][k], At[m][k], acc[ai][bj][m][n], 0, 0, 0); __builtin_amdgcn_s_setprio(0); } while (0)
; #define PG8_WAIT_L(n) asm volatile("s_waitcnt lgkmcnt(" #n ")" ::: "memory")
; #define PG8_BAR __builtin_amdgcn_s_barrier()
; #define PG8_SCHED __builtin_amdgcn_sched_barrier(0)
; template <class Epi>
; DI void gemm_phase(LAS unsigned char* lds, int wid, int K, int lda, int ldb, bool bperm, const Sched3& S, const Epi& E) {
;     ...
;             PG8_LDB(B0, 0, 0); PG8_SCHED; PG8_LDA(At, 0, 0); PG8_STAGE(PG8_SA(1, 1), a1 + hA, voffA);
;             PG8_WAIT_L(8); PG8_BAR; PG8_WAIT_L(0); PG8_MMA(0, 0, At, B0); PG8_BAR; PG8_SCHED;
;             PG8_LDB(B1, 0, 1); PG8_STAGE(PG8_SB(0, 0), b2, voffB);
;             PG8_BAR; PG8_WAIT_L(0); PG8_MMA(0, 1, At, B1); PG8_BAR;
;             PG8_LDA(At, 0, 1); PG8_STAGE(PG8_SA(0, 0), a2, voffA);
;             PG8_BAR; PG8_WAIT_L(0); if (full) PG8_MMA(1, 0, At, B0); PG8_BAR; PG8_SCHED;
.LBB0_872:
	s_add_u32 s36, s36, 0x80080
	s_addc_u32 s37, s37, 0
	s_add_u32 s19, s38, 0x100
	s_nop 0
	s_addc_u32 s21, s39, 0
	s_mov_b32 s27, -2
	s_waitcnt lgkmcnt(0)
	ds_read_b128 v[128:131], v189
	ds_read_b128 v[132:135], v189 offset:1024
	ds_read_b128 v[136:139], v189 offset:2048
	ds_read_b128 v[140:143], v189 offset:3072
	s_add_u32 s38, s36, 0xfff80080
	s_addc_u32 s39, s37, -1
	s_cmp_eq_u32 s27, 28
	s_cselect_b32 s41, s29, s39
	s_cselect_b32 s40, s28, s38
	s_cselect_b32 s39, s31, s21
	s_cselect_b32 s38, s30, s19
	v_lshl_add_u64 v[168:169], s[36:37], 0, v[160:161]
	s_add_i32 m0, s48, 0xc000
	ds_read_b128 v[180:183], v195
	ds_read_b128 v[190:193], v195 offset:1024
	ds_read_b128 v[200:203], v195 offset:2048
	ds_read_b128 v[204:207], v195 offset:3072
	ds_read_b128 v[208:211], v195 offset:4096
	ds_read_b128 v[212:215], v195 offset:5120
	ds_read_b128 v[216:219], v195 offset:6144
	ds_read_b128 v[224:227], v195 offset:7168
	global_load_lds_dwordx4 v[168:169], off
	v_lshl_add_u64 v[168:169], s[36:37], 0, v[162:163]
	s_add_i32 m0, s48, 0xe000
	s_nop 0
	global_load_lds_dwordx4 v[168:169], off
	s_waitcnt lgkmcnt(8)
	s_barrier
	s_waitcnt lgkmcnt(0)
	s_setprio 1
	s_waitcnt lgkmcnt(0)
	v_mfma_f32_16x16x32_bf16 v[124:127], v[128:131], v[180:183], 0
	v_mfma_f32_16x16x32_bf16 v[120:123], v[136:139], v[180:183], 0
	v_mfma_f32_16x16x32_bf16 v[108:111], v[128:131], v[200:203], 0
	v_mfma_f32_16x16x32_bf16 v[104:107], v[136:139], v[200:203], 0
	v_mfma_f32_16x16x32_bf16 v[92:95], v[128:131], v[208:211], 0
	v_mfma_f32_16x16x32_bf16 v[88:91], v[136:139], v[208:211], 0
	v_mfma_f32_16x16x32_bf16 v[76:79], v[128:131], v[216:219], 0
	v_mfma_f32_16x16x32_bf16 v[72:75], v[136:139], v[216:219], 0
	v_mfma_f32_16x16x32_bf16 v[124:127], v[132:135], v[190:193], v[124:127]
	v_mfma_f32_16x16x32_bf16 v[120:123], v[140:143], v[190:193], v[120:123]
	v_mfma_f32_16x16x32_bf16 v[108:111], v[132:135], v[204:207], v[108:111]
	v_mfma_f32_16x16x32_bf16 v[104:107], v[140:143], v[204:207], v[104:107]
	v_mfma_f32_16x16x32_bf16 v[92:95], v[132:135], v[212:215], v[92:95]
	v_mfma_f32_16x16x32_bf16 v[88:91], v[140:143], v[212:215], v[88:91]
	v_mfma_f32_16x16x32_bf16 v[76:79], v[132:135], v[224:227], v[76:79]
	v_mfma_f32_16x16x32_bf16 v[72:75], v[140:143], v[224:227], v[72:75]
	s_setprio 0
	s_barrier
	s_add_i32 s64, s59, s47
	v_lshl_add_u64 v[168:169], s[38:39], 0, v[146:147]
	s_mov_b32 m0, s64
	ds_read_b128 v[228:231], v197
	ds_read_b128 v[232:235], v197 offset:1024
	ds_read_b128 v[236:239], v197 offset:2048
	ds_read_b128 v[240:243], v197 offset:3072
	global_load_lds_dwordx4 v[168:169], off
	v_lshl_add_u64 v[172:173], s[38:39], 0, v[150:151]
	s_add_i32 m0, s64, 0x2000
	s_nop 0
	global_load_lds_dwordx4 v[172:173], off
	s_barrier
	s_waitcnt lgkmcnt(0)
	s_setprio 1
	s_waitcnt lgkmcnt(0)
	v_mfma_f32_16x16x32_bf16 v[116:119], v[228:231], v[180:183], 0
	v_mfma_f32_16x16x32_bf16 v[112:115], v[236:239], v[180:183], 0
	v_mfma_f32_16x16x32_bf16 v[100:103], v[228:231], v[200:203], 0
	v_mfma_f32_16x16x32_bf16 v[96:99], v[236:239], v[200:203], 0
	v_mfma_f32_16x16x32_bf16 v[84:87], v[228:231], v[208:211], 0
	v_mfma_f32_16x16x32_bf16 v[80:83], v[236:239], v[208:211], 0
	v_mfma_f32_16x16x32_bf16 v[68:71], v[228:231], v[216:219], 0
	v_mfma_f32_16x16x32_bf16 v[64:67], v[236:239], v[216:219], 0
	v_mfma_f32_16x16x32_bf16 v[116:119], v[232:235], v[190:193], v[116:119]
	v_mfma_f32_16x16x32_bf16 v[112:115], v[240:243], v[190:193], v[112:115]
	v_mfma_f32_16x16x32_bf16 v[100:103], v[232:235], v[204:207], v[100:103]
	v_mfma_f32_16x16x32_bf16 v[96:99], v[240:243], v[204:207], v[96:99]
	v_mfma_f32_16x16x32_bf16 v[84:87], v[232:235], v[212:215], v[84:87]
	v_mfma_f32_16x16x32_bf16 v[80:83], v[240:243], v[212:215], v[80:83]
	v_mfma_f32_16x16x32_bf16 v[68:71], v[232:235], v[224:227], v[68:71]
	v_mfma_f32_16x16x32_bf16 v[64:67], v[240:243], v[224:227], v[64:67]
	s_setprio 0
	s_mov_b32 m0, s48
	v_lshl_add_u64 v[176:177], s[40:41], 0, v[144:145]
	s_barrier
	ds_read_b128 v[180:183], v195 offset:16384
	ds_read_b128 v[190:193], v195 offset:17408
	ds_read_b128 v[200:203], v195 offset:18432
	ds_read_b128 v[204:207], v195 offset:19456
	ds_read_b128 v[208:211], v195 offset:20480
	ds_read_b128 v[212:215], v195 offset:21504
	ds_read_b128 v[216:219], v195 offset:22528
	ds_read_b128 v[224:227], v195 offset:23552
	global_load_lds_dwordx4 v[176:177], off
	v_lshl_add_u64 v[186:187], s[40:41], 0, v[148:149]
	s_mov_b32 m0, s49
	s_nop 0
	global_load_lds_dwordx4 v[186:187], off
	s_barrier
	s_waitcnt lgkmcnt(0)
	s_setprio 1
	s_waitcnt lgkmcnt(0)
	v_mfma_f32_16x16x32_bf16 v[60:63], v[128:131], v[180:183], 0
	v_mfma_f32_16x16x32_bf16 v[56:59], v[136:139], v[180:183], 0
	v_mfma_f32_16x16x32_bf16 v[44:47], v[128:131], v[200:203], 0
	v_mfma_f32_16x16x32_bf16 v[40:43], v[136:139], v[200:203], 0
	v_mfma_f32_16x16x32_bf16 v[28:31], v[128:131], v[208:211], 0
	v_mfma_f32_16x16x32_bf16 v[24:27], v[136:139], v[208:211], 0
	v_mfma_f32_16x16x32_bf16 v[12:15], v[128:131], v[216:219], 0
	v_mfma_f32_16x16x32_bf16 v[8:11], v[136:139], v[216:219], 0
	v_mfma_f32_16x16x32_bf16 v[60:63], v[132:135], v[190:193], v[60:63]
	v_mfma_f32_16x16x32_bf16 v[56:59], v[140:143], v[190:193], v[56:59]
	v_mfma_f32_16x16x32_bf16 v[44:47], v[132:135], v[204:207], v[44:47]
	v_mfma_f32_16x16x32_bf16 v[40:43], v[140:143], v[204:207], v[40:43]
	v_mfma_f32_16x16x32_bf16 v[28:31], v[132:135], v[212:215], v[28:31]
	v_mfma_f32_16x16x32_bf16 v[24:27], v[140:143], v[212:215], v[24:27]
	v_mfma_f32_16x16x32_bf16 v[12:15], v[132:135], v[224:227], v[12:15]
	v_mfma_f32_16x16x32_bf16 v[8:11], v[140:143], v[224:227], v[8:11]
	s_setprio 0
	s_barrier
; #define PG8_STAGE(bufoff, gbase, voff) do { _Pragma("unroll") for (int _i = 0; _i < 2; ++_i) \
;         __builtin_amdgcn_global_load_lds((const unsigned*)((const char*)(gbase) + (voff)[_i]), (LAS unsigned*)(lds + (bufoff) + ldsw + _i * 8192), 16, 0, 0); } while (0)
; #define PG8_LDA(dst, b, h) do { _Pragma("unroll") for (int m = 0; m < 4; ++m) _Pragma("unroll") for (int k = 0; k < 2; ++k) dst[m][k] = *(const LAS bf16x8*)(lds + PG8_SA(b, h) + aoff + m * 2048 + k * 1024); } while (0)
; #define PG8_LDB(dst, b, h) do { _Pragma("unroll") for (int n = 0; n < 2; ++n) _Pragma("unroll") for (int k = 0; k < 2; ++k) dst[n][k] = *(const LAS bf16x8*)(lds + PG8_SB(b, h) + boff + n * 2048 + k * 1024); } while (0)
; #define PG8_MMA(ai, bj, At, Bt) do { __builtin_amdgcn_s_setprio(1); _Pragma("unroll") for (int m = 0; m < 4; ++m) _Pragma("unroll") for (int n = 0; n < 2; ++n) _Pragma("unroll") for (int k = 0; k < 2; ++k) \
;         acc[ai][bj][m][n] = __builtin_amdgcn_mfma_f32_16x16x32_bf16(Bt[n][k], At[m][k], acc[ai][bj][m][n], 0, 0, 0); __builtin_amdgcn_s_setprio(0); } while (0)
; #define PG8_WAIT_V(n) asm volatile("s_waitcnt vmcnt(" #n ")" ::: "memory")
; #define PG8_WAIT_L(n) asm volatile("s_waitcnt lgkmcnt(" #n ")" ::: "memory")
; #define PG8_BAR __builtin_amdgcn_s_barrier()
; #define PG8_SCHED __builtin_amdgcn_sched_barrier(0)
; template <class Epi>
; DI void gemm_phase(LAS unsigned char* lds, int wid, int K, int lda, int ldb, bool bperm, const Sched3& S, const Epi& E) {
;     ...
;             PG8_STAGE(PG8_SB(0, 1), b2 + hstepB, voffB);
;             PG8_WAIT_V(6); PG8_BAR; if (full) PG8_MMA(1, 1, At, B1); PG8_BAR;
;             PG8_LDB(B0, 1, 0); PG8_SCHED; PG8_LDA(At, 1, 0); PG8_STAGE(PG8_SA(0, 1), a2 + h2, voffA);
;             PG8_WAIT_L(8); PG8_BAR; PG8_WAIT_L(0); PG8_MMA(0, 0, At, B0); PG8_BAR; PG8_SCHED;
;             PG8_LDB(B1, 1, 1); PG8_STAGE(PG8_SB(1, 0), b3, voffB);
;             PG8_BAR; PG8_WAIT_L(0); PG8_MMA(0, 1, At, B1); PG8_BAR;
	s_add_u32 s64, s38, 0x80000
	s_addc_u32 s65, s39, 0
	s_add_i32 s66, s60, s47
	v_lshl_add_u64 v[128:129], s[64:65], 0, v[146:147]
	s_mov_b32 m0, s66
	s_nop 0
	global_load_lds_dwordx4 v[128:129], off
	v_lshl_add_u64 v[128:129], s[64:65], 0, v[150:151]
	s_add_i32 m0, s66, 0x2000
	s_nop 0
	global_load_lds_dwordx4 v[128:129], off
	s_waitcnt vmcnt(6)
	s_barrier
	s_setprio 1
	v_mfma_f32_16x16x32_bf16 v[52:55], v[228:231], v[180:183], 0
	v_mfma_f32_16x16x32_bf16 v[48:51], v[236:239], v[180:183], 0
	v_mfma_f32_16x16x32_bf16 v[36:39], v[228:231], v[200:203], 0
	v_mfma_f32_16x16x32_bf16 v[32:35], v[236:239], v[200:203], 0
	v_mfma_f32_16x16x32_bf16 v[20:23], v[228:231], v[208:211], 0
	v_mfma_f32_16x16x32_bf16 v[16:19], v[236:239], v[208:211], 0
	v_mfma_f32_16x16x32_bf16 v[4:7], v[228:231], v[216:219], 0
	v_mfma_f32_16x16x32_bf16 v[0:3], v[236:239], v[216:219], 0
	v_mfma_f32_16x16x32_bf16 v[52:55], v[232:235], v[190:193], v[52:55]
	v_mfma_f32_16x16x32_bf16 v[48:51], v[240:243], v[190:193], v[48:51]
	v_mfma_f32_16x16x32_bf16 v[36:39], v[232:235], v[204:207], v[36:39]
	v_mfma_f32_16x16x32_bf16 v[32:35], v[240:243], v[204:207], v[32:35]
	v_mfma_f32_16x16x32_bf16 v[20:23], v[232:235], v[212:215], v[20:23]
	v_mfma_f32_16x16x32_bf16 v[16:19], v[240:243], v[212:215], v[16:19]
	v_mfma_f32_16x16x32_bf16 v[4:7], v[232:235], v[224:227], v[4:7]
	v_mfma_f32_16x16x32_bf16 v[0:3], v[240:243], v[224:227], v[0:3]
	s_setprio 0
	s_add_i32 s64, 0, 0x18000
	v_add_u32_e32 v140, s64, v171
	s_barrier
	ds_read_b128 v[128:131], v140
	ds_read_b128 v[132:135], v140 offset:1024
	ds_read_b128 v[136:139], v140 offset:2048
	ds_read_b128 v[140:143], v140 offset:3072
	s_add_u32 s40, s40, 0x80000
	s_addc_u32 s41, s41, 0
	s_mov_b32 m0, s50
	v_lshl_add_u64 v[220:221], s[40:41], 0, v[144:145]
	ds_read_b128 v[180:183], v195 offset:32768
	ds_read_b128 v[190:193], v195 offset:33792
	ds_read_b128 v[200:203], v195 offset:34816
	ds_read_b128 v[204:207], v195 offset:35840
	ds_read_b128 v[208:211], v195 offset:36864
	ds_read_b128 v[212:215], v195 offset:37888
	ds_read_b128 v[216:219], v195 offset:38912
	ds_read_b128 v[224:227], v195 offset:39936
	global_load_lds_dwordx4 v[220:221], off
	v_lshl_add_u64 v[220:221], s[40:41], 0, v[148:149]
	s_mov_b32 m0, s51
	s_nop 0
	global_load_lds_dwordx4 v[220:221], off
	s_waitcnt lgkmcnt(8)
	s_barrier
	s_waitcnt lgkmcnt(0)
	s_setprio 1
	s_waitcnt lgkmcnt(0)
	v_mfma_f32_16x16x32_bf16 v[124:127], v[128:131], v[180:183], v[124:127]
	v_mfma_f32_16x16x32_bf16 v[120:123], v[136:139], v[180:183], v[120:123]
	v_mfma_f32_16x16x32_bf16 v[108:111], v[128:131], v[200:203], v[108:111]
	v_mfma_f32_16x16x32_bf16 v[104:107], v[136:139], v[200:203], v[104:107]
	v_mfma_f32_16x16x32_bf16 v[92:95], v[128:131], v[208:211], v[92:95]
	v_mfma_f32_16x16x32_bf16 v[88:91], v[136:139], v[208:211], v[88:91]
	v_mfma_f32_16x16x32_bf16 v[76:79], v[128:131], v[216:219], v[76:79]
	v_mfma_f32_16x16x32_bf16 v[72:75], v[136:139], v[216:219], v[72:75]
	v_mfma_f32_16x16x32_bf16 v[124:127], v[132:135], v[190:193], v[124:127]
	v_mfma_f32_16x16x32_bf16 v[120:123], v[140:143], v[190:193], v[120:123]
	v_mfma_f32_16x16x32_bf16 v[108:111], v[132:135], v[204:207], v[108:111]
	v_mfma_f32_16x16x32_bf16 v[104:107], v[140:143], v[204:207], v[104:107]
	v_mfma_f32_16x16x32_bf16 v[92:95], v[132:135], v[212:215], v[92:95]
	v_mfma_f32_16x16x32_bf16 v[88:91], v[140:143], v[212:215], v[88:91]
	v_mfma_f32_16x16x32_bf16 v[76:79], v[132:135], v[224:227], v[76:79]
	v_mfma_f32_16x16x32_bf16 v[72:75], v[140:143], v[224:227], v[72:75]
	s_setprio 0
	s_barrier
	s_add_i32 s40, 0, 0x1c000
	s_add_i32 s41, s64, s47
	v_add_u32_e32 v152, s40, v171
	v_lshl_add_u64 v[168:169], v[168:169], 0, s[12:13]
	s_mov_b32 m0, s41
	ds_read_b128 v[228:231], v152
	ds_read_b128 v[232:235], v152 offset:1024
	ds_read_b128 v[236:239], v152 offset:2048
	ds_read_b128 v[240:243], v152 offset:3072
	global_load_lds_dwordx4 v[168:169], off
	v_lshl_add_u64 v[168:169], v[172:173], 0, s[12:13]
	s_add_i32 m0, s41, 0x2000
	s_nop 0
	global_load_lds_dwordx4 v[168:169], off
	s_barrier
; #define PG8_STAGE(bufoff, gbase, voff) do { _Pragma("unroll") for (int _i = 0; _i < 2; ++_i) \
;         __builtin_amdgcn_global_load_lds((const unsigned*)((const char*)(gbase) + (voff)[_i]), (LAS unsigned*)(lds + (bufoff) + ldsw + _i * 8192), 16, 0, 0); } while (0)
; #define PG8_LDA(dst, b, h) do { _Pragma("unroll") for (int m = 0; m < 4; ++m) _Pragma("unroll") for (int k = 0; k < 2; ++k) dst[m][k] = *(const LAS bf16x8*)(lds + PG8_SA(b, h) + aoff + m * 2048 + k * 1024); } while (0)
; #define PG8_MMA(ai, bj, At, Bt) do { __builtin_amdgcn_s_setprio(1); _Pragma("unroll") for (int m = 0; m < 4; ++m) _Pragma("unroll") for (int n = 0; n < 2; ++n) _Pragma("unroll") for (int k = 0; k < 2; ++k) \
;         acc[ai][bj][m][n] = __builtin_amdgcn_mfma_f32_16x16x32_bf16(Bt[n][k], At[m][k], acc[ai][bj][m][n], 0, 0, 0); __builtin_amdgcn_s_setprio(0); } while (0)
; #define PG8_WAIT_V(n) asm volatile("s_waitcnt vmcnt(" #n ")" ::: "memory")
; #define PG8_WAIT_L(n) asm volatile("s_waitcnt lgkmcnt(" #n ")" ::: "memory")
; #define PG8_BAR __builtin_amdgcn_s_barrier()
; #define PG8_SCHED __builtin_amdgcn_sched_barrier(0)
; template <class Epi>
; DI void gemm_phase(LAS unsigned char* lds, int wid, int K, int lda, int ldb, bool bperm, const Sched3& S, const Epi& E) {
;     ...
;             PG8_BAR; PG8_WAIT_L(0); PG8_MMA(0, 1, At, B1); PG8_BAR;
;             PG8_LDA(At, 1, 1); PG8_STAGE(PG8_SA(1, 0), a3, voffA);
;             PG8_BAR; PG8_WAIT_L(0); if (full) PG8_MMA(1, 0, At, B0); PG8_BAR; PG8_SCHED;
;             PG8_STAGE(PG8_SB(1, 1), b3 + hstepB, voffB);
;             PG8_WAIT_V(6); PG8_BAR; if (full) PG8_MMA(1, 1, At, B1); PG8_BAR;
;         }
	s_waitcnt lgkmcnt(0)
	s_setprio 1
	s_waitcnt lgkmcnt(0)
	v_mfma_f32_16x16x32_bf16 v[116:119], v[228:231], v[180:183], v[116:119]
	v_mfma_f32_16x16x32_bf16 v[112:115], v[236:239], v[180:183], v[112:115]
	v_mfma_f32_16x16x32_bf16 v[100:103], v[228:231], v[200:203], v[100:103]
	v_mfma_f32_16x16x32_bf16 v[96:99], v[236:239], v[200:203], v[96:99]
	v_mfma_f32_16x16x32_bf16 v[84:87], v[228:231], v[208:211], v[84:87]
	v_mfma_f32_16x16x32_bf16 v[80:83], v[236:239], v[208:211], v[80:83]
	v_mfma_f32_16x16x32_bf16 v[68:71], v[228:231], v[216:219], v[68:71]
	v_mfma_f32_16x16x32_bf16 v[64:67], v[236:239], v[216:219], v[64:67]
	v_mfma_f32_16x16x32_bf16 v[116:119], v[232:235], v[190:193], v[116:119]
	v_mfma_f32_16x16x32_bf16 v[112:115], v[240:243], v[190:193], v[112:115]
	v_mfma_f32_16x16x32_bf16 v[100:103], v[232:235], v[204:207], v[100:103]
	v_mfma_f32_16x16x32_bf16 v[96:99], v[240:243], v[204:207], v[96:99]
	v_mfma_f32_16x16x32_bf16 v[84:87], v[232:235], v[212:215], v[84:87]
	v_mfma_f32_16x16x32_bf16 v[80:83], v[240:243], v[212:215], v[80:83]
	v_mfma_f32_16x16x32_bf16 v[68:71], v[232:235], v[224:227], v[68:71]
	v_mfma_f32_16x16x32_bf16 v[64:67], v[240:243], v[224:227], v[64:67]
	s_setprio 0
	s_mov_b32 m0, s53
	v_lshl_add_u64 v[168:169], v[176:177], 0, s[12:13]
	s_barrier
	ds_read_b128 v[180:183], v195 offset:49152
	ds_read_b128 v[190:193], v195 offset:50176
	ds_read_b128 v[200:203], v195 offset:51200
	ds_read_b128 v[204:207], v195 offset:52224
	ds_read_b128 v[208:211], v195 offset:53248
	ds_read_b128 v[212:215], v195 offset:54272
	ds_read_b128 v[216:219], v195 offset:55296
	ds_read_b128 v[224:227], v195 offset:56320
	global_load_lds_dwordx4 v[168:169], off
	v_lshl_add_u64 v[168:169], v[186:187], 0, s[12:13]
	s_mov_b32 m0, s54
	s_nop 0
	global_load_lds_dwordx4 v[168:169], off
	s_barrier
	s_waitcnt lgkmcnt(0)
	s_setprio 1
	s_waitcnt lgkmcnt(0)
	v_mfma_f32_16x16x32_bf16 v[60:63], v[128:131], v[180:183], v[60:63]
	v_mfma_f32_16x16x32_bf16 v[56:59], v[136:139], v[180:183], v[56:59]
	v_mfma_f32_16x16x32_bf16 v[44:47], v[128:131], v[200:203], v[44:47]
	v_mfma_f32_16x16x32_bf16 v[40:43], v[136:139], v[200:203], v[40:43]
	v_mfma_f32_16x16x32_bf16 v[28:31], v[128:131], v[208:211], v[28:31]
	v_mfma_f32_16x16x32_bf16 v[24:27], v[136:139], v[208:211], v[24:27]
	v_mfma_f32_16x16x32_bf16 v[12:15], v[128:131], v[216:219], v[12:15]
	v_mfma_f32_16x16x32_bf16 v[8:11], v[136:139], v[216:219], v[8:11]
	v_mfma_f32_16x16x32_bf16 v[60:63], v[132:135], v[190:193], v[60:63]
	v_mfma_f32_16x16x32_bf16 v[56:59], v[140:143], v[190:193], v[56:59]
	v_mfma_f32_16x16x32_bf16 v[44:47], v[132:135], v[204:207], v[44:47]
	v_mfma_f32_16x16x32_bf16 v[40:43], v[140:143], v[204:207], v[40:43]
	v_mfma_f32_16x16x32_bf16 v[28:31], v[132:135], v[212:215], v[28:31]
	v_mfma_f32_16x16x32_bf16 v[24:27], v[140:143], v[212:215], v[24:27]
	v_mfma_f32_16x16x32_bf16 v[12:15], v[132:135], v[224:227], v[12:15]
	v_mfma_f32_16x16x32_bf16 v[8:11], v[140:143], v[224:227], v[8:11]
	s_setprio 0
	s_barrier
	s_add_u32 s38, s38, 0x80080
	s_addc_u32 s39, s39, 0
	s_add_i32 s40, s40, s47
	v_lshl_add_u64 v[128:129], s[38:39], 0, v[146:147]
	s_mov_b32 m0, s40
	s_nop 0
	global_load_lds_dwordx4 v[128:129], off
	v_lshl_add_u64 v[128:129], s[38:39], 0, v[150:151]
	s_add_i32 m0, s40, 0x2000
	s_nop 0
	global_load_lds_dwordx4 v[128:129], off
	s_waitcnt vmcnt(6)
	s_barrier
	s_setprio 1
	v_mfma_f32_16x16x32_bf16 v[52:55], v[228:231], v[180:183], v[52:55]
	v_mfma_f32_16x16x32_bf16 v[48:51], v[236:239], v[180:183], v[48:51]
	v_mfma_f32_16x16x32_bf16 v[36:39], v[228:231], v[200:203], v[36:39]
	v_mfma_f32_16x16x32_bf16 v[32:35], v[236:239], v[200:203], v[32:35]
	v_mfma_f32_16x16x32_bf16 v[20:23], v[228:231], v[208:211], v[20:23]
	v_mfma_f32_16x16x32_bf16 v[16:19], v[236:239], v[208:211], v[16:19]
	v_mfma_f32_16x16x32_bf16 v[4:7], v[228:231], v[216:219], v[4:7]
	v_mfma_f32_16x16x32_bf16 v[0:3], v[236:239], v[216:219], v[0:3]
	v_mfma_f32_16x16x32_bf16 v[52:55], v[232:235], v[190:193], v[52:55]
	v_mfma_f32_16x16x32_bf16 v[48:51], v[240:243], v[190:193], v[48:51]
	v_mfma_f32_16x16x32_bf16 v[36:39], v[232:235], v[204:207], v[36:39]
	v_mfma_f32_16x16x32_bf16 v[32:35], v[240:243], v[204:207], v[32:35]
	v_mfma_f32_16x16x32_bf16 v[20:23], v[232:235], v[212:215], v[20:23]
	v_mfma_f32_16x16x32_bf16 v[16:19], v[240:243], v[212:215], v[16:19]
	v_mfma_f32_16x16x32_bf16 v[4:7], v[232:235], v[224:227], v[4:7]
	v_mfma_f32_16x16x32_bf16 v[0:3], v[240:243], v[224:227], v[0:3]
	s_setprio 0
	s_add_i32 s27, s27, 2
	s_add_u32 s36, s36, 0x100
	s_addc_u32 s37, s37, 0
	s_add_u32 s19, s19, 0x100
	s_addc_u32 s21, s21, 0
	s_cmp_gt_u32 s27, 29
	s_barrier
	s_cbranch_scc0 .LBB0_873
	s_branch .Lpeel_4_exit

; DI u32x2 pk4(f32x4 v) { u32x2 r; r.x = pk2(v[0], v[1]); r.y = pk2(v[2], v[3]); return r; }
; #define ROWS8 _Pragma("unroll") for (int ai = 0; ai < 2; ++ai) _Pragma("unroll") for (int m = 0; m < 4; ++m) if (ai == 0 || !hf)
; #define LOAD_ROW_RS(rsv, ssqp, invn) float rsv[2][4]; ROWS8_ALL rsv[ai][m] = (ssqp)[row0 + ai * HALF + m * 16]; ROWS8_ALL rsv[ai][m] = rstd_of(rsv[ai][m], invn)
;     DI void operator()(const Acc& acc, const Unit& u, int wr, int wc, int fr, int fq) const {
;     ...
;             LOAD_ROW_RS(rsv, SSQ(3), 1.f / 2048.f);
;             if (u.pn < 4) {
;                 bf16_t* dbase = (u.pn < 2) ? WSB(OFF_CQ) : WSB(OFF_CKV); float* sdst = (u.pn < 2) ? SSQ(4 + sqo) : SSQ(5 + sqo);
;                 const int cb = (u.pn & 1) * 256 + wc * 32 + 8 * fq;
;                 ROWS8 { const int r = row0 + ai * HALF + m * 16; const float rs = rsv[ai][m]; float part = 0.f;
;                     bf16_t* dst = dbase + (size_t)r * 512 + cb;
; #pragma unroll
;                     for (int bj = 0; bj < 2; ++bj) { const f32x4 v0 = acc[ai][bj][m][0] * rs, v1 = acc[ai][bj][m][1] * rs; *(u32x4*)(dst + bj * HALF) = PK8(v0, v1);
;                         part += v0[0] * v0[0] + v0[1] * v0[1] + v0[2] * v0[2] + v0[3] * v0[3] + v1[0] * v1[0] + v1[1] * v1[1] + v1[2] * v1[2] + v1[3] * v1[3]; }
;                     part += __shfl_xor(part, 16); part += __shfl_xor(part, 32);
;                     if (fq == 0) unsafeAtomicAdd(sdst + r, part);
;                 }
;             } else if (wc < 2) {
;                 const int j0 = 16 * wc + 4 * fq; const float* cs = WSF(OFF_CS);
; #pragma unroll
;                 for (int ai = 0; ai < 2; ++ai) if (ai == 0 || !hf) {
;                     f32x4 c4[4], s4[4];
; #pragma unroll
;                     for (int m = 0; m < 4; ++m) { const int pos = (row0 + ai * HALF + m * 16) & (SEQ - 1); c4[m] = *(const f32x4*)(cs + pos * 32 + j0); s4[m] = *(const f32x4*)(cs + 4096 * 32 + pos * 32 + j0); }
; #pragma unroll
;                     for (int m = 0; m < 4; ++m) { const int r = row0 + ai * HALF + m * 16; const float rs = rsv[ai][m];
;                         const f32x4 x1 = acc[ai][0][m][0] * rs, x2 = acc[ai][0][m][1] * rs;
;                         bf16_t* dst = WSB(OFF_KR) + (size_t)r * 64 + j0;
;                         *(u32x2*)(dst) = pk4(x1 * c4[m] - x2 * s4[m]); *(u32x2*)(dst + 32) = pk4(x2 * c4[m] + x1 * s4[m]); }
.Lpeel_4_exit:
	v_lshl_add_u32 v192, s26, 8, v167
	v_or_b32_e32 v190, 16, v192
	v_or_b32_e32 v186, 32, v192
	v_ashrrev_i32_e32 v193, 31, v192
	v_ashrrev_i32_e32 v191, 31, v190
	v_ashrrev_i32_e32 v187, 31, v186
	v_or_b32_e32 v182, 48, v192
	v_lshl_add_u64 v[128:129], v[192:193], 2, s[16:17]
	v_lshl_add_u64 v[130:131], v[190:191], 2, s[16:17]
	v_lshl_add_u64 v[132:133], v[186:187], 2, s[16:17]
	v_ashrrev_i32_e32 v183, 31, v182
	global_load_dword v136, v[128:129], off
	global_load_dword v137, v[128:129], off offset:512
	global_load_dword v138, v[128:129], off offset:576
	global_load_dword v139, v[128:129], off offset:640
	v_lshl_add_u64 v[134:135], v[182:183], 2, s[16:17]
	global_load_dword v130, v[130:131], off
	s_nop 0
	global_load_dword v131, v[132:133], off
	s_nop 0
	global_load_dword v132, v[134:135], off
	s_nop 0
	global_load_dword v128, v[128:129], off offset:704
	v_add_u32_e32 v180, 0x80, v192
	v_add_u32_e32 v176, 0x90, v192
	v_add_u32_e32 v172, 0xa0, v192
	v_add_u32_e32 v168, 0xb0, v192
	v_ashrrev_i32_e32 v181, 31, v180
	v_ashrrev_i32_e32 v177, 31, v176
	v_ashrrev_i32_e32 v173, 31, v172
	v_ashrrev_i32_e32 v169, 31, v168
	s_cmp_gt_i32 s63, 3
	s_mov_b64 s[26:27], -1
	s_waitcnt vmcnt(0)
	v_fmamk_f32 v129, v136, 0x3a000000, v198
	v_fmamk_f32 v133, v137, 0x3a000000, v198
	v_fmamk_f32 v134, v138, 0x3a000000, v198
	v_fmamk_f32 v135, v139, 0x3a000000, v198
	v_rsq_f32_e32 v196, v129
	v_fmamk_f32 v129, v130, 0x3a000000, v198
	v_fmamk_f32 v130, v131, 0x3a000000, v198
	v_fmamk_f32 v131, v132, 0x3a000000, v198
	v_fmamk_f32 v128, v128, 0x3a000000, v198
	v_rsq_f32_e32 v178, v133
	v_rsq_f32_e32 v174, v134
	v_rsq_f32_e32 v170, v135
	v_rsq_f32_e32 v194, v129
	v_rsq_f32_e32 v188, v130
	v_rsq_f32_e32 v184, v131
	v_rsq_f32_e32 v166, v128
	s_cbranch_scc0 .LBB0_878
	s_andn2_b64 vcc, exec, s[14:15]
	s_cbranch_vccnz .LBB0_877
	v_lshlrev_b32_e32 v128, 7, v192
	v_and_b32_e32 v152, 0x7e780, v128
	v_lshl_add_u64 v[128:129], v[154:155], 0, v[152:153]
	global_load_dwordx4 v[136:139], v[128:129], off
	v_lshl_add_u64 v[130:131], v[156:157], 0, v[152:153]
	global_load_dwordx4 v[140:143], v[130:131], off
	global_load_dwordx4 v[200:203], v[128:129], off offset:2048
	global_load_dwordx4 v[204:207], v[130:131], off offset:2048
	v_or_b32_e32 v128, 0x1000, v152
	v_mov_b32_e32 v129, v153
	v_lshl_add_u64 v[130:131], v[154:155], 0, v[128:129]
	v_lshl_add_u64 v[128:129], v[156:157], 0, v[128:129]
	global_load_dwordx4 v[208:211], v[130:131], off
	global_load_dwordx4 v[212:215], v[128:129], off
	v_or_b32_e32 v152, 0x1800, v152
	v_lshl_add_u64 v[128:129], v[154:155], 0, v[152:153]
	v_lshl_add_u64 v[132:133], v[156:157], 0, v[152:153]
	global_load_dwordx4 v[128:131], v[128:129], off
	v_pk_mul_f32 v[216:217], v[126:127], v[196:197] op_sel_hi:[1,0]
	global_load_dwordx4 v[132:135], v[132:133], off
	v_pk_mul_f32 v[218:219], v[124:125], v[196:197] op_sel_hi:[1,0]
	v_pk_mul_f32 v[220:221], v[122:123], v[196:197] op_sel_hi:[1,0]
	v_pk_mul_f32 v[222:223], v[120:121], v[196:197] op_sel_hi:[1,0]
	v_lshlrev_b64 v[224:225], 7, v[192:193]
	v_lshl_add_u64 v[224:225], v[158:159], 0, v[224:225]
	s_waitcnt vmcnt(0)
	v_pk_mul_f32 v[226:227], v[220:221], v[142:143]
	v_pk_mul_f32 v[228:229], v[222:223], v[140:141]
	v_pk_mul_f32 v[142:143], v[216:217], v[142:143]
	v_pk_mul_f32 v[140:141], v[218:219], v[140:141]
	v_pk_fma_f32 v[226:227], v[216:217], v[138:139], v[226:227] neg_lo:[0,0,1] neg_hi:[0,0,1]
	v_pk_fma_f32 v[228:229], v[218:219], v[136:137], v[228:229] neg_lo:[0,0,1] neg_hi:[0,0,1]
	v_pk_fma_f32 v[138:139], v[220:221], v[138:139], v[142:143]
	v_pk_fma_f32 v[136:137], v[222:223], v[136:137], v[140:141]
	v_pk_mul_f32 v[140:141], v[106:107], v[194:195] op_sel_hi:[1,0]
	v_cvt_pk_bf16_f32 v136, v136, v137
	v_cvt_pk_bf16_f32 v137, v138, v139
	v_pk_mul_f32 v[142:143], v[104:105], v[194:195] op_sel_hi:[1,0]
	global_store_dwordx2 v[224:225], v[136:137], off offset:64
	v_pk_mul_f32 v[136:137], v[110:111], v[194:195] op_sel_hi:[1,0]
	v_pk_mul_f32 v[138:139], v[108:109], v[194:195] op_sel_hi:[1,0]
	v_pk_mul_f32 v[218:219], v[140:141], v[206:207]
	v_pk_mul_f32 v[220:221], v[142:143], v[204:205]
	v_pk_fma_f32 v[218:219], v[136:137], v[202:203], v[218:219] neg_lo:[0,0,1] neg_hi:[0,0,1]
	v_pk_fma_f32 v[220:221], v[138:139], v[200:201], v[220:221] neg_lo:[0,0,1] neg_hi:[0,0,1]
	v_pk_mul_f32 v[136:137], v[136:137], v[206:207]
	v_pk_mul_f32 v[138:139], v[138:139], v[204:205]
	v_lshlrev_b64 v[216:217], 7, v[190:191]
	v_pk_fma_f32 v[136:137], v[140:141], v[202:203], v[136:137]
	v_pk_fma_f32 v[138:139], v[142:143], v[200:201], v[138:139]
	v_lshl_add_u64 v[216:217], v[158:159], 0, v[216:217]
	v_cvt_pk_bf16_f32 v138, v138, v139
	v_cvt_pk_bf16_f32 v139, v136, v137
	v_pk_mul_f32 v[140:141], v[90:91], v[188:189] op_sel_hi:[1,0]
	v_pk_mul_f32 v[142:143], v[88:89], v[188:189] op_sel_hi:[1,0]
	global_store_dwordx2 v[216:217], v[138:139], off offset:64
	v_pk_mul_f32 v[136:137], v[94:95], v[188:189] op_sel_hi:[1,0]
	v_pk_mul_f32 v[138:139], v[92:93], v[188:189] op_sel_hi:[1,0]
	v_pk_mul_f32 v[202:203], v[140:141], v[214:215]
	v_pk_mul_f32 v[204:205], v[142:143], v[212:213]
	v_pk_fma_f32 v[202:203], v[136:137], v[210:211], v[202:203] neg_lo:[0,0,1] neg_hi:[0,0,1]
	v_pk_fma_f32 v[204:205], v[138:139], v[208:209], v[204:205] neg_lo:[0,0,1] neg_hi:[0,0,1]
	v_pk_mul_f32 v[136:137], v[136:137], v[214:215]
	v_pk_mul_f32 v[138:139], v[138:139], v[212:213]
	v_lshlrev_b64 v[200:201], 7, v[186:187]
	v_pk_fma_f32 v[136:137], v[140:141], v[210:211], v[136:137]
	v_pk_fma_f32 v[138:139], v[142:143], v[208:209], v[138:139]
	v_lshl_add_u64 v[200:201], v[158:159], 0, v[200:201]
	v_cvt_pk_bf16_f32 v138, v138, v139
	v_cvt_pk_bf16_f32 v139, v136, v137
; DI u32x2 pk4(f32x4 v) { u32x2 r; r.x = pk2(v[0], v[1]); r.y = pk2(v[2], v[3]); return r; }
;     DI void operator()(const Acc& acc, const Unit& u, int wr, int wc, int fr, int fq) const {
;     ...
;                 for (int ai = 0; ai < 2; ++ai) if (ai == 0 || !hf) {
;                     f32x4 c4[4], s4[4];
; #pragma unroll
;                     for (int m = 0; m < 4; ++m) { const int pos = (row0 + ai * HALF + m * 16) & (SEQ - 1); c4[m] = *(const f32x4*)(cs + pos * 32 + j0); s4[m] = *(const f32x4*)(cs + 4096 * 32 + pos * 32 + j0); }
; #pragma unroll
;                     for (int m = 0; m < 4; ++m) { const int r = row0 + ai * HALF + m * 16; const float rs = rsv[ai][m];
;                         const f32x4 x1 = acc[ai][0][m][0] * rs, x2 = acc[ai][0][m][1] * rs;
;                         bf16_t* dst = WSB(OFF_KR) + (size_t)r * 64 + j0;
;                         *(u32x2*)(dst) = pk4(x1 * c4[m] - x2 * s4[m]); *(u32x2*)(dst + 32) = pk4(x2 * c4[m] + x1 * s4[m]); }
	v_cvt_pk_bf16_f32 v204, v204, v205
	v_cvt_pk_bf16_f32 v205, v202, v203
	global_store_dwordx2 v[200:201], v[138:139], off offset:64
	v_pk_mul_f32 v[136:137], v[78:79], v[184:185] op_sel_hi:[1,0]
	v_pk_mul_f32 v[138:139], v[76:77], v[184:185] op_sel_hi:[1,0]
	v_pk_mul_f32 v[140:141], v[74:75], v[184:185] op_sel_hi:[1,0]
	v_pk_mul_f32 v[142:143], v[72:73], v[184:185] op_sel_hi:[1,0]
	global_store_dwordx2 v[200:201], v[204:205], off
	v_pk_mul_f32 v[202:203], v[140:141], v[134:135]
	v_pk_mul_f32 v[204:205], v[142:143], v[132:133]
	v_pk_mul_f32 v[134:135], v[136:137], v[134:135]
	v_pk_mul_f32 v[132:133], v[138:139], v[132:133]
	v_lshlrev_b64 v[200:201], 7, v[182:183]
	v_pk_fma_f32 v[202:203], v[136:137], v[130:131], v[202:203] neg_lo:[0,0,1] neg_hi:[0,0,1]
	v_pk_fma_f32 v[204:205], v[138:139], v[128:129], v[204:205] neg_lo:[0,0,1] neg_hi:[0,0,1]
	v_pk_fma_f32 v[130:131], v[140:141], v[130:131], v[134:135]
	v_pk_fma_f32 v[128:129], v[142:143], v[128:129], v[132:133]
	v_lshl_add_u64 v[200:201], v[158:159], 0, v[200:201]
	v_cvt_pk_bf16_f32 v128, v128, v129
	v_cvt_pk_bf16_f32 v129, v130, v131
	global_store_dwordx2 v[200:201], v[128:129], off offset:64
	v_lshl_add_u32 v128, v192, 5, v199
	v_and_b32_e32 v128, 0x1f9e0, v128
	v_cvt_pk_bf16_f32 v228, v228, v229
	v_cvt_pk_bf16_f32 v229, v226, v227
	v_cvt_pk_bf16_f32 v220, v220, v221
	v_cvt_pk_bf16_f32 v221, v218, v219
	v_cvt_pk_bf16_f32 v204, v204, v205
	v_cvt_pk_bf16_f32 v205, v202, v203
	v_lshlrev_b32_e32 v152, 2, v128
	global_store_dwordx2 v[224:225], v[228:229], off
	global_store_dwordx2 v[216:217], v[220:221], off
	global_store_dwordx2 v[200:201], v[204:205], off
	v_lshl_add_u64 v[128:129], v[154:155], 0, v[152:153]
	global_load_dwordx4 v[200:203], v[128:129], off
	v_lshl_add_u64 v[130:131], v[156:157], 0, v[152:153]
	global_load_dwordx4 v[204:207], v[130:131], off
	global_load_dwordx4 v[208:211], v[128:129], off offset:2048
	global_load_dwordx4 v[212:215], v[130:131], off offset:2048
	v_or_b32_e32 v128, 0x1000, v152
	v_mov_b32_e32 v129, v153
	v_lshl_add_u64 v[130:131], v[154:155], 0, v[128:129]
	v_lshl_add_u64 v[128:129], v[156:157], 0, v[128:129]
	global_load_dwordx4 v[132:135], v[130:131], off
	global_load_dwordx4 v[140:143], v[128:129], off
	v_or_b32_e32 v152, 0x1800, v152
	v_lshl_add_u64 v[128:129], v[154:155], 0, v[152:153]
	v_lshl_add_u64 v[136:137], v[156:157], 0, v[152:153]
	global_load_dwordx4 v[128:131], v[128:129], off
	v_pk_mul_f32 v[216:217], v[62:63], v[178:179] op_sel_hi:[1,0]
	global_load_dwordx4 v[136:139], v[136:137], off
	v_pk_mul_f32 v[218:219], v[60:61], v[178:179] op_sel_hi:[1,0]
	v_pk_mul_f32 v[220:221], v[58:59], v[178:179] op_sel_hi:[1,0]
	v_pk_mul_f32 v[222:223], v[56:57], v[178:179] op_sel_hi:[1,0]
	v_lshlrev_b64 v[224:225], 7, v[180:181]
	v_lshl_add_u64 v[224:225], v[158:159], 0, v[224:225]
	s_waitcnt vmcnt(0)
	v_pk_mul_f32 v[226:227], v[220:221], v[206:207]
	v_pk_mul_f32 v[228:229], v[222:223], v[204:205]
	v_pk_mul_f32 v[206:207], v[216:217], v[206:207]
	v_pk_mul_f32 v[204:205], v[218:219], v[204:205]
	v_pk_fma_f32 v[226:227], v[216:217], v[202:203], v[226:227] neg_lo:[0,0,1] neg_hi:[0,0,1]
	v_pk_fma_f32 v[228:229], v[218:219], v[200:201], v[228:229] neg_lo:[0,0,1] neg_hi:[0,0,1]
	v_pk_fma_f32 v[202:203], v[220:221], v[202:203], v[206:207]
	v_pk_fma_f32 v[200:201], v[222:223], v[200:201], v[204:205]
	v_pk_mul_f32 v[204:205], v[42:43], v[174:175] op_sel_hi:[1,0]
	v_cvt_pk_bf16_f32 v200, v200, v201
	v_cvt_pk_bf16_f32 v201, v202, v203
	v_pk_mul_f32 v[206:207], v[40:41], v[174:175] op_sel_hi:[1,0]
	global_store_dwordx2 v[224:225], v[200:201], off offset:64
	v_pk_mul_f32 v[200:201], v[46:47], v[174:175] op_sel_hi:[1,0]
	v_pk_mul_f32 v[202:203], v[44:45], v[174:175] op_sel_hi:[1,0]
	v_pk_mul_f32 v[218:219], v[204:205], v[214:215]
	v_pk_mul_f32 v[220:221], v[206:207], v[212:213]
	v_pk_fma_f32 v[218:219], v[200:201], v[210:211], v[218:219] neg_lo:[0,0,1] neg_hi:[0,0,1]
	v_pk_fma_f32 v[220:221], v[202:203], v[208:209], v[220:221] neg_lo:[0,0,1] neg_hi:[0,0,1]
	v_pk_mul_f32 v[200:201], v[200:201], v[214:215]
	v_pk_mul_f32 v[202:203], v[202:203], v[212:213]
	v_lshlrev_b64 v[216:217], 7, v[176:177]
	v_pk_fma_f32 v[200:201], v[204:205], v[210:211], v[200:201]
	v_pk_fma_f32 v[202:203], v[206:207], v[208:209], v[202:203]
	v_lshl_add_u64 v[216:217], v[158:159], 0, v[216:217]
	v_cvt_pk_bf16_f32 v202, v202, v203
	v_cvt_pk_bf16_f32 v203, v200, v201
	global_store_dwordx2 v[216:217], v[202:203], off offset:64
	v_pk_mul_f32 v[200:201], v[30:31], v[170:171] op_sel_hi:[1,0]
	v_pk_mul_f32 v[202:203], v[28:29], v[170:171] op_sel_hi:[1,0]
	v_pk_mul_f32 v[204:205], v[26:27], v[170:171] op_sel_hi:[1,0]
	v_pk_mul_f32 v[206:207], v[24:25], v[170:171] op_sel_hi:[1,0]
	v_pk_mul_f32 v[210:211], v[204:205], v[142:143]
	v_pk_mul_f32 v[212:213], v[206:207], v[140:141]
	v_pk_mul_f32 v[142:143], v[200:201], v[142:143]
	v_pk_mul_f32 v[140:141], v[202:203], v[140:141]
	v_lshlrev_b64 v[208:209], 7, v[172:173]
	v_pk_fma_f32 v[210:211], v[200:201], v[134:135], v[210:211] neg_lo:[0,0,1] neg_hi:[0,0,1]
	v_pk_fma_f32 v[212:213], v[202:203], v[132:133], v[212:213] neg_lo:[0,0,1] neg_hi:[0,0,1]
	v_pk_fma_f32 v[134:135], v[204:205], v[134:135], v[142:143]
	v_pk_fma_f32 v[132:133], v[206:207], v[132:133], v[140:141]
	v_lshl_add_u64 v[208:209], v[158:159], 0, v[208:209]
	v_cvt_pk_bf16_f32 v132, v132, v133
	v_cvt_pk_bf16_f32 v133, v134, v135
	v_pk_mul_f32 v[140:141], v[10:11], v[166:167] op_sel_hi:[1,0]
	v_pk_mul_f32 v[142:143], v[8:9], v[166:167] op_sel_hi:[1,0]
	global_store_dwordx2 v[208:209], v[132:133], off offset:64
	v_pk_mul_f32 v[132:133], v[14:15], v[166:167] op_sel_hi:[1,0]
	v_pk_mul_f32 v[134:135], v[12:13], v[166:167] op_sel_hi:[1,0]
	v_pk_mul_f32 v[202:203], v[140:141], v[138:139]
	v_pk_mul_f32 v[204:205], v[142:143], v[136:137]
	v_pk_fma_f32 v[202:203], v[132:133], v[130:131], v[202:203] neg_lo:[0,0,1] neg_hi:[0,0,1]
	v_pk_fma_f32 v[204:205], v[134:135], v[128:129], v[204:205] neg_lo:[0,0,1] neg_hi:[0,0,1]
	v_pk_mul_f32 v[132:133], v[132:133], v[138:139]
	v_pk_mul_f32 v[134:135], v[134:135], v[136:137]
	v_lshlrev_b64 v[200:201], 7, v[168:169]
	v_pk_fma_f32 v[130:131], v[140:141], v[130:131], v[132:133]
	v_pk_fma_f32 v[128:129], v[142:143], v[128:129], v[134:135]
	v_cvt_pk_bf16_f32 v228, v228, v229
	v_cvt_pk_bf16_f32 v229, v226, v227
	v_cvt_pk_bf16_f32 v220, v220, v221
	v_cvt_pk_bf16_f32 v221, v218, v219
	v_cvt_pk_bf16_f32 v212, v212, v213
	v_cvt_pk_bf16_f32 v213, v210, v211
	v_lshl_add_u64 v[200:201], v[158:159], 0, v[200:201]
	v_cvt_pk_bf16_f32 v204, v204, v205
	v_cvt_pk_bf16_f32 v205, v202, v203
	v_cvt_pk_bf16_f32 v128, v128, v129
	v_cvt_pk_bf16_f32 v129, v130, v131
	global_store_dwordx2 v[224:225], v[228:229], off
	global_store_dwordx2 v[216:217], v[220:221], off
	global_store_dwordx2 v[208:209], v[212:213], off
	global_store_dwordx2 v[200:201], v[204:205], off
	global_store_dwordx2 v[200:201], v[128:129], off offset:64

; #define PG8_STAGE(bufoff, gbase, voff) do { _Pragma("unroll") for (int _i = 0; _i < 2; ++_i) \
;         __builtin_amdgcn_global_load_lds((const unsigned*)((const char*)(gbase) + (voff)[_i]), (LAS unsigned*)(lds + (bufoff) + ldsw + _i * 8192), 16, 0, 0); } while (0)
; #define PG8_LDA(dst, b, h) do { _Pragma("unroll") for (int m = 0; m < 4; ++m) _Pragma("unroll") for (int k = 0; k < 2; ++k) dst[m][k] = *(const LAS bf16x8*)(lds + PG8_SA(b, h) + aoff + m * 2048 + k * 1024); } while (0)
; #define PG8_LDB(dst, b, h) do { _Pragma("unroll") for (int n = 0; n < 2; ++n) _Pragma("unroll") for (int k = 0; k < 2; ++k) dst[n][k] = *(const LAS bf16x8*)(lds + PG8_SB(b, h) + boff + n * 2048 + k * 1024); } while (0)
; #define PG8_MMA(ai, bj, At, Bt) do { __builtin_amdgcn_s_setprio(1); _Pragma("unroll") for (int m = 0; m < 4; ++m) _Pragma("unroll") for (int n = 0; n < 2; ++n) _Pragma("unroll") for (int k = 0; k < 2; ++k) \
;         acc[ai][bj][m][n] = __builtin_amdgcn_mfma_f32_16x16x32_bf16(Bt[n][k], At[m][k], acc[ai][bj][m][n], 0, 0, 0); __builtin_amdgcn_s_setprio(0); } while (0)
; #define PG8_WAIT_L(n) asm volatile("s_waitcnt lgkmcnt(" #n ")" ::: "memory")
; template <class Epi>
; DI void gemm_phase(LAS unsigned char* lds, int wid, int K, int lda, int ldb, bool bperm, const Sched3& S, const Epi& E) {
;     ...
;         const char* nA = has_next ? nxt.A : cA; const char* nB = has_next ? nxt.B : cB; const size_t nhA = has_next ? (nxt.half ? (size_t)0 : hstepA) : hA; const bool full = (cur.half == 0);
;         for (int t = 0; t < nt; t += 2) {
;             const bool last = (t == nt - 2);
;             const char* a1 = cA + (size_t)(t + 1) * kstep;
;             const char* a2 = last ? nA : cA + (size_t)(t + 2) * kstep; const char* b2 = last ? nB : cB + (size_t)(t + 2) * kstep;
;             const char* a3 = a2 + kstep; const char* b3 = b2 + kstep; const size_t h2 = last ? nhA : hA;
;             PG8_LDB(B0, 0, 0); PG8_SCHED; PG8_LDA(At, 0, 0); PG8_STAGE(PG8_SA(1, 1), a1 + hA, voffA);
;             PG8_WAIT_L(8); PG8_BAR; PG8_WAIT_L(0); PG8_MMA(0, 0, At, B0); PG8_BAR; PG8_SCHED;
;             PG8_LDB(B1, 0, 1); PG8_STAGE(PG8_SB(0, 0), b2, voffB);
;             PG8_BAR; PG8_WAIT_L(0); PG8_MMA(0, 1, At, B1); PG8_BAR;
;             PG8_LDA(At, 0, 1); PG8_STAGE(PG8_SA(0, 0), a2, voffA);
;             PG8_BAR; PG8_WAIT_L(0); if (full) PG8_MMA(1, 0, At, B0); PG8_BAR; PG8_SCHED;
.LBB0_995:
	s_xor_b64 s[48:49], s[56:57], -1
	s_and_b64 s[56:57], s[56:57], exec
	s_cselect_b32 s41, s45, s53
	s_cselect_b32 s43, s44, s52
	s_cselect_b32 s51, s47, s55
	s_cselect_b32 s58, s46, s54
	s_add_u32 s52, s52, 0x20080
	s_addc_u32 s53, s53, 0
	s_add_u32 s59, s54, 0x100
	s_nop 0
	s_addc_u32 s60, s55, 0
	s_mov_b32 s61, -2
	ds_read_b128 v[156:159], v182
	ds_read_b128 v[160:163], v182 offset:1024
	ds_read_b128 v[164:167], v182 offset:2048
	ds_read_b128 v[168:171], v182 offset:3072
	s_add_u32 s54, s52, 0xfffe0080
	s_addc_u32 s55, s53, -1
	s_cmp_eq_u32 s61, 4
	s_cselect_b32 s57, s41, s55
	s_cselect_b32 s56, s43, s54
	s_cselect_b32 s55, s51, s60
	s_cselect_b32 s54, s58, s59
	v_lshl_add_u64 v[214:215], s[52:53], 0, v[144:145]
	s_add_i32 m0, s66, 0xc000
	ds_read_b128 v[172:175], v183
	ds_read_b128 v[186:189], v183 offset:1024
	ds_read_b128 v[190:193], v183 offset:2048
	ds_read_b128 v[194:197], v183 offset:3072
	ds_read_b128 v[198:201], v183 offset:4096
	ds_read_b128 v[202:205], v183 offset:5120
	ds_read_b128 v[206:209], v183 offset:6144
	ds_read_b128 v[210:213], v183 offset:7168
	global_load_lds_dwordx4 v[214:215], off
	v_lshl_add_u64 v[214:215], s[52:53], 0, v[146:147]
	s_add_i32 m0, s66, 0xe000
	s_nop 0
	global_load_lds_dwordx4 v[214:215], off
	s_waitcnt lgkmcnt(8)
	s_barrier
	s_waitcnt lgkmcnt(0)
	s_setprio 1
	s_waitcnt lgkmcnt(0)
	v_mfma_f32_16x16x32_bf16 v[124:127], v[156:159], v[172:175], 0
	v_mfma_f32_16x16x32_bf16 v[120:123], v[164:167], v[172:175], 0
	v_mfma_f32_16x16x32_bf16 v[116:119], v[156:159], v[190:193], 0
	v_mfma_f32_16x16x32_bf16 v[112:115], v[164:167], v[190:193], 0
	v_mfma_f32_16x16x32_bf16 v[108:111], v[156:159], v[198:201], 0
	v_mfma_f32_16x16x32_bf16 v[104:107], v[164:167], v[198:201], 0
	v_mfma_f32_16x16x32_bf16 v[100:103], v[156:159], v[206:209], 0
	v_mfma_f32_16x16x32_bf16 v[96:99], v[164:167], v[206:209], 0
	v_mfma_f32_16x16x32_bf16 v[124:127], v[160:163], v[186:189], v[124:127]
	v_mfma_f32_16x16x32_bf16 v[120:123], v[168:171], v[186:189], v[120:123]
	v_mfma_f32_16x16x32_bf16 v[116:119], v[160:163], v[194:197], v[116:119]
	v_mfma_f32_16x16x32_bf16 v[112:115], v[168:171], v[194:197], v[112:115]
	v_mfma_f32_16x16x32_bf16 v[108:111], v[160:163], v[202:205], v[108:111]
	v_mfma_f32_16x16x32_bf16 v[104:107], v[168:171], v[202:205], v[104:107]
	v_mfma_f32_16x16x32_bf16 v[100:103], v[160:163], v[210:213], v[100:103]
	v_mfma_f32_16x16x32_bf16 v[96:99], v[168:171], v[210:213], v[96:99]
	s_setprio 0
	s_barrier
	s_add_i32 s62, s76, s65
	v_lshl_add_u64 v[222:223], s[54:55], 0, v[130:131]
	s_mov_b32 m0, s62
	ds_read_b128 v[214:217], v184
	ds_read_b128 v[218:221], v184 offset:1024
	ds_read_b128 v[224:227], v184 offset:2048
	ds_read_b128 v[228:231], v184 offset:3072
	global_load_lds_dwordx4 v[222:223], off
	v_lshl_add_u64 v[232:233], s[54:55], 0, v[134:135]
	s_add_i32 m0, s62, 0x2000
	s_nop 0
	global_load_lds_dwordx4 v[232:233], off
	s_barrier
	s_waitcnt lgkmcnt(0)
	s_setprio 1
	s_waitcnt lgkmcnt(0)
	v_mfma_f32_16x16x32_bf16 v[60:63], v[214:217], v[172:175], 0
	v_mfma_f32_16x16x32_bf16 v[56:59], v[224:227], v[172:175], 0
	v_mfma_f32_16x16x32_bf16 v[52:55], v[214:217], v[190:193], 0
	v_mfma_f32_16x16x32_bf16 v[48:51], v[224:227], v[190:193], 0
	v_mfma_f32_16x16x32_bf16 v[44:47], v[214:217], v[198:201], 0
	v_mfma_f32_16x16x32_bf16 v[40:43], v[224:227], v[198:201], 0
	v_mfma_f32_16x16x32_bf16 v[36:39], v[214:217], v[206:209], 0
	v_mfma_f32_16x16x32_bf16 v[32:35], v[224:227], v[206:209], 0
	v_mfma_f32_16x16x32_bf16 v[60:63], v[218:221], v[186:189], v[60:63]
	v_mfma_f32_16x16x32_bf16 v[56:59], v[228:231], v[186:189], v[56:59]
	v_mfma_f32_16x16x32_bf16 v[52:55], v[218:221], v[194:197], v[52:55]
	v_mfma_f32_16x16x32_bf16 v[48:51], v[228:231], v[194:197], v[48:51]
	v_mfma_f32_16x16x32_bf16 v[44:47], v[218:221], v[202:205], v[44:47]
	v_mfma_f32_16x16x32_bf16 v[40:43], v[228:231], v[202:205], v[40:43]
	v_mfma_f32_16x16x32_bf16 v[36:39], v[218:221], v[210:213], v[36:39]
	v_mfma_f32_16x16x32_bf16 v[32:35], v[228:231], v[210:213], v[32:35]
	s_setprio 0
	s_mov_b32 m0, s66
	v_lshl_add_u64 v[234:235], s[56:57], 0, v[128:129]
	s_barrier
	ds_read_b128 v[172:175], v183 offset:16384
	ds_read_b128 v[186:189], v183 offset:17408
	ds_read_b128 v[190:193], v183 offset:18432
	ds_read_b128 v[194:197], v183 offset:19456
	ds_read_b128 v[198:201], v183 offset:20480
	ds_read_b128 v[202:205], v183 offset:21504
	ds_read_b128 v[206:209], v183 offset:22528
	ds_read_b128 v[210:213], v183 offset:23552
	global_load_lds_dwordx4 v[234:235], off
	v_lshl_add_u64 v[236:237], s[56:57], 0, v[132:133]
	s_mov_b32 m0, s67
	s_nop 0
	global_load_lds_dwordx4 v[236:237], off
	s_barrier
	s_waitcnt lgkmcnt(0)
	s_setprio 1
	s_waitcnt lgkmcnt(0)
	v_mfma_f32_16x16x32_bf16 v[92:95], v[156:159], v[172:175], 0
	v_mfma_f32_16x16x32_bf16 v[88:91], v[164:167], v[172:175], 0
	v_mfma_f32_16x16x32_bf16 v[84:87], v[156:159], v[190:193], 0
	v_mfma_f32_16x16x32_bf16 v[80:83], v[164:167], v[190:193], 0
	v_mfma_f32_16x16x32_bf16 v[76:79], v[156:159], v[198:201], 0
	v_mfma_f32_16x16x32_bf16 v[72:75], v[164:167], v[198:201], 0
	v_mfma_f32_16x16x32_bf16 v[68:71], v[156:159], v[206:209], 0
	v_mfma_f32_16x16x32_bf16 v[64:67], v[164:167], v[206:209], 0
	v_mfma_f32_16x16x32_bf16 v[92:95], v[160:163], v[186:189], v[92:95]
	v_mfma_f32_16x16x32_bf16 v[88:91], v[168:171], v[186:189], v[88:91]
	v_mfma_f32_16x16x32_bf16 v[84:87], v[160:163], v[194:197], v[84:87]
	v_mfma_f32_16x16x32_bf16 v[80:83], v[168:171], v[194:197], v[80:83]
	v_mfma_f32_16x16x32_bf16 v[76:79], v[160:163], v[202:205], v[76:79]
	v_mfma_f32_16x16x32_bf16 v[72:75], v[168:171], v[202:205], v[72:75]
	v_mfma_f32_16x16x32_bf16 v[68:71], v[160:163], v[210:213], v[68:71]
	v_mfma_f32_16x16x32_bf16 v[64:67], v[168:171], v[210:213], v[64:67]
	s_setprio 0
	s_barrier
; #define PG8_STAGE(bufoff, gbase, voff) do { _Pragma("unroll") for (int _i = 0; _i < 2; ++_i) \
;         __builtin_amdgcn_global_load_lds((const unsigned*)((const char*)(gbase) + (voff)[_i]), (LAS unsigned*)(lds + (bufoff) + ldsw + _i * 8192), 16, 0, 0); } while (0)
; #define PG8_LDA(dst, b, h) do { _Pragma("unroll") for (int m = 0; m < 4; ++m) _Pragma("unroll") for (int k = 0; k < 2; ++k) dst[m][k] = *(const LAS bf16x8*)(lds + PG8_SA(b, h) + aoff + m * 2048 + k * 1024); } while (0)
; #define PG8_LDB(dst, b, h) do { _Pragma("unroll") for (int n = 0; n < 2; ++n) _Pragma("unroll") for (int k = 0; k < 2; ++k) dst[n][k] = *(const LAS bf16x8*)(lds + PG8_SB(b, h) + boff + n * 2048 + k * 1024); } while (0)
; #define PG8_MMA(ai, bj, At, Bt) do { __builtin_amdgcn_s_setprio(1); _Pragma("unroll") for (int m = 0; m < 4; ++m) _Pragma("unroll") for (int n = 0; n < 2; ++n) _Pragma("unroll") for (int k = 0; k < 2; ++k) \
;         acc[ai][bj][m][n] = __builtin_amdgcn_mfma_f32_16x16x32_bf16(Bt[n][k], At[m][k], acc[ai][bj][m][n], 0, 0, 0); __builtin_amdgcn_s_setprio(0); } while (0)
; #define PG8_WAIT_V(n) asm volatile("s_waitcnt vmcnt(" #n ")" ::: "memory")
; #define PG8_WAIT_L(n) asm volatile("s_waitcnt lgkmcnt(" #n ")" ::: "memory")
; #define PG8_BAR __builtin_amdgcn_s_barrier()
; #define PG8_SCHED __builtin_amdgcn_sched_barrier(0)
; template <class Epi>
; DI void gemm_phase(LAS unsigned char* lds, int wid, int K, int lda, int ldb, bool bperm, const Sched3& S, const Epi& E) {
;     ...
;             PG8_STAGE(PG8_SB(0, 1), b2 + hstepB, voffB);
;             PG8_WAIT_V(6); PG8_BAR; if (full) PG8_MMA(1, 1, At, B1); PG8_BAR;
;             PG8_LDB(B0, 1, 0); PG8_SCHED; PG8_LDA(At, 1, 0); PG8_STAGE(PG8_SA(0, 1), a2 + h2, voffA);
;             PG8_WAIT_L(8); PG8_BAR; PG8_WAIT_L(0); PG8_MMA(0, 0, At, B0); PG8_BAR; PG8_SCHED;
;             PG8_LDB(B1, 1, 1); PG8_STAGE(PG8_SB(1, 0), b3, voffB);
;             PG8_BAR; PG8_WAIT_L(0); PG8_MMA(0, 1, At, B1); PG8_BAR;
;             PG8_LDA(At, 1, 1); PG8_STAGE(PG8_SA(1, 0), a3, voffA);
	s_add_u32 s62, s54, 0x20000
	s_addc_u32 s63, s55, 0
	s_add_i32 s86, s77, s65
	v_lshl_add_u64 v[156:157], s[62:63], 0, v[130:131]
	s_mov_b32 m0, s86
	s_nop 0
	global_load_lds_dwordx4 v[156:157], off
	v_lshl_add_u64 v[156:157], s[62:63], 0, v[134:135]
	s_add_i32 m0, s86, 0x2000
	s_nop 0
	global_load_lds_dwordx4 v[156:157], off
	s_waitcnt vmcnt(6)
	s_barrier
	s_setprio 1
	v_mfma_f32_16x16x32_bf16 v[28:31], v[214:217], v[172:175], 0
	v_mfma_f32_16x16x32_bf16 v[24:27], v[224:227], v[172:175], 0
	v_mfma_f32_16x16x32_bf16 v[20:23], v[214:217], v[190:193], 0
	v_mfma_f32_16x16x32_bf16 v[16:19], v[224:227], v[190:193], 0
	v_mfma_f32_16x16x32_bf16 v[12:15], v[214:217], v[198:201], 0
	v_mfma_f32_16x16x32_bf16 v[8:11], v[224:227], v[198:201], 0
	v_mfma_f32_16x16x32_bf16 v[4:7], v[214:217], v[206:209], 0
	v_mfma_f32_16x16x32_bf16 v[0:3], v[224:227], v[206:209], 0
	v_mfma_f32_16x16x32_bf16 v[28:31], v[218:221], v[186:189], v[28:31]
	v_mfma_f32_16x16x32_bf16 v[24:27], v[228:231], v[186:189], v[24:27]
	v_mfma_f32_16x16x32_bf16 v[20:23], v[218:221], v[194:197], v[20:23]
	v_mfma_f32_16x16x32_bf16 v[16:19], v[228:231], v[194:197], v[16:19]
	v_mfma_f32_16x16x32_bf16 v[12:15], v[218:221], v[202:205], v[12:15]
	v_mfma_f32_16x16x32_bf16 v[8:11], v[228:231], v[202:205], v[8:11]
	v_mfma_f32_16x16x32_bf16 v[4:7], v[218:221], v[210:213], v[4:7]
	v_mfma_f32_16x16x32_bf16 v[0:3], v[228:231], v[210:213], v[0:3]
	s_setprio 0
	s_add_i32 s62, 0, 0x18000
	v_add_u32_e32 v136, s62, v179
	s_barrier
	ds_read_b128 v[156:159], v136
	ds_read_b128 v[160:163], v136 offset:1024
	ds_read_b128 v[164:167], v136 offset:2048
	ds_read_b128 v[168:171], v136 offset:3072
	s_add_u32 s56, s56, 0x20000
	s_addc_u32 s57, s57, 0
	s_mov_b32 m0, s68
	v_lshl_add_u64 v[214:215], s[56:57], 0, v[128:129]
	ds_read_b128 v[172:175], v183 offset:32768
	ds_read_b128 v[186:189], v183 offset:33792
	ds_read_b128 v[190:193], v183 offset:34816
	ds_read_b128 v[194:197], v183 offset:35840
	ds_read_b128 v[198:201], v183 offset:36864
	ds_read_b128 v[202:205], v183 offset:37888
	ds_read_b128 v[206:209], v183 offset:38912
	ds_read_b128 v[210:213], v183 offset:39936
	global_load_lds_dwordx4 v[214:215], off
	v_lshl_add_u64 v[214:215], s[56:57], 0, v[132:133]
	s_mov_b32 m0, s69
	s_nop 0
	global_load_lds_dwordx4 v[214:215], off
	s_waitcnt lgkmcnt(8)
	s_barrier
	s_waitcnt lgkmcnt(0)
	s_setprio 1
	s_waitcnt lgkmcnt(0)
	v_mfma_f32_16x16x32_bf16 v[124:127], v[156:159], v[172:175], v[124:127]
	v_mfma_f32_16x16x32_bf16 v[120:123], v[164:167], v[172:175], v[120:123]
	v_mfma_f32_16x16x32_bf16 v[116:119], v[156:159], v[190:193], v[116:119]
	v_mfma_f32_16x16x32_bf16 v[112:115], v[164:167], v[190:193], v[112:115]
	v_mfma_f32_16x16x32_bf16 v[108:111], v[156:159], v[198:201], v[108:111]
	v_mfma_f32_16x16x32_bf16 v[104:107], v[164:167], v[198:201], v[104:107]
	v_mfma_f32_16x16x32_bf16 v[100:103], v[156:159], v[206:209], v[100:103]
	v_mfma_f32_16x16x32_bf16 v[96:99], v[164:167], v[206:209], v[96:99]
	v_mfma_f32_16x16x32_bf16 v[124:127], v[160:163], v[186:189], v[124:127]
	v_mfma_f32_16x16x32_bf16 v[120:123], v[168:171], v[186:189], v[120:123]
	v_mfma_f32_16x16x32_bf16 v[116:119], v[160:163], v[194:197], v[116:119]
	v_mfma_f32_16x16x32_bf16 v[112:115], v[168:171], v[194:197], v[112:115]
	v_mfma_f32_16x16x32_bf16 v[108:111], v[160:163], v[202:205], v[108:111]
	v_mfma_f32_16x16x32_bf16 v[104:107], v[168:171], v[202:205], v[104:107]
	v_mfma_f32_16x16x32_bf16 v[100:103], v[160:163], v[210:213], v[100:103]
	v_mfma_f32_16x16x32_bf16 v[96:99], v[168:171], v[210:213], v[96:99]
	s_setprio 0
	s_barrier
	s_add_i32 s56, 0, 0x1c000
	s_add_i32 s57, s62, s65
	v_add_u32_e32 v136, s56, v179
	v_lshl_add_u64 v[222:223], v[222:223], 0, s[16:17]
	s_mov_b32 m0, s57
	ds_read_b128 v[214:217], v136
	ds_read_b128 v[218:221], v136 offset:1024
	ds_read_b128 v[224:227], v136 offset:2048
	ds_read_b128 v[228:231], v136 offset:3072
	global_load_lds_dwordx4 v[222:223], off
	v_lshl_add_u64 v[222:223], v[232:233], 0, s[16:17]
	s_add_i32 m0, s57, 0x2000
	s_nop 0
	global_load_lds_dwordx4 v[222:223], off
	s_barrier
; #define PG8_STAGE(bufoff, gbase, voff) do { _Pragma("unroll") for (int _i = 0; _i < 2; ++_i) \
;         __builtin_amdgcn_global_load_lds((const unsigned*)((const char*)(gbase) + (voff)[_i]), (LAS unsigned*)(lds + (bufoff) + ldsw + _i * 8192), 16, 0, 0); } while (0)
; #define PG8_LDA(dst, b, h) do { _Pragma("unroll") for (int m = 0; m < 4; ++m) _Pragma("unroll") for (int k = 0; k < 2; ++k) dst[m][k] = *(const LAS bf16x8*)(lds + PG8_SA(b, h) + aoff + m * 2048 + k * 1024); } while (0)
; #define PG8_LDB(dst, b, h) do { _Pragma("unroll") for (int n = 0; n < 2; ++n) _Pragma("unroll") for (int k = 0; k < 2; ++k) dst[n][k] = *(const LAS bf16x8*)(lds + PG8_SB(b, h) + boff + n * 2048 + k * 1024); } while (0)
; #define PG8_MMA(ai, bj, At, Bt) do { __builtin_amdgcn_s_setprio(1); _Pragma("unroll") for (int m = 0; m < 4; ++m) _Pragma("unroll") for (int n = 0; n < 2; ++n) _Pragma("unroll") for (int k = 0; k < 2; ++k) \
;         acc[ai][bj][m][n] = __builtin_amdgcn_mfma_f32_16x16x32_bf16(Bt[n][k], At[m][k], acc[ai][bj][m][n], 0, 0, 0); __builtin_amdgcn_s_setprio(0); } while (0)
; #define PG8_WAIT_V(n) asm volatile("s_waitcnt vmcnt(" #n ")" ::: "memory")
; #define PG8_WAIT_L(n) asm volatile("s_waitcnt lgkmcnt(" #n ")" ::: "memory")
; #define PG8_BAR __builtin_amdgcn_s_barrier()
; #define PG8_SCHED __builtin_amdgcn_sched_barrier(0)
; template <class Epi>
; DI void gemm_phase(LAS unsigned char* lds, int wid, int K, int lda, int ldb, bool bperm, const Sched3& S, const Epi& E) {
;     ...
;         for (int t = 0; t < nt; t += 2) {
;     ...
;             PG8_LDB(B1, 1, 1); PG8_STAGE(PG8_SB(1, 0), b3, voffB);
;             PG8_BAR; PG8_WAIT_L(0); PG8_MMA(0, 1, At, B1); PG8_BAR;
;             PG8_LDA(At, 1, 1); PG8_STAGE(PG8_SA(1, 0), a3, voffA);
;             PG8_BAR; PG8_WAIT_L(0); if (full) PG8_MMA(1, 0, At, B0); PG8_BAR; PG8_SCHED;
;             PG8_STAGE(PG8_SB(1, 1), b3 + hstepB, voffB);
;             PG8_WAIT_V(6); PG8_BAR; if (full) PG8_MMA(1, 1, At, B1); PG8_BAR;
	s_waitcnt lgkmcnt(0)
	s_setprio 1
	s_waitcnt lgkmcnt(0)
	v_mfma_f32_16x16x32_bf16 v[60:63], v[214:217], v[172:175], v[60:63]
	v_mfma_f32_16x16x32_bf16 v[56:59], v[224:227], v[172:175], v[56:59]
	v_mfma_f32_16x16x32_bf16 v[52:55], v[214:217], v[190:193], v[52:55]
	v_mfma_f32_16x16x32_bf16 v[48:51], v[224:227], v[190:193], v[48:51]
	v_mfma_f32_16x16x32_bf16 v[44:47], v[214:217], v[198:201], v[44:47]
	v_mfma_f32_16x16x32_bf16 v[40:43], v[224:227], v[198:201], v[40:43]
	v_mfma_f32_16x16x32_bf16 v[36:39], v[214:217], v[206:209], v[36:39]
	v_mfma_f32_16x16x32_bf16 v[32:35], v[224:227], v[206:209], v[32:35]
	v_mfma_f32_16x16x32_bf16 v[60:63], v[218:221], v[186:189], v[60:63]
	v_mfma_f32_16x16x32_bf16 v[56:59], v[228:231], v[186:189], v[56:59]
	v_mfma_f32_16x16x32_bf16 v[52:55], v[218:221], v[194:197], v[52:55]
	v_mfma_f32_16x16x32_bf16 v[48:51], v[228:231], v[194:197], v[48:51]
	v_mfma_f32_16x16x32_bf16 v[44:47], v[218:221], v[202:205], v[44:47]
	v_mfma_f32_16x16x32_bf16 v[40:43], v[228:231], v[202:205], v[40:43]
	v_mfma_f32_16x16x32_bf16 v[36:39], v[218:221], v[210:213], v[36:39]
	v_mfma_f32_16x16x32_bf16 v[32:35], v[228:231], v[210:213], v[32:35]
	s_setprio 0
	s_mov_b32 m0, s72
	v_lshl_add_u64 v[222:223], v[234:235], 0, s[16:17]
	s_barrier
	ds_read_b128 v[172:175], v183 offset:49152
	ds_read_b128 v[186:189], v183 offset:50176
	ds_read_b128 v[190:193], v183 offset:51200
	ds_read_b128 v[194:197], v183 offset:52224
	ds_read_b128 v[198:201], v183 offset:53248
	ds_read_b128 v[202:205], v183 offset:54272
	ds_read_b128 v[206:209], v183 offset:55296
	ds_read_b128 v[210:213], v183 offset:56320
	global_load_lds_dwordx4 v[222:223], off
	v_lshl_add_u64 v[222:223], v[236:237], 0, s[16:17]
	s_mov_b32 m0, s73
	s_nop 0
	global_load_lds_dwordx4 v[222:223], off
	s_barrier
	s_waitcnt lgkmcnt(0)
	s_setprio 1
	s_waitcnt lgkmcnt(0)
	v_mfma_f32_16x16x32_bf16 v[92:95], v[156:159], v[172:175], v[92:95]
	v_mfma_f32_16x16x32_bf16 v[88:91], v[164:167], v[172:175], v[88:91]
	v_mfma_f32_16x16x32_bf16 v[84:87], v[156:159], v[190:193], v[84:87]
	v_mfma_f32_16x16x32_bf16 v[80:83], v[164:167], v[190:193], v[80:83]
	v_mfma_f32_16x16x32_bf16 v[76:79], v[156:159], v[198:201], v[76:79]
	v_mfma_f32_16x16x32_bf16 v[72:75], v[164:167], v[198:201], v[72:75]
	v_mfma_f32_16x16x32_bf16 v[68:71], v[156:159], v[206:209], v[68:71]
	v_mfma_f32_16x16x32_bf16 v[64:67], v[164:167], v[206:209], v[64:67]
	v_mfma_f32_16x16x32_bf16 v[92:95], v[160:163], v[186:189], v[92:95]
	v_mfma_f32_16x16x32_bf16 v[88:91], v[168:171], v[186:189], v[88:91]
	v_mfma_f32_16x16x32_bf16 v[84:87], v[160:163], v[194:197], v[84:87]
	v_mfma_f32_16x16x32_bf16 v[80:83], v[168:171], v[194:197], v[80:83]
	v_mfma_f32_16x16x32_bf16 v[76:79], v[160:163], v[202:205], v[76:79]
	v_mfma_f32_16x16x32_bf16 v[72:75], v[168:171], v[202:205], v[72:75]
	v_mfma_f32_16x16x32_bf16 v[68:71], v[160:163], v[210:213], v[68:71]
	v_mfma_f32_16x16x32_bf16 v[64:67], v[168:171], v[210:213], v[64:67]
	s_setprio 0
	s_barrier
	s_add_u32 s54, s54, 0x20080
	s_addc_u32 s55, s55, 0
	s_add_i32 s56, s56, s65
	v_lshl_add_u64 v[156:157], s[54:55], 0, v[130:131]
	s_mov_b32 m0, s56
	s_nop 0
	global_load_lds_dwordx4 v[156:157], off
	v_lshl_add_u64 v[156:157], s[54:55], 0, v[134:135]
	s_add_i32 m0, s56, 0x2000
	s_nop 0
	global_load_lds_dwordx4 v[156:157], off
	s_waitcnt vmcnt(6)
	s_barrier
	s_setprio 1
	v_mfma_f32_16x16x32_bf16 v[28:31], v[214:217], v[172:175], v[28:31]
	v_mfma_f32_16x16x32_bf16 v[24:27], v[224:227], v[172:175], v[24:27]
	v_mfma_f32_16x16x32_bf16 v[20:23], v[214:217], v[190:193], v[20:23]
	v_mfma_f32_16x16x32_bf16 v[16:19], v[224:227], v[190:193], v[16:19]
	v_mfma_f32_16x16x32_bf16 v[12:15], v[214:217], v[198:201], v[12:15]
	v_mfma_f32_16x16x32_bf16 v[8:11], v[224:227], v[198:201], v[8:11]
	v_mfma_f32_16x16x32_bf16 v[4:7], v[214:217], v[206:209], v[4:7]
	v_mfma_f32_16x16x32_bf16 v[0:3], v[224:227], v[206:209], v[0:3]
	v_mfma_f32_16x16x32_bf16 v[28:31], v[218:221], v[186:189], v[28:31]
	v_mfma_f32_16x16x32_bf16 v[24:27], v[228:231], v[186:189], v[24:27]
	v_mfma_f32_16x16x32_bf16 v[20:23], v[218:221], v[194:197], v[20:23]
	v_mfma_f32_16x16x32_bf16 v[16:19], v[228:231], v[194:197], v[16:19]
	v_mfma_f32_16x16x32_bf16 v[12:15], v[218:221], v[202:205], v[12:15]
	v_mfma_f32_16x16x32_bf16 v[8:11], v[228:231], v[202:205], v[8:11]
	v_mfma_f32_16x16x32_bf16 v[4:7], v[218:221], v[210:213], v[4:7]
	v_mfma_f32_16x16x32_bf16 v[0:3], v[228:231], v[210:213], v[0:3]
	s_setprio 0
	s_add_i32 s61, s61, 2
	s_add_u32 s52, s52, 0x100
	s_addc_u32 s53, s53, 0
	s_add_u32 s59, s59, 0x100
	s_addc_u32 s60, s60, 0
	s_cmp_gt_u32 s61, 5
	s_barrier
	s_cbranch_scc0 .LBB0_996
	s_branch .Lpeel_5_exit

; #define ROWS8 _Pragma("unroll") for (int ai = 0; ai < 2; ++ai) _Pragma("unroll") for (int m = 0; m < 4; ++m) if (ai == 0 || !hf)
; #define LOAD_ROW_RS(rsv, ssqp, invn) float rsv[2][4]; ROWS8_ALL rsv[ai][m] = (ssqp)[row0 + ai * HALF + m * 16]; ROWS8_ALL rsv[ai][m] = rstd_of(rsv[ai][m], invn)
; #define PK8(v0, v1) ({ const u32x2 h0_ = pk4(v0), h1_ = pk4(v1); (u32x4){h0_.x, h0_.y, h1_.x, h1_.y}; })
;     DI void operator()(const Acc& acc, const Unit& u, int wr, int wc, int fr, int fq) const {
;     ...
;             } else if (u.kind == K_KN) {
;                 LOAD_ROW_RS(rsv, SSQ(5), 1.f / 512.f);
;                 ROWS8 { const int r = row0 + ai * HALF + m * 16; const float rs = rsv[ai][m];
;                     bf16_t* dst = WSB(OFF_KN) + (size_t)r * 2048 + colp;
; #pragma unroll
;                     for (int bj = 0; bj < 2; ++bj) *(u32x4*)(dst + bj * HALF) = PK8(acc[ai][bj][m][0] * rs, acc[ai][bj][m][1] * rs); }
.Lpeel_5_exit:
	v_lshl_add_u32 v156, s50, 8, v177
	v_lshl_add_u32 v164, s84, 8, v181
	s_mov_b64 s[54:55], -1
	s_mov_b64 s[50:51], 0
	s_cmp_lt_i32 s85, 7
	s_mov_b64 s[52:53], 0
	s_cbranch_scc1 .LBB0_1001
	s_cmp_eq_u32 s85, 7
	s_mov_b64 s[52:53], -1
	s_cbranch_scc0 .LBB0_1000
	v_or_b32_e32 v168, 16, v156
	v_ashrrev_i32_e32 v169, 31, v168
	v_or_b32_e32 v170, 32, v156
	v_or_b32_e32 v198, 48, v156
	v_lshl_add_u64 v[158:159], v[168:169], 2, s[18:19]
	v_ashrrev_i32_e32 v171, 31, v170
	v_ashrrev_i32_e32 v199, 31, v198
	v_ashrrev_i32_e32 v157, 31, v156
	v_lshl_add_u64 v[160:161], v[170:171], 2, s[18:19]
	v_lshl_add_u64 v[162:163], v[198:199], 2, s[18:19]
	v_lshl_add_u64 v[166:167], v[156:157], 2, s[18:19]
	global_load_dword v136, v[158:159], off
	global_load_dword v176, v[160:161], off
	global_load_dword v178, v[162:163], off
	global_load_dword v180, v[166:167], off
	v_add_u32_e32 v200, 0x80, v156
	v_add_u32_e32 v166, 0x90, v156
	v_add_u32_e32 v162, 0xa0, v156
	v_add_u32_e32 v158, 0xb0, v156
	v_ashrrev_i32_e32 v201, 31, v200
	v_ashrrev_i32_e32 v167, 31, v166
	v_ashrrev_i32_e32 v163, 31, v162
	v_ashrrev_i32_e32 v159, 31, v158
	v_lshl_add_u64 v[160:161], v[200:201], 2, s[18:19]
	v_lshl_add_u64 v[172:173], v[166:167], 2, s[18:19]
	v_lshl_add_u64 v[174:175], v[162:163], 2, s[18:19]
	v_lshl_add_u64 v[186:187], v[158:159], 2, s[18:19]
	global_load_dword v228, v[160:161], off
	global_load_dword v229, v[172:173], off
	global_load_dword v230, v[174:175], off
	global_load_dword v231, v[186:187], off
	v_ashrrev_i32_e32 v165, 31, v164
	v_lshlrev_b64 v[172:173], 12, v[156:157]
	v_lshlrev_b64 v[168:169], 12, v[168:169]
	v_lshlrev_b64 v[160:161], 1, v[164:165]
	v_lshl_add_u64 v[168:169], s[20:21], 0, v[168:169]
	v_lshl_add_u64 v[202:203], v[168:169], 0, v[160:161]
	v_lshlrev_b64 v[170:171], 12, v[170:171]
	v_lshl_add_u64 v[172:173], s[20:21], 0, v[172:173]
	v_lshl_add_u64 v[170:171], s[20:21], 0, v[170:171]
	v_lshl_add_u64 v[196:197], v[172:173], 0, v[160:161]
	v_lshl_add_u64 v[204:205], v[170:171], 0, v[160:161]
	v_lshlrev_b64 v[166:167], 12, v[166:167]
	v_lshl_add_u64 v[166:167], s[20:21], 0, v[166:167]
	v_lshlrev_b64 v[162:163], 12, v[162:163]
	v_lshl_add_u64 v[162:163], s[20:21], 0, v[162:163]
	v_lshl_add_u64 v[162:163], v[162:163], 0, v[160:161]
	v_lshlrev_b64 v[158:159], 12, v[158:159]
	v_lshl_add_u64 v[158:159], s[20:21], 0, v[158:159]
	s_mov_b64 s[52:53], 0
	s_waitcnt vmcnt(0)
	v_fmamk_f32 v157, v136, 0x3b000000, v185
	v_fmamk_f32 v165, v176, 0x3b000000, v185
	v_rsq_f32_e32 v168, v157
	v_fmamk_f32 v136, v180, 0x3b000000, v185
	v_rsq_f32_e32 v136, v136
	v_rsq_f32_e32 v176, v165
	v_fmamk_f32 v169, v178, 0x3b000000, v185
	v_rsq_f32_e32 v178, v169
	v_pk_mul_f32 v[170:171], v[126:127], v[136:137] op_sel_hi:[1,0]
	v_pk_mul_f32 v[172:173], v[124:125], v[136:137] op_sel_hi:[1,0]
	v_pk_mul_f32 v[174:175], v[122:123], v[136:137] op_sel_hi:[1,0]
	v_pk_mul_f32 v[186:187], v[120:121], v[136:137] op_sel_hi:[1,0]
	v_pk_mul_f32 v[188:189], v[62:63], v[136:137] op_sel_hi:[1,0]
	v_pk_mul_f32 v[190:191], v[60:61], v[136:137] op_sel_hi:[1,0]
	v_pk_mul_f32 v[192:193], v[58:59], v[136:137] op_sel_hi:[1,0]
	v_pk_mul_f32 v[194:195], v[56:57], v[136:137] op_sel_hi:[1,0]
	v_pk_mul_f32 v[206:207], v[118:119], v[168:169] op_sel_hi:[1,0]
	v_pk_mul_f32 v[208:209], v[116:117], v[168:169] op_sel_hi:[1,0]
	v_pk_mul_f32 v[210:211], v[114:115], v[168:169] op_sel_hi:[1,0]
	v_pk_mul_f32 v[212:213], v[112:113], v[168:169] op_sel_hi:[1,0]
	v_pk_mul_f32 v[214:215], v[54:55], v[168:169] op_sel_hi:[1,0]
	v_pk_mul_f32 v[216:217], v[52:53], v[168:169] op_sel_hi:[1,0]
	v_pk_mul_f32 v[218:219], v[50:51], v[168:169] op_sel_hi:[1,0]
	v_pk_mul_f32 v[220:221], v[48:49], v[168:169] op_sel_hi:[1,0]
	v_cvt_pk_bf16_f32 v168, v172, v173
	v_cvt_pk_bf16_f32 v169, v170, v171
	v_cvt_pk_bf16_f32 v170, v186, v187
	v_cvt_pk_bf16_f32 v171, v174, v175
	v_cvt_pk_bf16_f32 v172, v190, v191
	v_cvt_pk_bf16_f32 v173, v188, v189
	v_cvt_pk_bf16_f32 v174, v194, v195
	v_cvt_pk_bf16_f32 v175, v192, v193
	v_cvt_pk_bf16_f32 v186, v208, v209
	v_cvt_pk_bf16_f32 v187, v206, v207
	v_cvt_pk_bf16_f32 v188, v212, v213
	v_cvt_pk_bf16_f32 v189, v210, v211
	v_cvt_pk_bf16_f32 v190, v216, v217
	v_cvt_pk_bf16_f32 v191, v214, v215
	v_cvt_pk_bf16_f32 v192, v220, v221
	v_cvt_pk_bf16_f32 v193, v218, v219
	global_store_dwordx4 v[196:197], v[168:171], off
	global_store_dwordx4 v[196:197], v[172:175], off offset:256
	global_store_dwordx4 v[202:203], v[186:189], off
	global_store_dwordx4 v[202:203], v[190:193], off offset:256
	v_pk_mul_f32 v[168:169], v[104:105], v[176:177] op_sel_hi:[1,0]
	v_pk_mul_f32 v[170:171], v[46:47], v[176:177] op_sel_hi:[1,0]
	v_cvt_pk_bf16_f32 v196, v168, v169
	v_pk_mul_f32 v[168:169], v[44:45], v[176:177] op_sel_hi:[1,0]
	v_pk_mul_f32 v[172:173], v[42:43], v[176:177] op_sel_hi:[1,0]
	v_cvt_pk_bf16_f32 v168, v168, v169
	v_cvt_pk_bf16_f32 v169, v170, v171
	v_pk_mul_f32 v[170:171], v[40:41], v[176:177] op_sel_hi:[1,0]
	v_pk_mul_f32 v[174:175], v[98:99], v[178:179] op_sel_hi:[1,0]
	v_cvt_pk_bf16_f32 v170, v170, v171
	v_cvt_pk_bf16_f32 v171, v172, v173
	global_store_dwordx4 v[204:205], v[168:171], off offset:256
	v_fmamk_f32 v157, v230, 0x3b000000, v185
	v_pk_mul_f32 v[222:223], v[110:111], v[176:177] op_sel_hi:[1,0]
	v_lshlrev_b64 v[168:169], 12, v[198:199]
	v_lshl_add_u64 v[168:169], s[20:21], 0, v[168:169]
	v_lshl_add_u64 v[172:173], v[168:169], 0, v[160:161]
; #define ROWS8 _Pragma("unroll") for (int ai = 0; ai < 2; ++ai) _Pragma("unroll") for (int m = 0; m < 4; ++m) if (ai == 0 || !hf)
; #define PK8(v0, v1) ({ const u32x2 h0_ = pk4(v0), h1_ = pk4(v1); (u32x4){h0_.x, h0_.y, h1_.x, h1_.y}; })
;     DI void operator()(const Acc& acc, const Unit& u, int wr, int wc, int fr, int fq) const {
;     ...
;                 ROWS8 { const int r = row0 + ai * HALF + m * 16; const float rs = rsv[ai][m];
;                     bf16_t* dst = WSB(OFF_KN) + (size_t)r * 2048 + colp;
; #pragma unroll
;                     for (int bj = 0; bj < 2; ++bj) *(u32x4*)(dst + bj * HALF) = PK8(acc[ai][bj][m][0] * rs, acc[ai][bj][m][1] * rs); }
	v_pk_mul_f32 v[170:171], v[102:103], v[178:179] op_sel_hi:[1,0]
	v_pk_mul_f32 v[168:169], v[100:101], v[178:179] op_sel_hi:[1,0]
	v_pk_mul_f32 v[224:225], v[108:109], v[176:177] op_sel_hi:[1,0]
	v_cvt_pk_bf16_f32 v168, v168, v169
	v_cvt_pk_bf16_f32 v169, v170, v171
	v_pk_mul_f32 v[170:171], v[96:97], v[178:179] op_sel_hi:[1,0]
	v_pk_mul_f32 v[226:227], v[106:107], v[176:177] op_sel_hi:[1,0]
	v_cvt_pk_bf16_f32 v170, v170, v171
	v_cvt_pk_bf16_f32 v171, v174, v175
	global_store_dwordx4 v[172:173], v[168:171], off
	v_pk_mul_f32 v[174:175], v[34:35], v[178:179] op_sel_hi:[1,0]
	v_fmamk_f32 v136, v231, 0x3b000000, v185
	v_pk_mul_f32 v[170:171], v[38:39], v[178:179] op_sel_hi:[1,0]
	v_pk_mul_f32 v[168:169], v[36:37], v[178:179] op_sel_hi:[1,0]
	v_rsq_f32_e32 v136, v136
	v_cvt_pk_bf16_f32 v168, v168, v169
	v_cvt_pk_bf16_f32 v169, v170, v171
	v_pk_mul_f32 v[170:171], v[32:33], v[178:179] op_sel_hi:[1,0]
	v_cvt_pk_bf16_f32 v194, v224, v225
	v_cvt_pk_bf16_f32 v170, v170, v171
	v_cvt_pk_bf16_f32 v171, v174, v175
	global_store_dwordx4 v[172:173], v[168:171], off offset:256
	v_rsq_f32_e32 v172, v157
	v_fmamk_f32 v157, v229, 0x3b000000, v185
	v_rsq_f32_e32 v174, v157
	v_fmamk_f32 v157, v228, 0x3b000000, v185
	v_rsq_f32_e32 v176, v157
	v_lshlrev_b64 v[168:169], 12, v[200:201]
	v_lshl_add_u64 v[168:169], s[20:21], 0, v[168:169]
	v_lshl_add_u64 v[186:187], v[168:169], 0, v[160:161]
	v_pk_mul_f32 v[170:171], v[94:95], v[176:177] op_sel_hi:[1,0]
	v_pk_mul_f32 v[168:169], v[92:93], v[176:177] op_sel_hi:[1,0]
	v_pk_mul_f32 v[188:189], v[90:91], v[176:177] op_sel_hi:[1,0]
	v_cvt_pk_bf16_f32 v168, v168, v169
	v_cvt_pk_bf16_f32 v169, v170, v171
	v_pk_mul_f32 v[170:171], v[88:89], v[176:177] op_sel_hi:[1,0]
	v_cvt_pk_bf16_f32 v195, v222, v223
	v_cvt_pk_bf16_f32 v170, v170, v171
	v_cvt_pk_bf16_f32 v171, v188, v189
	global_store_dwordx4 v[186:187], v[168:171], off
	v_pk_mul_f32 v[188:189], v[26:27], v[176:177] op_sel_hi:[1,0]
	v_cvt_pk_bf16_f32 v197, v226, v227
	v_pk_mul_f32 v[170:171], v[30:31], v[176:177] op_sel_hi:[1,0]
	v_pk_mul_f32 v[168:169], v[28:29], v[176:177] op_sel_hi:[1,0]
	global_store_dwordx4 v[204:205], v[194:197], off
	v_cvt_pk_bf16_f32 v168, v168, v169
	v_cvt_pk_bf16_f32 v169, v170, v171
	v_pk_mul_f32 v[170:171], v[24:25], v[176:177] op_sel_hi:[1,0]
	s_nop 0
	v_cvt_pk_bf16_f32 v170, v170, v171
	v_cvt_pk_bf16_f32 v171, v188, v189
	global_store_dwordx4 v[186:187], v[168:171], off offset:256
	v_pk_mul_f32 v[186:187], v[82:83], v[174:175] op_sel_hi:[1,0]
	s_nop 0
	v_lshl_add_u64 v[170:171], v[166:167], 0, v[160:161]
	v_pk_mul_f32 v[168:169], v[86:87], v[174:175] op_sel_hi:[1,0]
	v_pk_mul_f32 v[166:167], v[84:85], v[174:175] op_sel_hi:[1,0]
	s_nop 0
	v_cvt_pk_bf16_f32 v166, v166, v167
	v_cvt_pk_bf16_f32 v167, v168, v169
	v_pk_mul_f32 v[168:169], v[80:81], v[174:175] op_sel_hi:[1,0]
	s_nop 0
	v_cvt_pk_bf16_f32 v168, v168, v169
	v_cvt_pk_bf16_f32 v169, v186, v187
	global_store_dwordx4 v[170:171], v[166:169], off
	v_pk_mul_f32 v[186:187], v[18:19], v[174:175] op_sel_hi:[1,0]
	s_nop 0
	v_pk_mul_f32 v[168:169], v[22:23], v[174:175] op_sel_hi:[1,0]
	v_pk_mul_f32 v[166:167], v[20:21], v[174:175] op_sel_hi:[1,0]
	s_nop 0
	v_cvt_pk_bf16_f32 v166, v166, v167
	v_cvt_pk_bf16_f32 v167, v168, v169
	v_pk_mul_f32 v[168:169], v[16:17], v[174:175] op_sel_hi:[1,0]
	s_nop 0
	v_cvt_pk_bf16_f32 v168, v168, v169
	v_cvt_pk_bf16_f32 v169, v186, v187
	global_store_dwordx4 v[170:171], v[166:169], off offset:256
	v_pk_mul_f32 v[170:171], v[74:75], v[172:173] op_sel_hi:[1,0]
	s_nop 0
	v_pk_mul_f32 v[168:169], v[78:79], v[172:173] op_sel_hi:[1,0]
	v_pk_mul_f32 v[166:167], v[76:77], v[172:173] op_sel_hi:[1,0]
	s_nop 0
	v_cvt_pk_bf16_f32 v166, v166, v167
	v_cvt_pk_bf16_f32 v167, v168, v169
	v_pk_mul_f32 v[168:169], v[72:73], v[172:173] op_sel_hi:[1,0]
	s_nop 0
	v_cvt_pk_bf16_f32 v168, v168, v169
	v_cvt_pk_bf16_f32 v169, v170, v171
	global_store_dwordx4 v[162:163], v[166:169], off
	v_pk_mul_f32 v[170:171], v[10:11], v[172:173] op_sel_hi:[1,0]
	s_nop 0
	v_pk_mul_f32 v[168:169], v[14:15], v[172:173] op_sel_hi:[1,0]
	v_pk_mul_f32 v[166:167], v[12:13], v[172:173] op_sel_hi:[1,0]
	s_nop 0
	v_cvt_pk_bf16_f32 v166, v166, v167
	v_cvt_pk_bf16_f32 v167, v168, v169
	v_pk_mul_f32 v[168:169], v[8:9], v[172:173] op_sel_hi:[1,0]
	s_nop 0
	v_cvt_pk_bf16_f32 v168, v168, v169
	v_cvt_pk_bf16_f32 v169, v170, v171
	global_store_dwordx4 v[162:163], v[166:169], off offset:256
	v_lshl_add_u64 v[162:163], v[158:159], 0, v[160:161]
	v_pk_mul_f32 v[160:161], v[70:71], v[136:137] op_sel_hi:[1,0]
	v_pk_mul_f32 v[158:159], v[68:69], v[136:137] op_sel_hi:[1,0]
	v_pk_mul_f32 v[166:167], v[66:67], v[136:137] op_sel_hi:[1,0]
	v_cvt_pk_bf16_f32 v158, v158, v159
	v_cvt_pk_bf16_f32 v159, v160, v161
	v_pk_mul_f32 v[160:161], v[64:65], v[136:137] op_sel_hi:[1,0]
	s_nop 0
	v_cvt_pk_bf16_f32 v160, v160, v161
	v_cvt_pk_bf16_f32 v161, v166, v167
	global_store_dwordx4 v[162:163], v[158:161], off
	v_pk_mul_f32 v[166:167], v[2:3], v[136:137] op_sel_hi:[1,0]
	s_nop 0
	v_pk_mul_f32 v[160:161], v[6:7], v[136:137] op_sel_hi:[1,0]
	v_pk_mul_f32 v[158:159], v[4:5], v[136:137] op_sel_hi:[1,0]
	s_nop 0
	v_cvt_pk_bf16_f32 v158, v158, v159
	v_cvt_pk_bf16_f32 v159, v160, v161
	v_pk_mul_f32 v[160:161], v[0:1], v[136:137] op_sel_hi:[1,0]
	s_nop 0
	v_cvt_pk_bf16_f32 v160, v160, v161
	v_cvt_pk_bf16_f32 v161, v166, v167
	global_store_dwordx4 v[162:163], v[158:161], off offset:256

; #define PG8_STAGE(bufoff, gbase, voff) do { _Pragma("unroll") for (int _i = 0; _i < 2; ++_i) \
;         __builtin_amdgcn_global_load_lds((const unsigned*)((const char*)(gbase) + (voff)[_i]), (LAS unsigned*)(lds + (bufoff) + ldsw + _i * 8192), 16, 0, 0); } while (0)
; #define PG8_LDA(dst, b, h) do { _Pragma("unroll") for (int m = 0; m < 4; ++m) _Pragma("unroll") for (int k = 0; k < 2; ++k) dst[m][k] = *(const LAS bf16x8*)(lds + PG8_SA(b, h) + aoff + m * 2048 + k * 1024); } while (0)
; #define PG8_LDB(dst, b, h) do { _Pragma("unroll") for (int n = 0; n < 2; ++n) _Pragma("unroll") for (int k = 0; k < 2; ++k) dst[n][k] = *(const LAS bf16x8*)(lds + PG8_SB(b, h) + boff + n * 2048 + k * 1024); } while (0)
; #define PG8_MMA(ai, bj, At, Bt) do { __builtin_amdgcn_s_setprio(1); _Pragma("unroll") for (int m = 0; m < 4; ++m) _Pragma("unroll") for (int n = 0; n < 2; ++n) _Pragma("unroll") for (int k = 0; k < 2; ++k) \
;         acc[ai][bj][m][n] = __builtin_amdgcn_mfma_f32_16x16x32_bf16(Bt[n][k], At[m][k], acc[ai][bj][m][n], 0, 0, 0); __builtin_amdgcn_s_setprio(0); } while (0)
; #define PG8_WAIT_L(n) asm volatile("s_waitcnt lgkmcnt(" #n ")" ::: "memory")
; #define PG8_BAR __builtin_amdgcn_s_barrier()
; #define PG8_SCHED __builtin_amdgcn_sched_barrier(0)
; template <class Epi>
; DI void gemm_phase(LAS unsigned char* lds, int wid, int K, int lda, int ldb, bool bperm, const Sched3& S, const Epi& E) {
;     ...
;     const char* cA = cur.A; const char* cB = cur.B; size_t hA = cur.half ? (size_t)0 : hstepA;
;     ...
;             PG8_LDB(B0, 0, 0); PG8_SCHED; PG8_LDA(At, 0, 0); PG8_STAGE(PG8_SA(1, 1), a1 + hA, voffA);
;             PG8_WAIT_L(8); PG8_BAR; PG8_WAIT_L(0); PG8_MMA(0, 0, At, B0); PG8_BAR; PG8_SCHED;
;             PG8_LDB(B1, 0, 1); PG8_STAGE(PG8_SB(0, 0), b2, voffB);
;             PG8_BAR; PG8_WAIT_L(0); PG8_MMA(0, 1, At, B1); PG8_BAR;
;             PG8_LDA(At, 0, 1); PG8_STAGE(PG8_SA(0, 0), a2, voffA);
;             PG8_BAR; PG8_WAIT_L(0); if (full) PG8_MMA(1, 0, At, B0); PG8_BAR; PG8_SCHED;
;     ...
; #pragma unroll
;         for (int a = 0; a < 2; ++a)
; #pragma unroll
;             for (int b = 0; b < 2; ++b)
; #pragma unroll
;                 for (int m = 0; m < 4; ++m)
; #pragma unroll
;                     for (int n = 0; n < 2; ++n) acc[a][b][m][n] = (f32x4){0.f, 0.f, 0.f, 0.f};
.LBB0_1175:
	s_add_u32 s36, s36, 0x80080
	s_addc_u32 s37, s37, 0
	s_add_u32 s19, s38, 0x100
	s_nop 0
	s_addc_u32 s21, s39, 0
	s_mov_b32 s27, -2
	s_waitcnt lgkmcnt(0)
	ds_read_b128 v[128:131], v185
	ds_read_b128 v[132:135], v185 offset:1024
	ds_read_b128 v[136:139], v185 offset:2048
	ds_read_b128 v[140:143], v185 offset:3072
	s_add_u32 s38, s36, 0xfff80080
	s_addc_u32 s39, s37, -1
	s_cmp_eq_u32 s27, 28
	s_cselect_b32 s41, s29, s39
	s_cselect_b32 s40, s28, s38
	s_cselect_b32 s39, s31, s21
	s_cselect_b32 s38, s30, s19
	v_lshl_add_u64 v[178:179], s[36:37], 0, v[156:157]
	s_add_i32 m0, s48, 0xc000
	ds_read_b128 v[144:147], v186
	ds_read_b128 v[148:151], v186 offset:1024
	ds_read_b128 v[162:165], v186 offset:2048
	ds_read_b128 v[166:169], v186 offset:3072
	ds_read_b128 v[170:173], v186 offset:4096
	ds_read_b128 v[174:177], v186 offset:5120
	ds_read_b128 v[188:191], v186 offset:6144
	ds_read_b128 v[192:195], v186 offset:7168
	global_load_lds_dwordx4 v[178:179], off
	v_lshl_add_u64 v[178:179], s[36:37], 0, v[158:159]
	s_add_i32 m0, s48, 0xe000
	s_nop 0
	global_load_lds_dwordx4 v[178:179], off
	s_waitcnt lgkmcnt(8)
	s_barrier
	s_waitcnt lgkmcnt(0)
	s_setprio 1
	s_waitcnt lgkmcnt(0)
	v_mfma_f32_16x16x32_bf16 v[124:127], v[128:131], v[144:147], 0
	v_mfma_f32_16x16x32_bf16 v[120:123], v[136:139], v[144:147], 0
	v_mfma_f32_16x16x32_bf16 v[108:111], v[128:131], v[162:165], 0
	v_mfma_f32_16x16x32_bf16 v[104:107], v[136:139], v[162:165], 0
	v_mfma_f32_16x16x32_bf16 v[92:95], v[128:131], v[170:173], 0
	v_mfma_f32_16x16x32_bf16 v[88:91], v[136:139], v[170:173], 0
	v_mfma_f32_16x16x32_bf16 v[76:79], v[128:131], v[188:191], 0
	v_mfma_f32_16x16x32_bf16 v[72:75], v[136:139], v[188:191], 0
	v_mfma_f32_16x16x32_bf16 v[124:127], v[132:135], v[148:151], v[124:127]
	v_mfma_f32_16x16x32_bf16 v[120:123], v[140:143], v[148:151], v[120:123]
	v_mfma_f32_16x16x32_bf16 v[108:111], v[132:135], v[166:169], v[108:111]
	v_mfma_f32_16x16x32_bf16 v[104:107], v[140:143], v[166:169], v[104:107]
	v_mfma_f32_16x16x32_bf16 v[92:95], v[132:135], v[174:177], v[92:95]
	v_mfma_f32_16x16x32_bf16 v[88:91], v[140:143], v[174:177], v[88:91]
	v_mfma_f32_16x16x32_bf16 v[76:79], v[132:135], v[192:195], v[76:79]
	v_mfma_f32_16x16x32_bf16 v[72:75], v[140:143], v[192:195], v[72:75]
	s_setprio 0
	s_barrier
	s_add_i32 s61, s57, s47
	v_lshl_add_u64 v[178:179], s[38:39], 0, v[152:153]
	s_mov_b32 m0, s61
	ds_read_b128 v[196:199], v187
	ds_read_b128 v[200:203], v187 offset:1024
	ds_read_b128 v[204:207], v187 offset:2048
	ds_read_b128 v[208:211], v187 offset:3072
	global_load_lds_dwordx4 v[178:179], off
	v_lshl_add_u64 v[212:213], s[38:39], 0, v[154:155]
	s_add_i32 m0, s61, 0x2000
	s_nop 0
	global_load_lds_dwordx4 v[212:213], off
	s_barrier
	s_waitcnt lgkmcnt(0)
	s_setprio 1
	s_waitcnt lgkmcnt(0)
	v_mfma_f32_16x16x32_bf16 v[116:119], v[196:199], v[144:147], 0
	v_mfma_f32_16x16x32_bf16 v[112:115], v[204:207], v[144:147], 0
	v_mfma_f32_16x16x32_bf16 v[100:103], v[196:199], v[162:165], 0
	v_mfma_f32_16x16x32_bf16 v[96:99], v[204:207], v[162:165], 0
	v_mfma_f32_16x16x32_bf16 v[84:87], v[196:199], v[170:173], 0
	v_mfma_f32_16x16x32_bf16 v[80:83], v[204:207], v[170:173], 0
	v_mfma_f32_16x16x32_bf16 v[68:71], v[196:199], v[188:191], 0
	v_mfma_f32_16x16x32_bf16 v[64:67], v[204:207], v[188:191], 0
	v_mfma_f32_16x16x32_bf16 v[116:119], v[200:203], v[148:151], v[116:119]
	v_mfma_f32_16x16x32_bf16 v[112:115], v[208:211], v[148:151], v[112:115]
	v_mfma_f32_16x16x32_bf16 v[100:103], v[200:203], v[166:169], v[100:103]
	v_mfma_f32_16x16x32_bf16 v[96:99], v[208:211], v[166:169], v[96:99]
	v_mfma_f32_16x16x32_bf16 v[84:87], v[200:203], v[174:177], v[84:87]
	v_mfma_f32_16x16x32_bf16 v[80:83], v[208:211], v[174:177], v[80:83]
	v_mfma_f32_16x16x32_bf16 v[68:71], v[200:203], v[192:195], v[68:71]
	v_mfma_f32_16x16x32_bf16 v[64:67], v[208:211], v[192:195], v[64:67]
	s_setprio 0
	s_mov_b32 m0, s48
	v_lshl_add_u64 v[214:215], s[40:41], 0, v[152:153]
	s_barrier
	ds_read_b128 v[144:147], v186 offset:16384
	ds_read_b128 v[148:151], v186 offset:17408
	ds_read_b128 v[162:165], v186 offset:18432
	ds_read_b128 v[166:169], v186 offset:19456
	ds_read_b128 v[170:173], v186 offset:20480
	ds_read_b128 v[174:177], v186 offset:21504
	ds_read_b128 v[188:191], v186 offset:22528
	ds_read_b128 v[192:195], v186 offset:23552
	global_load_lds_dwordx4 v[214:215], off
	v_lshl_add_u64 v[216:217], s[40:41], 0, v[154:155]
	s_mov_b32 m0, s49
	s_nop 0
	global_load_lds_dwordx4 v[216:217], off
	s_barrier
	s_waitcnt lgkmcnt(0)
	s_setprio 1
	s_waitcnt lgkmcnt(0)
	v_mfma_f32_16x16x32_bf16 v[60:63], v[128:131], v[144:147], 0
	v_mfma_f32_16x16x32_bf16 v[56:59], v[136:139], v[144:147], 0
	v_mfma_f32_16x16x32_bf16 v[44:47], v[128:131], v[162:165], 0
	v_mfma_f32_16x16x32_bf16 v[40:43], v[136:139], v[162:165], 0
	v_mfma_f32_16x16x32_bf16 v[28:31], v[128:131], v[170:173], 0
	v_mfma_f32_16x16x32_bf16 v[24:27], v[136:139], v[170:173], 0
	v_mfma_f32_16x16x32_bf16 v[12:15], v[128:131], v[188:191], 0
	v_mfma_f32_16x16x32_bf16 v[8:11], v[136:139], v[188:191], 0
	v_mfma_f32_16x16x32_bf16 v[60:63], v[132:135], v[148:151], v[60:63]
	v_mfma_f32_16x16x32_bf16 v[56:59], v[140:143], v[148:151], v[56:59]
	v_mfma_f32_16x16x32_bf16 v[44:47], v[132:135], v[166:169], v[44:47]
	v_mfma_f32_16x16x32_bf16 v[40:43], v[140:143], v[166:169], v[40:43]
	v_mfma_f32_16x16x32_bf16 v[28:31], v[132:135], v[174:177], v[28:31]
	v_mfma_f32_16x16x32_bf16 v[24:27], v[140:143], v[174:177], v[24:27]
	v_mfma_f32_16x16x32_bf16 v[12:15], v[132:135], v[192:195], v[12:15]
	v_mfma_f32_16x16x32_bf16 v[8:11], v[140:143], v[192:195], v[8:11]
	s_setprio 0
	s_barrier
; #define PG8_STAGE(bufoff, gbase, voff) do { _Pragma("unroll") for (int _i = 0; _i < 2; ++_i) \
;         __builtin_amdgcn_global_load_lds((const unsigned*)((const char*)(gbase) + (voff)[_i]), (LAS unsigned*)(lds + (bufoff) + ldsw + _i * 8192), 16, 0, 0); } while (0)
; #define PG8_LDA(dst, b, h) do { _Pragma("unroll") for (int m = 0; m < 4; ++m) _Pragma("unroll") for (int k = 0; k < 2; ++k) dst[m][k] = *(const LAS bf16x8*)(lds + PG8_SA(b, h) + aoff + m * 2048 + k * 1024); } while (0)
; #define PG8_LDB(dst, b, h) do { _Pragma("unroll") for (int n = 0; n < 2; ++n) _Pragma("unroll") for (int k = 0; k < 2; ++k) dst[n][k] = *(const LAS bf16x8*)(lds + PG8_SB(b, h) + boff + n * 2048 + k * 1024); } while (0)
; #define PG8_MMA(ai, bj, At, Bt) do { __builtin_amdgcn_s_setprio(1); _Pragma("unroll") for (int m = 0; m < 4; ++m) _Pragma("unroll") for (int n = 0; n < 2; ++n) _Pragma("unroll") for (int k = 0; k < 2; ++k) \
;         acc[ai][bj][m][n] = __builtin_amdgcn_mfma_f32_16x16x32_bf16(Bt[n][k], At[m][k], acc[ai][bj][m][n], 0, 0, 0); __builtin_amdgcn_s_setprio(0); } while (0)
; #define PG8_WAIT_V(n) asm volatile("s_waitcnt vmcnt(" #n ")" ::: "memory")
; #define PG8_WAIT_L(n) asm volatile("s_waitcnt lgkmcnt(" #n ")" ::: "memory")
; #define PG8_BAR __builtin_amdgcn_s_barrier()
; #define PG8_SCHED __builtin_amdgcn_sched_barrier(0)
; template <class Epi>
; DI void gemm_phase(LAS unsigned char* lds, int wid, int K, int lda, int ldb, bool bperm, const Sched3& S, const Epi& E) {
;     ...
;             PG8_STAGE(PG8_SB(0, 1), b2 + hstepB, voffB);
;             PG8_WAIT_V(6); PG8_BAR; if (full) PG8_MMA(1, 1, At, B1); PG8_BAR;
;             PG8_LDB(B0, 1, 0); PG8_SCHED; PG8_LDA(At, 1, 0); PG8_STAGE(PG8_SA(0, 1), a2 + h2, voffA);
;             PG8_WAIT_L(8); PG8_BAR; PG8_WAIT_L(0); PG8_MMA(0, 0, At, B0); PG8_BAR; PG8_SCHED;
;             PG8_LDB(B1, 1, 1); PG8_STAGE(PG8_SB(1, 0), b3, voffB);
;             PG8_BAR; PG8_WAIT_L(0); PG8_MMA(0, 1, At, B1); PG8_BAR;
	s_add_u32 s62, s38, 0x80000
	s_addc_u32 s63, s39, 0
	s_add_i32 s61, s58, s47
	v_lshl_add_u64 v[128:129], s[62:63], 0, v[152:153]
	s_mov_b32 m0, s61
	s_nop 0
	global_load_lds_dwordx4 v[128:129], off
	v_lshl_add_u64 v[128:129], s[62:63], 0, v[154:155]
	s_add_i32 m0, s61, 0x2000
	s_nop 0
	global_load_lds_dwordx4 v[128:129], off
	s_waitcnt vmcnt(6)
	s_barrier
	s_setprio 1
	v_mfma_f32_16x16x32_bf16 v[52:55], v[196:199], v[144:147], 0
	v_mfma_f32_16x16x32_bf16 v[48:51], v[204:207], v[144:147], 0
	v_mfma_f32_16x16x32_bf16 v[36:39], v[196:199], v[162:165], 0
	v_mfma_f32_16x16x32_bf16 v[32:35], v[204:207], v[162:165], 0
	v_mfma_f32_16x16x32_bf16 v[20:23], v[196:199], v[170:173], 0
	v_mfma_f32_16x16x32_bf16 v[16:19], v[204:207], v[170:173], 0
	v_mfma_f32_16x16x32_bf16 v[4:7], v[196:199], v[188:191], 0
	v_mfma_f32_16x16x32_bf16 v[0:3], v[204:207], v[188:191], 0
	v_mfma_f32_16x16x32_bf16 v[52:55], v[200:203], v[148:151], v[52:55]
	v_mfma_f32_16x16x32_bf16 v[48:51], v[208:211], v[148:151], v[48:51]
	v_mfma_f32_16x16x32_bf16 v[36:39], v[200:203], v[166:169], v[36:39]
	v_mfma_f32_16x16x32_bf16 v[32:35], v[208:211], v[166:169], v[32:35]
	v_mfma_f32_16x16x32_bf16 v[20:23], v[200:203], v[174:177], v[20:23]
	v_mfma_f32_16x16x32_bf16 v[16:19], v[208:211], v[174:177], v[16:19]
	v_mfma_f32_16x16x32_bf16 v[4:7], v[200:203], v[192:195], v[4:7]
	v_mfma_f32_16x16x32_bf16 v[0:3], v[208:211], v[192:195], v[0:3]
	s_setprio 0
	s_add_i32 s61, 0, 0x18000
	v_add_u32_e32 v140, s61, v181
	s_barrier
	ds_read_b128 v[128:131], v140
	ds_read_b128 v[132:135], v140 offset:1024
	ds_read_b128 v[136:139], v140 offset:2048
	ds_read_b128 v[140:143], v140 offset:3072
	s_add_u32 s40, s40, 0x80000
	s_addc_u32 s41, s41, 0
	s_mov_b32 m0, s50
	v_lshl_add_u64 v[196:197], s[40:41], 0, v[152:153]
	ds_read_b128 v[144:147], v186 offset:32768
	ds_read_b128 v[148:151], v186 offset:33792
	ds_read_b128 v[162:165], v186 offset:34816
	ds_read_b128 v[166:169], v186 offset:35840
	ds_read_b128 v[170:173], v186 offset:36864
	ds_read_b128 v[174:177], v186 offset:37888
	ds_read_b128 v[188:191], v186 offset:38912
	ds_read_b128 v[192:195], v186 offset:39936
	global_load_lds_dwordx4 v[196:197], off
	v_lshl_add_u64 v[196:197], s[40:41], 0, v[154:155]
	s_mov_b32 m0, s51
	s_nop 0
	global_load_lds_dwordx4 v[196:197], off
	s_waitcnt lgkmcnt(8)
	s_barrier
	s_waitcnt lgkmcnt(0)
	s_setprio 1
	s_waitcnt lgkmcnt(0)
	v_mfma_f32_16x16x32_bf16 v[124:127], v[128:131], v[144:147], v[124:127]
	v_mfma_f32_16x16x32_bf16 v[120:123], v[136:139], v[144:147], v[120:123]
	v_mfma_f32_16x16x32_bf16 v[108:111], v[128:131], v[162:165], v[108:111]
	v_mfma_f32_16x16x32_bf16 v[104:107], v[136:139], v[162:165], v[104:107]
	v_mfma_f32_16x16x32_bf16 v[92:95], v[128:131], v[170:173], v[92:95]
	v_mfma_f32_16x16x32_bf16 v[88:91], v[136:139], v[170:173], v[88:91]
	v_mfma_f32_16x16x32_bf16 v[76:79], v[128:131], v[188:191], v[76:79]
	v_mfma_f32_16x16x32_bf16 v[72:75], v[136:139], v[188:191], v[72:75]
	v_mfma_f32_16x16x32_bf16 v[124:127], v[132:135], v[148:151], v[124:127]
	v_mfma_f32_16x16x32_bf16 v[120:123], v[140:143], v[148:151], v[120:123]
	v_mfma_f32_16x16x32_bf16 v[108:111], v[132:135], v[166:169], v[108:111]
	v_mfma_f32_16x16x32_bf16 v[104:107], v[140:143], v[166:169], v[104:107]
	v_mfma_f32_16x16x32_bf16 v[92:95], v[132:135], v[174:177], v[92:95]
	v_mfma_f32_16x16x32_bf16 v[88:91], v[140:143], v[174:177], v[88:91]
	v_mfma_f32_16x16x32_bf16 v[76:79], v[132:135], v[192:195], v[76:79]
	v_mfma_f32_16x16x32_bf16 v[72:75], v[140:143], v[192:195], v[72:75]
	s_setprio 0
	s_barrier
	s_add_i32 s40, 0, 0x1c000
	s_add_i32 s41, s61, s47
	v_add_u32_e32 v208, s40, v181
	v_lshl_add_u64 v[178:179], v[178:179], 0, s[12:13]
	s_mov_b32 m0, s41
	ds_read_b128 v[196:199], v208
	ds_read_b128 v[200:203], v208 offset:1024
	ds_read_b128 v[204:207], v208 offset:2048
	ds_read_b128 v[208:211], v208 offset:3072
	global_load_lds_dwordx4 v[178:179], off
	v_lshl_add_u64 v[178:179], v[212:213], 0, s[12:13]
	s_add_i32 m0, s41, 0x2000
	s_nop 0
	global_load_lds_dwordx4 v[178:179], off
	s_barrier
; #define PG8_STAGE(bufoff, gbase, voff) do { _Pragma("unroll") for (int _i = 0; _i < 2; ++_i) \
;         __builtin_amdgcn_global_load_lds((const unsigned*)((const char*)(gbase) + (voff)[_i]), (LAS unsigned*)(lds + (bufoff) + ldsw + _i * 8192), 16, 0, 0); } while (0)
; #define PG8_LDA(dst, b, h) do { _Pragma("unroll") for (int m = 0; m < 4; ++m) _Pragma("unroll") for (int k = 0; k < 2; ++k) dst[m][k] = *(const LAS bf16x8*)(lds + PG8_SA(b, h) + aoff + m * 2048 + k * 1024); } while (0)
; #define PG8_LDB(dst, b, h) do { _Pragma("unroll") for (int n = 0; n < 2; ++n) _Pragma("unroll") for (int k = 0; k < 2; ++k) dst[n][k] = *(const LAS bf16x8*)(lds + PG8_SB(b, h) + boff + n * 2048 + k * 1024); } while (0)
; #define PG8_MMA(ai, bj, At, Bt) do { __builtin_amdgcn_s_setprio(1); _Pragma("unroll") for (int m = 0; m < 4; ++m) _Pragma("unroll") for (int n = 0; n < 2; ++n) _Pragma("unroll") for (int k = 0; k < 2; ++k) \
;         acc[ai][bj][m][n] = __builtin_amdgcn_mfma_f32_16x16x32_bf16(Bt[n][k], At[m][k], acc[ai][bj][m][n], 0, 0, 0); __builtin_amdgcn_s_setprio(0); } while (0)
; #define PG8_WAIT_V(n) asm volatile("s_waitcnt vmcnt(" #n ")" ::: "memory")
; #define PG8_WAIT_L(n) asm volatile("s_waitcnt lgkmcnt(" #n ")" ::: "memory")
; #define PG8_BAR __builtin_amdgcn_s_barrier()
; #define PG8_SCHED __builtin_amdgcn_sched_barrier(0)
; template <class Epi>
; DI void gemm_phase(LAS unsigned char* lds, int wid, int K, int lda, int ldb, bool bperm, const Sched3& S, const Epi& E) {
;     ...
;         for (int t = 0; t < nt; t += 2) {
;     ...
;             PG8_LDB(B1, 1, 1); PG8_STAGE(PG8_SB(1, 0), b3, voffB);
;             PG8_BAR; PG8_WAIT_L(0); PG8_MMA(0, 1, At, B1); PG8_BAR;
;             PG8_LDA(At, 1, 1); PG8_STAGE(PG8_SA(1, 0), a3, voffA);
;             PG8_BAR; PG8_WAIT_L(0); if (full) PG8_MMA(1, 0, At, B0); PG8_BAR; PG8_SCHED;
;             PG8_STAGE(PG8_SB(1, 1), b3 + hstepB, voffB);
;             PG8_WAIT_V(6); PG8_BAR; if (full) PG8_MMA(1, 1, At, B1); PG8_BAR;
	s_waitcnt lgkmcnt(0)
	s_setprio 1
	s_waitcnt lgkmcnt(0)
	v_mfma_f32_16x16x32_bf16 v[116:119], v[196:199], v[144:147], v[116:119]
	v_mfma_f32_16x16x32_bf16 v[112:115], v[204:207], v[144:147], v[112:115]
	v_mfma_f32_16x16x32_bf16 v[100:103], v[196:199], v[162:165], v[100:103]
	v_mfma_f32_16x16x32_bf16 v[96:99], v[204:207], v[162:165], v[96:99]
	v_mfma_f32_16x16x32_bf16 v[84:87], v[196:199], v[170:173], v[84:87]
	v_mfma_f32_16x16x32_bf16 v[80:83], v[204:207], v[170:173], v[80:83]
	v_mfma_f32_16x16x32_bf16 v[68:71], v[196:199], v[188:191], v[68:71]
	v_mfma_f32_16x16x32_bf16 v[64:67], v[204:207], v[188:191], v[64:67]
	v_mfma_f32_16x16x32_bf16 v[116:119], v[200:203], v[148:151], v[116:119]
	v_mfma_f32_16x16x32_bf16 v[112:115], v[208:211], v[148:151], v[112:115]
	v_mfma_f32_16x16x32_bf16 v[100:103], v[200:203], v[166:169], v[100:103]
	v_mfma_f32_16x16x32_bf16 v[96:99], v[208:211], v[166:169], v[96:99]
	v_mfma_f32_16x16x32_bf16 v[84:87], v[200:203], v[174:177], v[84:87]
	v_mfma_f32_16x16x32_bf16 v[80:83], v[208:211], v[174:177], v[80:83]
	v_mfma_f32_16x16x32_bf16 v[68:71], v[200:203], v[192:195], v[68:71]
	v_mfma_f32_16x16x32_bf16 v[64:67], v[208:211], v[192:195], v[64:67]
	s_setprio 0
	s_mov_b32 m0, s53
	v_lshl_add_u64 v[178:179], v[214:215], 0, s[12:13]
	s_barrier
	ds_read_b128 v[144:147], v186 offset:49152
	ds_read_b128 v[148:151], v186 offset:50176
	ds_read_b128 v[162:165], v186 offset:51200
	ds_read_b128 v[166:169], v186 offset:52224
	ds_read_b128 v[170:173], v186 offset:53248
	ds_read_b128 v[174:177], v186 offset:54272
	ds_read_b128 v[188:191], v186 offset:55296
	ds_read_b128 v[192:195], v186 offset:56320
	global_load_lds_dwordx4 v[178:179], off
	v_lshl_add_u64 v[178:179], v[216:217], 0, s[12:13]
	s_mov_b32 m0, s54
	s_nop 0
	global_load_lds_dwordx4 v[178:179], off
	s_barrier
	s_waitcnt lgkmcnt(0)
	s_setprio 1
	s_waitcnt lgkmcnt(0)
	v_mfma_f32_16x16x32_bf16 v[60:63], v[128:131], v[144:147], v[60:63]
	v_mfma_f32_16x16x32_bf16 v[56:59], v[136:139], v[144:147], v[56:59]
	v_mfma_f32_16x16x32_bf16 v[44:47], v[128:131], v[162:165], v[44:47]
	v_mfma_f32_16x16x32_bf16 v[40:43], v[136:139], v[162:165], v[40:43]
	v_mfma_f32_16x16x32_bf16 v[28:31], v[128:131], v[170:173], v[28:31]
	v_mfma_f32_16x16x32_bf16 v[24:27], v[136:139], v[170:173], v[24:27]
	v_mfma_f32_16x16x32_bf16 v[12:15], v[128:131], v[188:191], v[12:15]
	v_mfma_f32_16x16x32_bf16 v[8:11], v[136:139], v[188:191], v[8:11]
	v_mfma_f32_16x16x32_bf16 v[60:63], v[132:135], v[148:151], v[60:63]
	v_mfma_f32_16x16x32_bf16 v[56:59], v[140:143], v[148:151], v[56:59]
	v_mfma_f32_16x16x32_bf16 v[44:47], v[132:135], v[166:169], v[44:47]
	v_mfma_f32_16x16x32_bf16 v[40:43], v[140:143], v[166:169], v[40:43]
	v_mfma_f32_16x16x32_bf16 v[28:31], v[132:135], v[174:177], v[28:31]
	v_mfma_f32_16x16x32_bf16 v[24:27], v[140:143], v[174:177], v[24:27]
	v_mfma_f32_16x16x32_bf16 v[12:15], v[132:135], v[192:195], v[12:15]
	v_mfma_f32_16x16x32_bf16 v[8:11], v[140:143], v[192:195], v[8:11]
	s_setprio 0
	s_barrier
	s_add_u32 s38, s38, 0x80080
	s_addc_u32 s39, s39, 0
	s_add_i32 s40, s40, s47
	v_lshl_add_u64 v[128:129], s[38:39], 0, v[152:153]
	s_mov_b32 m0, s40
	s_nop 0
	global_load_lds_dwordx4 v[128:129], off
	v_lshl_add_u64 v[128:129], s[38:39], 0, v[154:155]
	s_add_i32 m0, s40, 0x2000
	s_nop 0
	global_load_lds_dwordx4 v[128:129], off
	s_waitcnt vmcnt(6)
	s_barrier
	s_setprio 1
	v_mfma_f32_16x16x32_bf16 v[52:55], v[196:199], v[144:147], v[52:55]
	v_mfma_f32_16x16x32_bf16 v[48:51], v[204:207], v[144:147], v[48:51]
	v_mfma_f32_16x16x32_bf16 v[36:39], v[196:199], v[162:165], v[36:39]
	v_mfma_f32_16x16x32_bf16 v[32:35], v[204:207], v[162:165], v[32:35]
	v_mfma_f32_16x16x32_bf16 v[20:23], v[196:199], v[170:173], v[20:23]
	v_mfma_f32_16x16x32_bf16 v[16:19], v[204:207], v[170:173], v[16:19]
	v_mfma_f32_16x16x32_bf16 v[4:7], v[196:199], v[188:191], v[4:7]
	v_mfma_f32_16x16x32_bf16 v[0:3], v[204:207], v[188:191], v[0:3]
	v_mfma_f32_16x16x32_bf16 v[52:55], v[200:203], v[148:151], v[52:55]
	v_mfma_f32_16x16x32_bf16 v[48:51], v[208:211], v[148:151], v[48:51]
	v_mfma_f32_16x16x32_bf16 v[36:39], v[200:203], v[166:169], v[36:39]
	v_mfma_f32_16x16x32_bf16 v[32:35], v[208:211], v[166:169], v[32:35]
	v_mfma_f32_16x16x32_bf16 v[20:23], v[200:203], v[174:177], v[20:23]
	v_mfma_f32_16x16x32_bf16 v[16:19], v[208:211], v[174:177], v[16:19]
	v_mfma_f32_16x16x32_bf16 v[4:7], v[200:203], v[192:195], v[4:7]
	v_mfma_f32_16x16x32_bf16 v[0:3], v[208:211], v[192:195], v[0:3]
	s_setprio 0
	s_add_i32 s27, s27, 2
	s_add_u32 s36, s36, 0x100
	s_addc_u32 s37, s37, 0
	s_add_u32 s19, s19, 0x100
	s_addc_u32 s21, s21, 0
	s_cmp_gt_u32 s27, 29
	s_barrier
	s_cbranch_scc0 .LBB0_1176
	s_branch .Lpeel_6_exit

; DI u32x2 pk4(f32x4 v) { u32x2 r; r.x = pk2(v[0], v[1]); r.y = pk2(v[2], v[3]); return r; }
; DI float bf_lo(unsigned w) { return __uint_as_float(w << 16); }
; DI float bf_hi(unsigned w) { return __uint_as_float(w & 0xffff0000u); }
; #define COLS4 _Pragma("unroll") for (int bj = 0; bj < 2; ++bj) _Pragma("unroll") for (int n = 0; n < 2; ++n)
;     DI void operator()(const Acc& acc, const Unit& u, int wr, int wc, int fr, int fq) const {
;     ...
;         } else if constexpr (PH == 4 || PH == 6 || PH == 10 || PH == 12) {
;             float* ssq = SSQ((PH == 4 ? 2 : PH == 6 ? 3 : PH == 10 ? 6 : 7) + sqo);
;             const int colp = u.pn * BM + wc * 32 + 8 * fq;
; #pragma unroll
;             for (int ai = 0; ai < 2; ++ai) if (ai == 0 || !hf) {
;                 f32x4 xo[4][2][2];
; #pragma unroll
;                 for (int m = 0; m < 4; ++m) { const size_t o = (size_t)(row0 + ai * HALF + m * 16) * 2048 + colp;
;                     if (PH == 4) { COLS4 xo[m][bj][n] = *(const f32x4*)(p.x + o + bj * HALF + n * 4); }
;                     else {
; #pragma unroll
;                         for (int bj = 0; bj < 2; ++bj) { const u32x4 w = *(const u32x4*)(WSB(OFF_XB) + o + bj * HALF);
;                             xo[m][bj][0] = (f32x4){bf_lo(w.x), bf_hi(w.x), bf_lo(w.y), bf_hi(w.y)}; xo[m][bj][1] = (f32x4){bf_lo(w.z), bf_hi(w.z), bf_lo(w.w), bf_hi(w.w)}; } } }
; #pragma unroll
;                 for (int m = 0; m < 4; ++m) { const int r = row0 + ai * HALF + m * 16; const size_t o = (size_t)r * 2048 + colp; float part = 0.f;
; #pragma unroll
;                     for (int bj = 0; bj < 2; ++bj) { const f32x4 x0 = xo[m][bj][0] + acc[ai][bj][m][0], x1 = xo[m][bj][1] + acc[ai][bj][m][1];
;                         const u32x2 h0 = pk4(x0), h1 = pk4(x1);
;                         *(u32x4*)(WSB(OFF_XB) + o + bj * HALF) = (u32x4){h0.x, h0.y, h1.x, h1.y};
;                         part += x0[0] * x0[0] + x0[1] * x0[1] + x0[2] * x0[2] + x0[3] * x0[3] + x1[0] * x1[0] + x1[1] * x1[1] + x1[2] * x1[2] + x1[3] * x1[3]; }
;                     part += __shfl_xor(part, 16); part += __shfl_xor(part, 32);
;                     if (fq == 0) unsafeAtomicAdd(ssq + r, part);
.Lpeel_6_exit:
	v_lshl_add_u32 v128, s60, 8, v182
	v_lshl_add_u32 v166, s26, 8, v180
	v_ashrrev_i32_e32 v129, 31, v128
	v_lshlrev_b64 v[162:163], 1, v[128:129]
	v_ashrrev_i32_e32 v167, 31, v166
	v_lshl_add_u64 v[164:165], s[16:17], 0, v[162:163]
	v_lshlrev_b64 v[196:197], 12, v[166:167]
	v_lshl_add_u64 v[128:129], v[164:165], 0, v[196:197]
	global_load_dwordx4 v[188:191], v[128:129], off
	global_load_dwordx4 v[192:195], v[128:129], off offset:256
	v_or_b32_e32 v176, 16, v166
	v_or_b32_e32 v172, 32, v166
	v_or_b32_e32 v168, 48, v166
	v_ashrrev_i32_e32 v177, 31, v176
	v_ashrrev_i32_e32 v173, 31, v172
	v_ashrrev_i32_e32 v169, 31, v168
	v_lshlrev_b64 v[178:179], 12, v[176:177]
	v_lshlrev_b64 v[174:175], 12, v[172:173]
	v_lshlrev_b64 v[170:171], 12, v[168:169]
	v_lshl_add_u64 v[128:129], v[164:165], 0, v[178:179]
	v_lshl_add_u64 v[130:131], v[164:165], 0, v[174:175]
	v_lshl_add_u64 v[198:199], v[164:165], 0, v[170:171]
	global_load_dwordx4 v[148:151], v[128:129], off
	global_load_dwordx4 v[144:147], v[128:129], off offset:256
	global_load_dwordx4 v[140:143], v[130:131], off
	global_load_dwordx4 v[136:139], v[130:131], off offset:256
	global_load_dwordx4 v[132:135], v[198:199], off
	s_nop 0
	global_load_dwordx4 v[128:131], v[198:199], off offset:256
	v_lshl_add_u64 v[198:199], s[16:17], 0, v[196:197]
	v_lshl_add_u64 v[198:199], v[198:199], 0, v[162:163]
	v_lshl_add_u64 v[196:197], s[10:11], 0, v[196:197]
	v_lshl_add_u64 v[196:197], v[196:197], 0, v[162:163]
	s_waitcnt vmcnt(0)
	v_lshlrev_b32_e32 v200, 16, v188
	v_and_b32_e32 v201, 0xffff0000, v188
	v_lshlrev_b32_e32 v188, 16, v189
	v_and_b32_e32 v189, 0xffff0000, v189
	v_lshlrev_b32_e32 v204, 16, v192
	v_and_b32_e32 v205, 0xffff0000, v192
	v_lshlrev_b32_e32 v192, 16, v193
	v_and_b32_e32 v193, 0xffff0000, v193
	v_lshlrev_b32_e32 v206, 16, v194
	v_and_b32_e32 v207, 0xffff0000, v194
	v_pk_add_f32 v[126:127], v[126:127], v[188:189]
	v_pk_add_f32 v[124:125], v[124:125], v[200:201]
	v_pk_add_f32 v[188:189], v[116:117], v[204:205]
	v_pk_add_f32 v[118:119], v[118:119], v[192:193]
	v_pk_add_f32 v[192:193], v[112:113], v[206:207]
	v_cvt_pk_bf16_f32 v112, v124, v125
	v_mul_f32_e32 v117, v125, v125
	v_mul_f32_e32 v125, v189, v189
	v_fmac_f32_e32 v117, v124, v124
	v_fmac_f32_e32 v125, v188, v188
	v_lshlrev_b32_e32 v202, 16, v190
	v_and_b32_e32 v203, 0xffff0000, v190
	v_fmac_f32_e32 v117, v126, v126
	v_fmac_f32_e32 v125, v118, v118
	v_pk_add_f32 v[120:121], v[120:121], v[202:203]
	v_fmac_f32_e32 v117, v127, v127
	v_fmac_f32_e32 v125, v119, v119
	v_lshlrev_b32_e32 v190, 16, v191
	v_and_b32_e32 v191, 0xffff0000, v191
	v_lshlrev_b32_e32 v194, 16, v195
	v_and_b32_e32 v195, 0xffff0000, v195
	v_fmac_f32_e32 v117, v120, v120
	v_fmac_f32_e32 v125, v192, v192
	v_pk_add_f32 v[122:123], v[122:123], v[190:191]
	v_pk_add_f32 v[190:191], v[114:115], v[194:195]
	v_fmac_f32_e32 v117, v121, v121
	v_fmac_f32_e32 v125, v193, v193
	v_fmac_f32_e32 v117, v122, v122
	v_fmac_f32_e32 v125, v190, v190
	v_fmac_f32_e32 v117, v123, v123
	v_fmac_f32_e32 v125, v191, v191
	v_cvt_pk_bf16_f32 v114, v120, v121
	v_add_f32_e32 v120, v117, v125
	ds_bpermute_b32 v121, v183, v120
	v_cvt_pk_bf16_f32 v113, v126, v127
	v_cvt_pk_bf16_f32 v115, v122, v123
	global_store_dwordx4 v[198:199], v[112:115], off sc1
	v_cvt_pk_bf16_f32 v116, v188, v189
	v_cvt_pk_bf16_f32 v117, v118, v119
	s_waitcnt lgkmcnt(0)
	v_add_f32_e32 v112, v120, v121
	ds_bpermute_b32 v113, v184, v112
	v_add_co_u32_e32 v114, vcc, s59, v196
	v_cvt_pk_bf16_f32 v118, v192, v193
	v_cvt_pk_bf16_f32 v119, v190, v191
	v_addc_co_u32_e32 v115, vcc, 0, v197, vcc
	global_store_dwordx4 v[114:115], v[116:119], off offset:256 sc1
	s_and_saveexec_b64 s[26:27], s[2:3]
	s_cbranch_execz .LBB0_1179
	s_waitcnt lgkmcnt(0)
	v_add_f32_e32 v114, v112, v113
	v_lshl_add_u64 v[112:113], v[166:167], 2, s[14:15]
	global_atomic_add_f32 v[112:113], v114, off
